# speedup vs baseline: 1.0146x; 1.0010x over previous
.LBB0_213:
	s_mov_b64 s[38:39], s[54:55]
	ds_read_b128 v[148:151], v153
	ds_read_b128 v[158:161], v153 offset:1024
	ds_read_b128 v[162:165], v153 offset:2048
	ds_read_b128 v[166:169], v153 offset:3072
	ds_read_b128 v[170:173], v155
	ds_read_b128 v[174:177], v155 offset:1024
	ds_read_b128 v[182:185], v155 offset:2048
	ds_read_b128 v[186:189], v155 offset:3072
	s_add_u32 s17, s6, s38
	s_addc_u32 s25, s7, s39
	s_add_u32 s40, s17, 0x100
	s_addc_u32 s41, s25, 0
	s_add_u32 s38, s36, s38
	s_addc_u32 s39, s37, s39
	s_add_u32 s38, s38, 0x100
	s_addc_u32 s39, s39, 0
	s_cmp_eq_u32 s70, s3
	s_cselect_b32 s61, s31, s41
	s_cselect_b32 s60, s30, s40
	s_cselect_b32 s59, s35, s39
	s_cselect_b32 s58, s34, s38
	s_add_u32 s38, s17, 0x80080
	s_addc_u32 s39, s25, 0
	v_lshl_add_u64 v[140:141], s[38:39], 0, v[128:129]
	s_add_i32 m0, s19, 0xc000
	ds_read_b128 v[190:193], v157
	ds_read_b128 v[194:197], v157 offset:1024
	ds_read_b128 v[198:201], v157 offset:2048
	ds_read_b128 v[202:205], v157 offset:3072
	ds_read_b128 v[206:209], v157 offset:4096
	ds_read_b128 v[210:213], v157 offset:5120
	ds_read_b128 v[214:217], v157 offset:6144
	ds_read_b128 v[218:221], v157 offset:7168
	global_load_lds_dwordx4 v[140:141], off
	v_lshl_add_u64 v[140:141], s[38:39], 0, v[132:133]
	s_add_i32 m0, s19, 0xe000
	s_nop 0
	global_load_lds_dwordx4 v[140:141], off
	s_waitcnt vmcnt(8)
	s_waitcnt lgkmcnt(0)
	s_barrier
	s_setprio 1
	v_mfma_f32_16x16x32_bf16 v[124:127], v[148:151], v[190:193], v[124:127]
	v_mfma_f32_16x16x32_bf16 v[120:123], v[162:165], v[190:193], v[120:123]
	v_mfma_f32_16x16x32_bf16 v[108:111], v[148:151], v[198:201], v[108:111]
	v_mfma_f32_16x16x32_bf16 v[104:107], v[162:165], v[198:201], v[104:107]
	v_mfma_f32_16x16x32_bf16 v[92:95], v[148:151], v[206:209], v[92:95]
	v_mfma_f32_16x16x32_bf16 v[88:91], v[162:165], v[206:209], v[88:91]
	v_mfma_f32_16x16x32_bf16 v[76:79], v[148:151], v[214:217], v[76:79]
	v_mfma_f32_16x16x32_bf16 v[72:75], v[162:165], v[214:217], v[72:75]
	v_mfma_f32_16x16x32_bf16 v[124:127], v[158:161], v[194:197], v[124:127]
	v_mfma_f32_16x16x32_bf16 v[120:123], v[166:169], v[194:197], v[120:123]
	v_mfma_f32_16x16x32_bf16 v[108:111], v[158:161], v[202:205], v[108:111]
	v_mfma_f32_16x16x32_bf16 v[104:107], v[166:169], v[202:205], v[104:107]
	v_mfma_f32_16x16x32_bf16 v[92:95], v[158:161], v[210:213], v[92:95]
	v_mfma_f32_16x16x32_bf16 v[88:91], v[166:169], v[210:213], v[88:91]
	v_mfma_f32_16x16x32_bf16 v[76:79], v[158:161], v[218:221], v[76:79]
	v_mfma_f32_16x16x32_bf16 v[72:75], v[166:169], v[218:221], v[72:75]
	v_mfma_f32_16x16x32_bf16 v[116:119], v[170:173], v[190:193], v[116:119]
	v_mfma_f32_16x16x32_bf16 v[112:115], v[182:185], v[190:193], v[112:115]
	v_mfma_f32_16x16x32_bf16 v[100:103], v[170:173], v[198:201], v[100:103]
	v_mfma_f32_16x16x32_bf16 v[96:99], v[182:185], v[198:201], v[96:99]
	v_mfma_f32_16x16x32_bf16 v[84:87], v[170:173], v[206:209], v[84:87]
	v_mfma_f32_16x16x32_bf16 v[80:83], v[182:185], v[206:209], v[80:83]
	v_mfma_f32_16x16x32_bf16 v[68:71], v[170:173], v[214:217], v[68:71]
	v_mfma_f32_16x16x32_bf16 v[64:67], v[182:185], v[214:217], v[64:67]
	v_mfma_f32_16x16x32_bf16 v[116:119], v[174:177], v[194:197], v[116:119]
	v_mfma_f32_16x16x32_bf16 v[112:115], v[186:189], v[194:197], v[112:115]
	v_mfma_f32_16x16x32_bf16 v[100:103], v[174:177], v[202:205], v[100:103]
	v_mfma_f32_16x16x32_bf16 v[96:99], v[186:189], v[202:205], v[96:99]
	v_mfma_f32_16x16x32_bf16 v[84:87], v[174:177], v[210:213], v[84:87]
	v_mfma_f32_16x16x32_bf16 v[80:83], v[186:189], v[210:213], v[80:83]
	v_mfma_f32_16x16x32_bf16 v[68:71], v[174:177], v[218:221], v[68:71]
	v_mfma_f32_16x16x32_bf16 v[64:67], v[186:189], v[218:221], v[64:67]
	s_setprio 0
	s_barrier
	s_add_i32 s17, s71, s18
	v_lshl_add_u64 v[140:141], s[58:59], 0, v[130:131]
	s_mov_b32 m0, s17
	ds_read_b128 v[190:193], v157 offset:16384
	ds_read_b128 v[194:197], v157 offset:17408
	ds_read_b128 v[198:201], v157 offset:18432
	ds_read_b128 v[202:205], v157 offset:19456
	ds_read_b128 v[206:209], v157 offset:20480
	ds_read_b128 v[210:213], v157 offset:21504
	ds_read_b128 v[214:217], v157 offset:22528
	ds_read_b128 v[218:221], v157 offset:23552
	global_load_lds_dwordx4 v[140:141], off
	s_add_i32 m0, s17, 0x2000
	s_add_u32 s38, s58, 0x80000
	v_lshl_add_u64 v[178:179], s[58:59], 0, v[134:135]
	s_addc_u32 s39, s59, 0
	s_add_i32 s17, s72, s18
	global_load_lds_dwordx4 v[178:179], off
	v_lshl_add_u64 v[222:223], s[38:39], 0, v[130:131]
	s_mov_b32 m0, s17
	v_lshl_add_u64 v[224:225], s[60:61], 0, v[132:133]
	global_load_lds_dwordx4 v[222:223], off
	v_lshl_add_u64 v[222:223], s[38:39], 0, v[134:135]
	s_add_i32 m0, s17, 0x2000
	s_nop 0
	global_load_lds_dwordx4 v[222:223], off
	v_lshl_add_u64 v[222:223], s[60:61], 0, v[128:129]
	s_mov_b32 m0, s19
	s_nop 0
	global_load_lds_dwordx4 v[222:223], off
	s_mov_b32 m0, s56
	s_nop 0
	global_load_lds_dwordx4 v[224:225], off
	s_waitcnt vmcnt(8)
	s_waitcnt lgkmcnt(0)
	s_barrier
	s_setprio 1
	v_mfma_f32_16x16x32_bf16 v[60:63], v[148:151], v[190:193], v[60:63]
	v_mfma_f32_16x16x32_bf16 v[56:59], v[162:165], v[190:193], v[56:59]
	v_mfma_f32_16x16x32_bf16 v[44:47], v[148:151], v[198:201], v[44:47]
	v_mfma_f32_16x16x32_bf16 v[40:43], v[162:165], v[198:201], v[40:43]
	v_mfma_f32_16x16x32_bf16 v[28:31], v[148:151], v[206:209], v[28:31]
	v_mfma_f32_16x16x32_bf16 v[24:27], v[162:165], v[206:209], v[24:27]
	v_mfma_f32_16x16x32_bf16 v[12:15], v[148:151], v[214:217], v[12:15]
	v_mfma_f32_16x16x32_bf16 v[8:11], v[162:165], v[214:217], v[8:11]
	v_mfma_f32_16x16x32_bf16 v[60:63], v[158:161], v[194:197], v[60:63]
	v_mfma_f32_16x16x32_bf16 v[56:59], v[166:169], v[194:197], v[56:59]
	v_mfma_f32_16x16x32_bf16 v[44:47], v[158:161], v[202:205], v[44:47]
	v_mfma_f32_16x16x32_bf16 v[40:43], v[166:169], v[202:205], v[40:43]
	v_mfma_f32_16x16x32_bf16 v[28:31], v[158:161], v[210:213], v[28:31]
	v_mfma_f32_16x16x32_bf16 v[24:27], v[166:169], v[210:213], v[24:27]
	v_mfma_f32_16x16x32_bf16 v[12:15], v[158:161], v[218:221], v[12:15]
	v_mfma_f32_16x16x32_bf16 v[8:11], v[166:169], v[218:221], v[8:11]
	v_mfma_f32_16x16x32_bf16 v[52:55], v[170:173], v[190:193], v[52:55]
	v_mfma_f32_16x16x32_bf16 v[48:51], v[182:185], v[190:193], v[48:51]
	v_mfma_f32_16x16x32_bf16 v[36:39], v[170:173], v[198:201], v[36:39]
	v_mfma_f32_16x16x32_bf16 v[32:35], v[182:185], v[198:201], v[32:35]
	v_mfma_f32_16x16x32_bf16 v[20:23], v[170:173], v[206:209], v[20:23]
	v_mfma_f32_16x16x32_bf16 v[16:19], v[182:185], v[206:209], v[16:19]
	v_mfma_f32_16x16x32_bf16 v[4:7], v[170:173], v[214:217], v[4:7]
	v_mfma_f32_16x16x32_bf16 v[0:3], v[182:185], v[214:217], v[0:3]
	v_mfma_f32_16x16x32_bf16 v[52:55], v[174:177], v[194:197], v[52:55]
	v_mfma_f32_16x16x32_bf16 v[48:51], v[186:189], v[194:197], v[48:51]
	v_mfma_f32_16x16x32_bf16 v[36:39], v[174:177], v[202:205], v[36:39]
	v_mfma_f32_16x16x32_bf16 v[32:35], v[186:189], v[202:205], v[32:35]
	v_mfma_f32_16x16x32_bf16 v[20:23], v[174:177], v[210:213], v[20:23]
	v_mfma_f32_16x16x32_bf16 v[16:19], v[186:189], v[210:213], v[16:19]
	v_mfma_f32_16x16x32_bf16 v[4:7], v[174:177], v[218:221], v[4:7]
	v_mfma_f32_16x16x32_bf16 v[0:3], v[186:189], v[218:221], v[0:3]
	s_setprio 0
	s_barrier
	s_add_i32 s17, 0, 0x18000
	v_add_u32_e32 v142, s17, v147
	s_add_i32 s25, 0, 0x1c000
	ds_read_b128 v[148:151], v142
	ds_read_b128 v[158:161], v142 offset:1024
	ds_read_b128 v[162:165], v142 offset:2048
	ds_read_b128 v[166:169], v142 offset:3072
	v_add_u32_e32 v142, s25, v147
	ds_read_b128 v[170:173], v142
	ds_read_b128 v[174:177], v142 offset:1024
	ds_read_b128 v[182:185], v142 offset:2048
	ds_read_b128 v[186:189], v142 offset:3072
	s_add_u32 s38, s60, 0x80000
	s_addc_u32 s39, s61, 0
	s_mov_b32 m0, s57
	v_lshl_add_u64 v[226:227], s[38:39], 0, v[128:129]
	ds_read_b128 v[190:193], v157 offset:32768
	ds_read_b128 v[194:197], v157 offset:33792
	ds_read_b128 v[198:201], v157 offset:34816
	ds_read_b128 v[202:205], v157 offset:35840
	ds_read_b128 v[206:209], v157 offset:36864
	ds_read_b128 v[210:213], v157 offset:37888
	ds_read_b128 v[214:217], v157 offset:38912
	ds_read_b128 v[218:221], v157 offset:39936
	global_load_lds_dwordx4 v[226:227], off
	v_lshl_add_u64 v[226:227], s[38:39], 0, v[132:133]
	s_mov_b32 m0, s62
	s_nop 0
	global_load_lds_dwordx4 v[226:227], off
	s_waitcnt vmcnt(8)
	s_waitcnt lgkmcnt(0)
	s_barrier
	s_setprio 1
	v_mfma_f32_16x16x32_bf16 v[124:127], v[148:151], v[190:193], v[124:127]
	v_mfma_f32_16x16x32_bf16 v[120:123], v[162:165], v[190:193], v[120:123]
	v_mfma_f32_16x16x32_bf16 v[108:111], v[148:151], v[198:201], v[108:111]
	v_mfma_f32_16x16x32_bf16 v[104:107], v[162:165], v[198:201], v[104:107]
	v_mfma_f32_16x16x32_bf16 v[92:95], v[148:151], v[206:209], v[92:95]
	v_mfma_f32_16x16x32_bf16 v[88:91], v[162:165], v[206:209], v[88:91]
	v_mfma_f32_16x16x32_bf16 v[76:79], v[148:151], v[214:217], v[76:79]
	v_mfma_f32_16x16x32_bf16 v[72:75], v[162:165], v[214:217], v[72:75]
	v_mfma_f32_16x16x32_bf16 v[124:127], v[158:161], v[194:197], v[124:127]
	v_mfma_f32_16x16x32_bf16 v[120:123], v[166:169], v[194:197], v[120:123]
	v_mfma_f32_16x16x32_bf16 v[108:111], v[158:161], v[202:205], v[108:111]
	v_mfma_f32_16x16x32_bf16 v[104:107], v[166:169], v[202:205], v[104:107]
	v_mfma_f32_16x16x32_bf16 v[92:95], v[158:161], v[210:213], v[92:95]
	v_mfma_f32_16x16x32_bf16 v[88:91], v[166:169], v[210:213], v[88:91]
	v_mfma_f32_16x16x32_bf16 v[76:79], v[158:161], v[218:221], v[76:79]
	v_mfma_f32_16x16x32_bf16 v[72:75], v[166:169], v[218:221], v[72:75]
	v_mfma_f32_16x16x32_bf16 v[116:119], v[170:173], v[190:193], v[116:119]
	v_mfma_f32_16x16x32_bf16 v[112:115], v[182:185], v[190:193], v[112:115]
	v_mfma_f32_16x16x32_bf16 v[100:103], v[170:173], v[198:201], v[100:103]
	v_mfma_f32_16x16x32_bf16 v[96:99], v[182:185], v[198:201], v[96:99]
	v_mfma_f32_16x16x32_bf16 v[84:87], v[170:173], v[206:209], v[84:87]
	v_mfma_f32_16x16x32_bf16 v[80:83], v[182:185], v[206:209], v[80:83]
	v_mfma_f32_16x16x32_bf16 v[68:71], v[170:173], v[214:217], v[68:71]
	v_mfma_f32_16x16x32_bf16 v[64:67], v[182:185], v[214:217], v[64:67]
	v_mfma_f32_16x16x32_bf16 v[116:119], v[174:177], v[194:197], v[116:119]
	v_mfma_f32_16x16x32_bf16 v[112:115], v[186:189], v[194:197], v[112:115]
	v_mfma_f32_16x16x32_bf16 v[100:103], v[174:177], v[202:205], v[100:103]
	v_mfma_f32_16x16x32_bf16 v[96:99], v[186:189], v[202:205], v[96:99]
	v_mfma_f32_16x16x32_bf16 v[84:87], v[174:177], v[210:213], v[84:87]
	v_mfma_f32_16x16x32_bf16 v[80:83], v[186:189], v[210:213], v[80:83]
	v_mfma_f32_16x16x32_bf16 v[68:71], v[174:177], v[218:221], v[68:71]
	v_mfma_f32_16x16x32_bf16 v[64:67], v[186:189], v[218:221], v[64:67]
	s_setprio 0
	s_barrier
	s_add_i32 s17, s17, s18
	v_lshl_add_u64 v[140:141], v[140:141], 0, s[12:13]
	s_mov_b32 m0, s17
	ds_read_b128 v[190:193], v157 offset:49152
	ds_read_b128 v[194:197], v157 offset:50176
	ds_read_b128 v[198:201], v157 offset:51200
	ds_read_b128 v[202:205], v157 offset:52224
	ds_read_b128 v[206:209], v157 offset:53248
	ds_read_b128 v[210:213], v157 offset:54272
	ds_read_b128 v[214:217], v157 offset:55296
	ds_read_b128 v[218:221], v157 offset:56320
	global_load_lds_dwordx4 v[140:141], off
	s_add_i32 m0, s17, 0x2000
	s_add_u32 s38, s58, 0x80080
	v_lshl_add_u64 v[140:141], v[178:179], 0, s[12:13]
	s_addc_u32 s39, s59, 0
	s_add_i32 s17, s25, s18
	global_load_lds_dwordx4 v[140:141], off
	v_lshl_add_u64 v[140:141], s[38:39], 0, v[130:131]
	s_mov_b32 m0, s17
	s_nop 0
	global_load_lds_dwordx4 v[140:141], off
	v_lshl_add_u64 v[140:141], s[38:39], 0, v[134:135]
	s_add_i32 m0, s17, 0x2000
	s_nop 0
	global_load_lds_dwordx4 v[140:141], off
	v_lshl_add_u64 v[140:141], v[222:223], 0, s[12:13]
	s_mov_b32 m0, s65
	s_nop 0
	global_load_lds_dwordx4 v[140:141], off
	v_lshl_add_u64 v[140:141], v[224:225], 0, s[12:13]
	s_mov_b32 m0, s68
	s_nop 0
	global_load_lds_dwordx4 v[140:141], off
	s_waitcnt vmcnt(8)
	s_waitcnt lgkmcnt(0)
	s_barrier
	s_setprio 1
	v_mfma_f32_16x16x32_bf16 v[60:63], v[148:151], v[190:193], v[60:63]
	v_mfma_f32_16x16x32_bf16 v[56:59], v[162:165], v[190:193], v[56:59]
	v_mfma_f32_16x16x32_bf16 v[44:47], v[148:151], v[198:201], v[44:47]
	v_mfma_f32_16x16x32_bf16 v[40:43], v[162:165], v[198:201], v[40:43]
	v_mfma_f32_16x16x32_bf16 v[28:31], v[148:151], v[206:209], v[28:31]
	v_mfma_f32_16x16x32_bf16 v[24:27], v[162:165], v[206:209], v[24:27]
	v_mfma_f32_16x16x32_bf16 v[12:15], v[148:151], v[214:217], v[12:15]
	v_mfma_f32_16x16x32_bf16 v[8:11], v[162:165], v[214:217], v[8:11]
	v_mfma_f32_16x16x32_bf16 v[60:63], v[158:161], v[194:197], v[60:63]
	v_mfma_f32_16x16x32_bf16 v[56:59], v[166:169], v[194:197], v[56:59]
	v_mfma_f32_16x16x32_bf16 v[44:47], v[158:161], v[202:205], v[44:47]
	v_mfma_f32_16x16x32_bf16 v[40:43], v[166:169], v[202:205], v[40:43]
	v_mfma_f32_16x16x32_bf16 v[28:31], v[158:161], v[210:213], v[28:31]
	v_mfma_f32_16x16x32_bf16 v[24:27], v[166:169], v[210:213], v[24:27]
	v_mfma_f32_16x16x32_bf16 v[12:15], v[158:161], v[218:221], v[12:15]
	v_mfma_f32_16x16x32_bf16 v[8:11], v[166:169], v[218:221], v[8:11]
	v_mfma_f32_16x16x32_bf16 v[52:55], v[170:173], v[190:193], v[52:55]
	v_mfma_f32_16x16x32_bf16 v[48:51], v[182:185], v[190:193], v[48:51]
	v_mfma_f32_16x16x32_bf16 v[36:39], v[170:173], v[198:201], v[36:39]
	v_mfma_f32_16x16x32_bf16 v[32:35], v[182:185], v[198:201], v[32:35]
	v_mfma_f32_16x16x32_bf16 v[20:23], v[170:173], v[206:209], v[20:23]
	v_mfma_f32_16x16x32_bf16 v[16:19], v[182:185], v[206:209], v[16:19]
	v_mfma_f32_16x16x32_bf16 v[4:7], v[170:173], v[214:217], v[4:7]
	v_mfma_f32_16x16x32_bf16 v[0:3], v[182:185], v[214:217], v[0:3]
	v_mfma_f32_16x16x32_bf16 v[52:55], v[174:177], v[194:197], v[52:55]
	v_mfma_f32_16x16x32_bf16 v[48:51], v[186:189], v[194:197], v[48:51]
	v_mfma_f32_16x16x32_bf16 v[36:39], v[174:177], v[202:205], v[36:39]
	v_mfma_f32_16x16x32_bf16 v[32:35], v[186:189], v[202:205], v[32:35]
	v_mfma_f32_16x16x32_bf16 v[20:23], v[174:177], v[210:213], v[20:23]
	v_mfma_f32_16x16x32_bf16 v[16:19], v[186:189], v[210:213], v[16:19]
	v_mfma_f32_16x16x32_bf16 v[4:7], v[174:177], v[218:221], v[4:7]
	v_mfma_f32_16x16x32_bf16 v[0:3], v[186:189], v[218:221], v[0:3]
	s_setprio 0
	s_barrier
	s_add_i32 s3, s3, 2
	s_add_u32 s54, s54, 0x100
	s_addc_u32 s55, s55, 0
	s_cmp_ge_i32 s3, s63
	s_cbranch_scc0 .LBB0_213

.LBB0_628:
	s_mov_b64 s[4:5], s[36:37]
	ds_read_b128 v[80:83], v199
	ds_read_b128 v[92:95], v199 offset:1024
	ds_read_b128 v[96:99], v199 offset:2048
	ds_read_b128 v[104:107], v199 offset:3072
	ds_read_b128 v[108:111], v200
	ds_read_b128 v[116:119], v200 offset:1024
	ds_read_b128 v[120:123], v200 offset:2048
	ds_read_b128 v[124:127], v200 offset:3072
	s_add_u32 s7, s12, s4
	s_addc_u32 s28, s13, s5
	s_add_u32 s29, s7, 0x100
	s_addc_u32 s31, s28, 0
	s_add_u32 s4, s16, s4
	s_addc_u32 s5, s17, s5
	s_add_u32 s4, s4, 0x100
	s_addc_u32 s5, s5, 0
	s_cmp_eq_u32 s72, s3
	s_cselect_b32 s65, s61, s31
	s_cselect_b32 s64, s60, s29
	s_cselect_b32 s55, s63, s5
	s_cselect_b32 s54, s62, s4
	s_add_u32 s4, s7, 0x80080
	s_addc_u32 s5, s28, 0
	v_lshl_add_u64 v[194:195], s[4:5], 0, v[182:183]
	s_add_i32 m0, s19, 0xc000
	ds_read_b128 v[160:163], v201
	ds_read_b128 v[164:167], v201 offset:1024
	ds_read_b128 v[168:171], v201 offset:2048
	ds_read_b128 v[172:175], v201 offset:3072
	ds_read_b128 v[176:179], v201 offset:4096
	ds_read_b128 v[190:193], v201 offset:5120
	ds_read_b128 v[202:205], v201 offset:6144
	ds_read_b128 v[206:209], v201 offset:7168
	global_load_lds_dwordx4 v[194:195], off
	v_lshl_add_u64 v[194:195], s[4:5], 0, v[184:185]
	s_add_i32 m0, s19, 0xe000
	s_nop 0
	global_load_lds_dwordx4 v[194:195], off
	s_waitcnt vmcnt(8)
	s_waitcnt lgkmcnt(0)
	s_barrier
	s_setprio 1
	v_mfma_f32_16x16x32_bf16 v[156:159], v[80:83], v[160:163], v[156:159]
	v_mfma_f32_16x16x32_bf16 v[152:155], v[96:99], v[160:163], v[152:155]
	v_mfma_f32_16x16x32_bf16 v[140:143], v[80:83], v[168:171], v[140:143]
	v_mfma_f32_16x16x32_bf16 v[136:139], v[96:99], v[168:171], v[136:139]
	v_mfma_f32_16x16x32_bf16 v[112:115], v[80:83], v[176:179], v[112:115]
	v_mfma_f32_16x16x32_bf16 v[100:103], v[96:99], v[176:179], v[100:103]
	v_mfma_f32_16x16x32_bf16 v[76:79], v[80:83], v[202:205], v[76:79]
	v_mfma_f32_16x16x32_bf16 v[72:75], v[96:99], v[202:205], v[72:75]
	v_mfma_f32_16x16x32_bf16 v[156:159], v[92:95], v[164:167], v[156:159]
	v_mfma_f32_16x16x32_bf16 v[152:155], v[104:107], v[164:167], v[152:155]
	v_mfma_f32_16x16x32_bf16 v[140:143], v[92:95], v[172:175], v[140:143]
	v_mfma_f32_16x16x32_bf16 v[136:139], v[104:107], v[172:175], v[136:139]
	v_mfma_f32_16x16x32_bf16 v[112:115], v[92:95], v[190:193], v[112:115]
	v_mfma_f32_16x16x32_bf16 v[100:103], v[104:107], v[190:193], v[100:103]
	v_mfma_f32_16x16x32_bf16 v[76:79], v[92:95], v[206:209], v[76:79]
	v_mfma_f32_16x16x32_bf16 v[72:75], v[104:107], v[206:209], v[72:75]
	v_mfma_f32_16x16x32_bf16 v[148:151], v[108:111], v[160:163], v[148:151]
	v_mfma_f32_16x16x32_bf16 v[144:147], v[120:123], v[160:163], v[144:147]
	v_mfma_f32_16x16x32_bf16 v[132:135], v[108:111], v[168:171], v[132:135]
	v_mfma_f32_16x16x32_bf16 v[128:131], v[120:123], v[168:171], v[128:131]
	v_mfma_f32_16x16x32_bf16 v[88:91], v[108:111], v[176:179], v[88:91]
	v_mfma_f32_16x16x32_bf16 v[84:87], v[120:123], v[176:179], v[84:87]
	v_mfma_f32_16x16x32_bf16 v[68:71], v[108:111], v[202:205], v[68:71]
	v_mfma_f32_16x16x32_bf16 v[64:67], v[120:123], v[202:205], v[64:67]
	v_mfma_f32_16x16x32_bf16 v[148:151], v[116:119], v[164:167], v[148:151]
	v_mfma_f32_16x16x32_bf16 v[144:147], v[124:127], v[164:167], v[144:147]
	v_mfma_f32_16x16x32_bf16 v[132:135], v[116:119], v[172:175], v[132:135]
	v_mfma_f32_16x16x32_bf16 v[128:131], v[124:127], v[172:175], v[128:131]
	v_mfma_f32_16x16x32_bf16 v[88:91], v[116:119], v[190:193], v[88:91]
	v_mfma_f32_16x16x32_bf16 v[84:87], v[124:127], v[190:193], v[84:87]
	v_mfma_f32_16x16x32_bf16 v[68:71], v[116:119], v[206:209], v[68:71]
	v_mfma_f32_16x16x32_bf16 v[64:67], v[124:127], v[206:209], v[64:67]
	s_setprio 0
	s_barrier
	s_add_i32 s4, s73, s18
	v_lshl_add_u64 v[194:195], s[54:55], 0, v[182:183]
	s_mov_b32 m0, s4
	ds_read_b128 v[160:163], v201 offset:16384
	ds_read_b128 v[164:167], v201 offset:17408
	ds_read_b128 v[168:171], v201 offset:18432
	ds_read_b128 v[172:175], v201 offset:19456
	ds_read_b128 v[176:179], v201 offset:20480
	ds_read_b128 v[190:193], v201 offset:21504
	ds_read_b128 v[202:205], v201 offset:22528
	ds_read_b128 v[206:209], v201 offset:23552
	global_load_lds_dwordx4 v[194:195], off
	s_add_i32 m0, s4, 0x2000
	s_add_u32 s4, s54, 0x80000
	v_lshl_add_u64 v[210:211], s[54:55], 0, v[184:185]
	s_addc_u32 s5, s55, 0
	s_add_i32 s7, s74, s18
	global_load_lds_dwordx4 v[210:211], off
	v_lshl_add_u64 v[212:213], s[4:5], 0, v[182:183]
	s_mov_b32 m0, s7
	v_lshl_add_u64 v[214:215], s[64:65], 0, v[184:185]
	global_load_lds_dwordx4 v[212:213], off
	v_lshl_add_u64 v[212:213], s[4:5], 0, v[184:185]
	s_add_i32 m0, s7, 0x2000
	s_nop 0
	global_load_lds_dwordx4 v[212:213], off
	v_lshl_add_u64 v[212:213], s[64:65], 0, v[182:183]
	s_mov_b32 m0, s19
	s_nop 0
	global_load_lds_dwordx4 v[212:213], off
	s_mov_b32 m0, s56
	s_nop 0
	global_load_lds_dwordx4 v[214:215], off
	s_waitcnt vmcnt(8)
	s_waitcnt lgkmcnt(0)
	s_barrier
	s_setprio 1
	v_mfma_f32_16x16x32_bf16 v[60:63], v[80:83], v[160:163], v[60:63]
	v_mfma_f32_16x16x32_bf16 v[56:59], v[96:99], v[160:163], v[56:59]
	v_mfma_f32_16x16x32_bf16 v[44:47], v[80:83], v[168:171], v[44:47]
	v_mfma_f32_16x16x32_bf16 v[40:43], v[96:99], v[168:171], v[40:43]
	v_mfma_f32_16x16x32_bf16 v[28:31], v[80:83], v[176:179], v[28:31]
	v_mfma_f32_16x16x32_bf16 v[24:27], v[96:99], v[176:179], v[24:27]
	v_mfma_f32_16x16x32_bf16 v[12:15], v[80:83], v[202:205], v[12:15]
	v_mfma_f32_16x16x32_bf16 v[8:11], v[96:99], v[202:205], v[8:11]
	v_mfma_f32_16x16x32_bf16 v[60:63], v[92:95], v[164:167], v[60:63]
	v_mfma_f32_16x16x32_bf16 v[56:59], v[104:107], v[164:167], v[56:59]
	v_mfma_f32_16x16x32_bf16 v[44:47], v[92:95], v[172:175], v[44:47]
	v_mfma_f32_16x16x32_bf16 v[40:43], v[104:107], v[172:175], v[40:43]
	v_mfma_f32_16x16x32_bf16 v[28:31], v[92:95], v[190:193], v[28:31]
	v_mfma_f32_16x16x32_bf16 v[24:27], v[104:107], v[190:193], v[24:27]
	v_mfma_f32_16x16x32_bf16 v[12:15], v[92:95], v[206:209], v[12:15]
	v_mfma_f32_16x16x32_bf16 v[8:11], v[104:107], v[206:209], v[8:11]
	v_mfma_f32_16x16x32_bf16 v[52:55], v[108:111], v[160:163], v[52:55]
	v_mfma_f32_16x16x32_bf16 v[48:51], v[120:123], v[160:163], v[48:51]
	v_mfma_f32_16x16x32_bf16 v[36:39], v[108:111], v[168:171], v[36:39]
	v_mfma_f32_16x16x32_bf16 v[32:35], v[120:123], v[168:171], v[32:35]
	v_mfma_f32_16x16x32_bf16 v[20:23], v[108:111], v[176:179], v[20:23]
	v_mfma_f32_16x16x32_bf16 v[16:19], v[120:123], v[176:179], v[16:19]
	v_mfma_f32_16x16x32_bf16 v[4:7], v[108:111], v[202:205], v[4:7]
	v_mfma_f32_16x16x32_bf16 v[0:3], v[120:123], v[202:205], v[0:3]
	v_mfma_f32_16x16x32_bf16 v[52:55], v[116:119], v[164:167], v[52:55]
	v_mfma_f32_16x16x32_bf16 v[48:51], v[124:127], v[164:167], v[48:51]
	v_mfma_f32_16x16x32_bf16 v[36:39], v[116:119], v[172:175], v[36:39]
	v_mfma_f32_16x16x32_bf16 v[32:35], v[124:127], v[172:175], v[32:35]
	v_mfma_f32_16x16x32_bf16 v[20:23], v[116:119], v[190:193], v[20:23]
	v_mfma_f32_16x16x32_bf16 v[16:19], v[124:127], v[190:193], v[16:19]
	v_mfma_f32_16x16x32_bf16 v[4:7], v[116:119], v[206:209], v[4:7]
	v_mfma_f32_16x16x32_bf16 v[0:3], v[124:127], v[206:209], v[0:3]
	s_setprio 0
	s_barrier
	s_add_i32 s7, 0, 0x18000
	s_add_i32 s28, 0, 0x1c000
	v_add_u32_e32 v104, s7, v198
	v_add_u32_e32 v124, s28, v198
	ds_read_b128 v[80:83], v104
	ds_read_b128 v[92:95], v104 offset:1024
	ds_read_b128 v[96:99], v104 offset:2048
	ds_read_b128 v[104:107], v104 offset:3072
	ds_read_b128 v[108:111], v124
	ds_read_b128 v[116:119], v124 offset:1024
	ds_read_b128 v[120:123], v124 offset:2048
	ds_read_b128 v[124:127], v124 offset:3072
	s_add_u32 s4, s64, 0x80000
	s_addc_u32 s5, s65, 0
	s_mov_b32 m0, s57
	v_lshl_add_u64 v[216:217], s[4:5], 0, v[182:183]
	ds_read_b128 v[160:163], v201 offset:32768
	ds_read_b128 v[164:167], v201 offset:33792
	ds_read_b128 v[168:171], v201 offset:34816
	ds_read_b128 v[172:175], v201 offset:35840
	ds_read_b128 v[176:179], v201 offset:36864
	ds_read_b128 v[190:193], v201 offset:37888
	ds_read_b128 v[202:205], v201 offset:38912
	ds_read_b128 v[206:209], v201 offset:39936
	global_load_lds_dwordx4 v[216:217], off
	v_lshl_add_u64 v[216:217], s[4:5], 0, v[184:185]
	s_mov_b32 m0, s66
	s_nop 0
	global_load_lds_dwordx4 v[216:217], off
	s_waitcnt vmcnt(8)
	s_waitcnt lgkmcnt(0)
	s_barrier
	s_setprio 1
	v_mfma_f32_16x16x32_bf16 v[156:159], v[80:83], v[160:163], v[156:159]
	v_mfma_f32_16x16x32_bf16 v[152:155], v[96:99], v[160:163], v[152:155]
	v_mfma_f32_16x16x32_bf16 v[140:143], v[80:83], v[168:171], v[140:143]
	v_mfma_f32_16x16x32_bf16 v[136:139], v[96:99], v[168:171], v[136:139]
	v_mfma_f32_16x16x32_bf16 v[112:115], v[80:83], v[176:179], v[112:115]
	v_mfma_f32_16x16x32_bf16 v[100:103], v[96:99], v[176:179], v[100:103]
	v_mfma_f32_16x16x32_bf16 v[76:79], v[80:83], v[202:205], v[76:79]
	v_mfma_f32_16x16x32_bf16 v[72:75], v[96:99], v[202:205], v[72:75]
	v_mfma_f32_16x16x32_bf16 v[156:159], v[92:95], v[164:167], v[156:159]
	v_mfma_f32_16x16x32_bf16 v[152:155], v[104:107], v[164:167], v[152:155]
	v_mfma_f32_16x16x32_bf16 v[140:143], v[92:95], v[172:175], v[140:143]
	v_mfma_f32_16x16x32_bf16 v[136:139], v[104:107], v[172:175], v[136:139]
	v_mfma_f32_16x16x32_bf16 v[112:115], v[92:95], v[190:193], v[112:115]
	v_mfma_f32_16x16x32_bf16 v[100:103], v[104:107], v[190:193], v[100:103]
	v_mfma_f32_16x16x32_bf16 v[76:79], v[92:95], v[206:209], v[76:79]
	v_mfma_f32_16x16x32_bf16 v[72:75], v[104:107], v[206:209], v[72:75]
	v_mfma_f32_16x16x32_bf16 v[148:151], v[108:111], v[160:163], v[148:151]
	v_mfma_f32_16x16x32_bf16 v[144:147], v[120:123], v[160:163], v[144:147]
	v_mfma_f32_16x16x32_bf16 v[132:135], v[108:111], v[168:171], v[132:135]
	v_mfma_f32_16x16x32_bf16 v[128:131], v[120:123], v[168:171], v[128:131]
	v_mfma_f32_16x16x32_bf16 v[88:91], v[108:111], v[176:179], v[88:91]
	v_mfma_f32_16x16x32_bf16 v[84:87], v[120:123], v[176:179], v[84:87]
	v_mfma_f32_16x16x32_bf16 v[68:71], v[108:111], v[202:205], v[68:71]
	v_mfma_f32_16x16x32_bf16 v[64:67], v[120:123], v[202:205], v[64:67]
	v_mfma_f32_16x16x32_bf16 v[148:151], v[116:119], v[164:167], v[148:151]
	v_mfma_f32_16x16x32_bf16 v[144:147], v[124:127], v[164:167], v[144:147]
	v_mfma_f32_16x16x32_bf16 v[132:135], v[116:119], v[172:175], v[132:135]
	v_mfma_f32_16x16x32_bf16 v[128:131], v[124:127], v[172:175], v[128:131]
	v_mfma_f32_16x16x32_bf16 v[88:91], v[116:119], v[190:193], v[88:91]
	v_mfma_f32_16x16x32_bf16 v[84:87], v[124:127], v[190:193], v[84:87]
	v_mfma_f32_16x16x32_bf16 v[68:71], v[116:119], v[206:209], v[68:71]
	v_mfma_f32_16x16x32_bf16 v[64:67], v[124:127], v[206:209], v[64:67]
	s_setprio 0
	s_barrier
	s_add_i32 s4, s7, s18
	v_lshl_add_u64 v[194:195], v[194:195], 0, s[14:15]
	s_mov_b32 m0, s4
	ds_read_b128 v[160:163], v201 offset:49152
	ds_read_b128 v[164:167], v201 offset:50176
	ds_read_b128 v[168:171], v201 offset:51200
	ds_read_b128 v[172:175], v201 offset:52224
	ds_read_b128 v[176:179], v201 offset:53248
	ds_read_b128 v[190:193], v201 offset:54272
	ds_read_b128 v[202:205], v201 offset:55296
	ds_read_b128 v[206:209], v201 offset:56320
	global_load_lds_dwordx4 v[194:195], off
	s_add_i32 m0, s4, 0x2000
	s_add_u32 s4, s54, 0x80080
	v_lshl_add_u64 v[194:195], v[210:211], 0, s[14:15]
	s_addc_u32 s5, s55, 0
	s_add_i32 s7, s28, s18
	global_load_lds_dwordx4 v[194:195], off
	v_lshl_add_u64 v[194:195], s[4:5], 0, v[182:183]
	s_mov_b32 m0, s7
	s_nop 0
	global_load_lds_dwordx4 v[194:195], off
	v_lshl_add_u64 v[194:195], s[4:5], 0, v[184:185]
	s_add_i32 m0, s7, 0x2000
	s_nop 0
	global_load_lds_dwordx4 v[194:195], off
	v_lshl_add_u64 v[194:195], v[212:213], 0, s[14:15]
	s_mov_b32 m0, s70
	s_nop 0
	global_load_lds_dwordx4 v[194:195], off
	v_lshl_add_u64 v[194:195], v[214:215], 0, s[14:15]
	s_mov_b32 m0, s71
	s_nop 0
	global_load_lds_dwordx4 v[194:195], off
	s_waitcnt vmcnt(8)
	s_waitcnt lgkmcnt(0)
	s_barrier
	s_setprio 1
	v_mfma_f32_16x16x32_bf16 v[60:63], v[80:83], v[160:163], v[60:63]
	v_mfma_f32_16x16x32_bf16 v[56:59], v[96:99], v[160:163], v[56:59]
	v_mfma_f32_16x16x32_bf16 v[44:47], v[80:83], v[168:171], v[44:47]
	v_mfma_f32_16x16x32_bf16 v[40:43], v[96:99], v[168:171], v[40:43]
	v_mfma_f32_16x16x32_bf16 v[28:31], v[80:83], v[176:179], v[28:31]
	v_mfma_f32_16x16x32_bf16 v[24:27], v[96:99], v[176:179], v[24:27]
	v_mfma_f32_16x16x32_bf16 v[12:15], v[80:83], v[202:205], v[12:15]
	v_mfma_f32_16x16x32_bf16 v[8:11], v[96:99], v[202:205], v[8:11]
	v_mfma_f32_16x16x32_bf16 v[60:63], v[92:95], v[164:167], v[60:63]
	v_mfma_f32_16x16x32_bf16 v[56:59], v[104:107], v[164:167], v[56:59]
	v_mfma_f32_16x16x32_bf16 v[44:47], v[92:95], v[172:175], v[44:47]
	v_mfma_f32_16x16x32_bf16 v[40:43], v[104:107], v[172:175], v[40:43]
	v_mfma_f32_16x16x32_bf16 v[28:31], v[92:95], v[190:193], v[28:31]
	v_mfma_f32_16x16x32_bf16 v[24:27], v[104:107], v[190:193], v[24:27]
	v_mfma_f32_16x16x32_bf16 v[12:15], v[92:95], v[206:209], v[12:15]
	v_mfma_f32_16x16x32_bf16 v[8:11], v[104:107], v[206:209], v[8:11]
	v_mfma_f32_16x16x32_bf16 v[52:55], v[108:111], v[160:163], v[52:55]
	v_mfma_f32_16x16x32_bf16 v[48:51], v[120:123], v[160:163], v[48:51]
	v_mfma_f32_16x16x32_bf16 v[36:39], v[108:111], v[168:171], v[36:39]
	v_mfma_f32_16x16x32_bf16 v[32:35], v[120:123], v[168:171], v[32:35]
	v_mfma_f32_16x16x32_bf16 v[20:23], v[108:111], v[176:179], v[20:23]
	v_mfma_f32_16x16x32_bf16 v[16:19], v[120:123], v[176:179], v[16:19]
	v_mfma_f32_16x16x32_bf16 v[4:7], v[108:111], v[202:205], v[4:7]
	v_mfma_f32_16x16x32_bf16 v[0:3], v[120:123], v[202:205], v[0:3]
	v_mfma_f32_16x16x32_bf16 v[52:55], v[116:119], v[164:167], v[52:55]
	v_mfma_f32_16x16x32_bf16 v[48:51], v[124:127], v[164:167], v[48:51]
	v_mfma_f32_16x16x32_bf16 v[36:39], v[116:119], v[172:175], v[36:39]
	v_mfma_f32_16x16x32_bf16 v[32:35], v[124:127], v[172:175], v[32:35]
	v_mfma_f32_16x16x32_bf16 v[20:23], v[116:119], v[190:193], v[20:23]
	v_mfma_f32_16x16x32_bf16 v[16:19], v[124:127], v[190:193], v[16:19]
	v_mfma_f32_16x16x32_bf16 v[4:7], v[116:119], v[206:209], v[4:7]
	v_mfma_f32_16x16x32_bf16 v[0:3], v[124:127], v[206:209], v[0:3]
	s_setprio 0
	s_barrier
	s_add_i32 s3, s3, 2
	s_add_u32 s36, s36, 0x100
	s_addc_u32 s37, s37, 0
	s_cmp_ge_i32 s3, s67
	s_cbranch_scc0 .LBB0_628

.LBB0_667:
	s_mov_b64 s[24:25], s[16:17]
	ds_read_b128 v[140:143], v134
	ds_read_b128 v[144:147], v134 offset:1024
	ds_read_b128 v[148:151], v134 offset:2048
	ds_read_b128 v[152:155], v134 offset:3072
	ds_read_b128 v[156:159], v135
	ds_read_b128 v[160:163], v135 offset:1024
	ds_read_b128 v[164:167], v135 offset:2048
	ds_read_b128 v[168:171], v135 offset:3072
	s_add_u32 s38, s0, s24
	s_addc_u32 s39, s1, s25
	s_add_u32 s26, s38, 0x100
	s_addc_u32 s27, s39, 0
	s_add_u32 s24, s2, s24
	s_addc_u32 s25, s3, s25
	s_add_u32 s24, s24, 0x100
	s_addc_u32 s25, s25, 0
	s_cmp_eq_u32 s31, s34
	s_cselect_b32 s27, s13, s27
	s_cselect_b32 s26, s12, s26
	s_cselect_b32 s25, s15, s25
	s_cselect_b32 s24, s14, s24
	s_add_u32 s38, s38, 0x80080
	s_addc_u32 s39, s39, 0
	s_mov_b32 m0, s35
	v_lshl_add_u64 v[206:207], s[38:39], 0, v[128:129]
	ds_read_b128 v[172:175], v136
	ds_read_b128 v[176:179], v136 offset:1024
	ds_read_b128 v[182:185], v136 offset:2048
	ds_read_b128 v[186:189], v136 offset:3072
	ds_read_b128 v[190:193], v136 offset:4096
	ds_read_b128 v[194:197], v136 offset:5120
	ds_read_b128 v[198:201], v136 offset:6144
	ds_read_b128 v[202:205], v136 offset:7168
	global_load_lds_dwordx4 v[206:207], off
	v_lshl_add_u64 v[206:207], s[38:39], 0, v[130:131]
	s_mov_b32 m0, s36
	s_nop 0
	global_load_lds_dwordx4 v[206:207], off
	s_waitcnt vmcnt(8)
	s_waitcnt lgkmcnt(0)
	s_barrier
	s_setprio 1
	v_mfma_f32_16x16x32_bf16 v[124:127], v[140:143], v[172:175], v[124:127]
	v_mfma_f32_16x16x32_bf16 v[120:123], v[148:151], v[172:175], v[120:123]
	v_mfma_f32_16x16x32_bf16 v[108:111], v[140:143], v[182:185], v[108:111]
	v_mfma_f32_16x16x32_bf16 v[104:107], v[148:151], v[182:185], v[104:107]
	v_mfma_f32_16x16x32_bf16 v[92:95], v[140:143], v[190:193], v[92:95]
	v_mfma_f32_16x16x32_bf16 v[88:91], v[148:151], v[190:193], v[88:91]
	v_mfma_f32_16x16x32_bf16 v[76:79], v[140:143], v[198:201], v[76:79]
	v_mfma_f32_16x16x32_bf16 v[72:75], v[148:151], v[198:201], v[72:75]
	v_mfma_f32_16x16x32_bf16 v[124:127], v[144:147], v[176:179], v[124:127]
	v_mfma_f32_16x16x32_bf16 v[120:123], v[152:155], v[176:179], v[120:123]
	v_mfma_f32_16x16x32_bf16 v[108:111], v[144:147], v[186:189], v[108:111]
	v_mfma_f32_16x16x32_bf16 v[104:107], v[152:155], v[186:189], v[104:107]
	v_mfma_f32_16x16x32_bf16 v[92:95], v[144:147], v[194:197], v[92:95]
	v_mfma_f32_16x16x32_bf16 v[88:91], v[152:155], v[194:197], v[88:91]
	v_mfma_f32_16x16x32_bf16 v[76:79], v[144:147], v[202:205], v[76:79]
	v_mfma_f32_16x16x32_bf16 v[72:75], v[152:155], v[202:205], v[72:75]
	v_mfma_f32_16x16x32_bf16 v[116:119], v[156:159], v[172:175], v[116:119]
	v_mfma_f32_16x16x32_bf16 v[112:115], v[164:167], v[172:175], v[112:115]
	v_mfma_f32_16x16x32_bf16 v[100:103], v[156:159], v[182:185], v[100:103]
	v_mfma_f32_16x16x32_bf16 v[96:99], v[164:167], v[182:185], v[96:99]
	v_mfma_f32_16x16x32_bf16 v[84:87], v[156:159], v[190:193], v[84:87]
	v_mfma_f32_16x16x32_bf16 v[80:83], v[164:167], v[190:193], v[80:83]
	v_mfma_f32_16x16x32_bf16 v[68:71], v[156:159], v[198:201], v[68:71]
	v_mfma_f32_16x16x32_bf16 v[64:67], v[164:167], v[198:201], v[64:67]
	v_mfma_f32_16x16x32_bf16 v[116:119], v[160:163], v[176:179], v[116:119]
	v_mfma_f32_16x16x32_bf16 v[112:115], v[168:171], v[176:179], v[112:115]
	v_mfma_f32_16x16x32_bf16 v[100:103], v[160:163], v[186:189], v[100:103]
	v_mfma_f32_16x16x32_bf16 v[96:99], v[168:171], v[186:189], v[96:99]
	v_mfma_f32_16x16x32_bf16 v[84:87], v[160:163], v[194:197], v[84:87]
	v_mfma_f32_16x16x32_bf16 v[80:83], v[168:171], v[194:197], v[80:83]
	v_mfma_f32_16x16x32_bf16 v[68:71], v[160:163], v[202:205], v[68:71]
	v_mfma_f32_16x16x32_bf16 v[64:67], v[168:171], v[202:205], v[64:67]
	s_setprio 0
	s_barrier
	s_mov_b32 m0, s37
	v_lshl_add_u64 v[206:207], s[24:25], 0, v[128:129]
	s_add_u32 s38, s24, 0x80000
	ds_read_b128 v[172:175], v136 offset:16384
	ds_read_b128 v[176:179], v136 offset:17408
	ds_read_b128 v[182:185], v136 offset:18432
	ds_read_b128 v[186:189], v136 offset:19456
	ds_read_b128 v[190:193], v136 offset:20480
	ds_read_b128 v[194:197], v136 offset:21504
	ds_read_b128 v[198:201], v136 offset:22528
	ds_read_b128 v[202:205], v136 offset:23552
	global_load_lds_dwordx4 v[206:207], off
	v_lshl_add_u64 v[208:209], s[24:25], 0, v[130:131]
	s_mov_b32 m0, s52
	s_addc_u32 s39, s25, 0
	global_load_lds_dwordx4 v[208:209], off
	v_lshl_add_u64 v[210:211], s[38:39], 0, v[128:129]
	s_mov_b32 m0, s53
	v_lshl_add_u64 v[212:213], s[26:27], 0, v[130:131]
	global_load_lds_dwordx4 v[210:211], off
	v_lshl_add_u64 v[210:211], s[38:39], 0, v[130:131]
	s_mov_b32 m0, s54
	s_nop 0
	global_load_lds_dwordx4 v[210:211], off
	v_lshl_add_u64 v[210:211], s[26:27], 0, v[128:129]
	s_mov_b32 m0, s9
	s_nop 0
	global_load_lds_dwordx4 v[210:211], off
	s_mov_b32 m0, s18
	s_nop 0
	global_load_lds_dwordx4 v[212:213], off
	s_waitcnt vmcnt(8)
	s_waitcnt lgkmcnt(0)
	s_barrier
	s_setprio 1
	v_mfma_f32_16x16x32_bf16 v[60:63], v[140:143], v[172:175], v[60:63]
	v_mfma_f32_16x16x32_bf16 v[56:59], v[148:151], v[172:175], v[56:59]
	v_mfma_f32_16x16x32_bf16 v[44:47], v[140:143], v[182:185], v[44:47]
	v_mfma_f32_16x16x32_bf16 v[40:43], v[148:151], v[182:185], v[40:43]
	v_mfma_f32_16x16x32_bf16 v[28:31], v[140:143], v[190:193], v[28:31]
	v_mfma_f32_16x16x32_bf16 v[24:27], v[148:151], v[190:193], v[24:27]
	v_mfma_f32_16x16x32_bf16 v[12:15], v[140:143], v[198:201], v[12:15]
	v_mfma_f32_16x16x32_bf16 v[8:11], v[148:151], v[198:201], v[8:11]
	v_mfma_f32_16x16x32_bf16 v[60:63], v[144:147], v[176:179], v[60:63]
	v_mfma_f32_16x16x32_bf16 v[56:59], v[152:155], v[176:179], v[56:59]
	v_mfma_f32_16x16x32_bf16 v[44:47], v[144:147], v[186:189], v[44:47]
	v_mfma_f32_16x16x32_bf16 v[40:43], v[152:155], v[186:189], v[40:43]
	v_mfma_f32_16x16x32_bf16 v[28:31], v[144:147], v[194:197], v[28:31]
	v_mfma_f32_16x16x32_bf16 v[24:27], v[152:155], v[194:197], v[24:27]
	v_mfma_f32_16x16x32_bf16 v[12:15], v[144:147], v[202:205], v[12:15]
	v_mfma_f32_16x16x32_bf16 v[8:11], v[152:155], v[202:205], v[8:11]
	v_mfma_f32_16x16x32_bf16 v[52:55], v[156:159], v[172:175], v[52:55]
	v_mfma_f32_16x16x32_bf16 v[48:51], v[164:167], v[172:175], v[48:51]
	v_mfma_f32_16x16x32_bf16 v[36:39], v[156:159], v[182:185], v[36:39]
	v_mfma_f32_16x16x32_bf16 v[32:35], v[164:167], v[182:185], v[32:35]
	v_mfma_f32_16x16x32_bf16 v[20:23], v[156:159], v[190:193], v[20:23]
	v_mfma_f32_16x16x32_bf16 v[16:19], v[164:167], v[190:193], v[16:19]
	v_mfma_f32_16x16x32_bf16 v[4:7], v[156:159], v[198:201], v[4:7]
	v_mfma_f32_16x16x32_bf16 v[0:3], v[164:167], v[198:201], v[0:3]
	v_mfma_f32_16x16x32_bf16 v[52:55], v[160:163], v[176:179], v[52:55]
	v_mfma_f32_16x16x32_bf16 v[48:51], v[168:171], v[176:179], v[48:51]
	v_mfma_f32_16x16x32_bf16 v[36:39], v[160:163], v[186:189], v[36:39]
	v_mfma_f32_16x16x32_bf16 v[32:35], v[168:171], v[186:189], v[32:35]
	v_mfma_f32_16x16x32_bf16 v[20:23], v[160:163], v[194:197], v[20:23]
	v_mfma_f32_16x16x32_bf16 v[16:19], v[168:171], v[194:197], v[16:19]
	v_mfma_f32_16x16x32_bf16 v[4:7], v[160:163], v[202:205], v[4:7]
	v_mfma_f32_16x16x32_bf16 v[0:3], v[168:171], v[202:205], v[0:3]
	s_setprio 0
	s_barrier
	ds_read_b128 v[140:143], v137
	ds_read_b128 v[144:147], v137 offset:1024
	ds_read_b128 v[148:151], v137 offset:2048
	ds_read_b128 v[152:155], v137 offset:3072
	ds_read_b128 v[156:159], v138
	ds_read_b128 v[160:163], v138 offset:1024
	ds_read_b128 v[164:167], v138 offset:2048
	ds_read_b128 v[168:171], v138 offset:3072
	s_add_u32 s26, s26, 0x80000
	s_addc_u32 s27, s27, 0
	s_mov_b32 m0, s19
	v_lshl_add_u64 v[214:215], s[26:27], 0, v[128:129]
	ds_read_b128 v[172:175], v136 offset:32768
	ds_read_b128 v[176:179], v136 offset:33792
	ds_read_b128 v[182:185], v136 offset:34816
	ds_read_b128 v[186:189], v136 offset:35840
	ds_read_b128 v[190:193], v136 offset:36864
	ds_read_b128 v[194:197], v136 offset:37888
	ds_read_b128 v[198:201], v136 offset:38912
	ds_read_b128 v[202:205], v136 offset:39936
	global_load_lds_dwordx4 v[214:215], off
	v_lshl_add_u64 v[214:215], s[26:27], 0, v[130:131]
	s_mov_b32 m0, s23
	s_nop 0
	global_load_lds_dwordx4 v[214:215], off
	s_waitcnt vmcnt(8)
	s_waitcnt lgkmcnt(0)
	s_barrier
	s_setprio 1
	v_mfma_f32_16x16x32_bf16 v[124:127], v[140:143], v[172:175], v[124:127]
	v_mfma_f32_16x16x32_bf16 v[120:123], v[148:151], v[172:175], v[120:123]
	v_mfma_f32_16x16x32_bf16 v[108:111], v[140:143], v[182:185], v[108:111]
	v_mfma_f32_16x16x32_bf16 v[104:107], v[148:151], v[182:185], v[104:107]
	v_mfma_f32_16x16x32_bf16 v[92:95], v[140:143], v[190:193], v[92:95]
	v_mfma_f32_16x16x32_bf16 v[88:91], v[148:151], v[190:193], v[88:91]
	v_mfma_f32_16x16x32_bf16 v[76:79], v[140:143], v[198:201], v[76:79]
	v_mfma_f32_16x16x32_bf16 v[72:75], v[148:151], v[198:201], v[72:75]
	v_mfma_f32_16x16x32_bf16 v[124:127], v[144:147], v[176:179], v[124:127]
	v_mfma_f32_16x16x32_bf16 v[120:123], v[152:155], v[176:179], v[120:123]
	v_mfma_f32_16x16x32_bf16 v[108:111], v[144:147], v[186:189], v[108:111]
	v_mfma_f32_16x16x32_bf16 v[104:107], v[152:155], v[186:189], v[104:107]
	v_mfma_f32_16x16x32_bf16 v[92:95], v[144:147], v[194:197], v[92:95]
	v_mfma_f32_16x16x32_bf16 v[88:91], v[152:155], v[194:197], v[88:91]
	v_mfma_f32_16x16x32_bf16 v[76:79], v[144:147], v[202:205], v[76:79]
	v_mfma_f32_16x16x32_bf16 v[72:75], v[152:155], v[202:205], v[72:75]
	v_mfma_f32_16x16x32_bf16 v[116:119], v[156:159], v[172:175], v[116:119]
	v_mfma_f32_16x16x32_bf16 v[112:115], v[164:167], v[172:175], v[112:115]
	v_mfma_f32_16x16x32_bf16 v[100:103], v[156:159], v[182:185], v[100:103]
	v_mfma_f32_16x16x32_bf16 v[96:99], v[164:167], v[182:185], v[96:99]
	v_mfma_f32_16x16x32_bf16 v[84:87], v[156:159], v[190:193], v[84:87]
	v_mfma_f32_16x16x32_bf16 v[80:83], v[164:167], v[190:193], v[80:83]
	v_mfma_f32_16x16x32_bf16 v[68:71], v[156:159], v[198:201], v[68:71]
	v_mfma_f32_16x16x32_bf16 v[64:67], v[164:167], v[198:201], v[64:67]
	v_mfma_f32_16x16x32_bf16 v[116:119], v[160:163], v[176:179], v[116:119]
	v_mfma_f32_16x16x32_bf16 v[112:115], v[168:171], v[176:179], v[112:115]
	v_mfma_f32_16x16x32_bf16 v[100:103], v[160:163], v[186:189], v[100:103]
	v_mfma_f32_16x16x32_bf16 v[96:99], v[168:171], v[186:189], v[96:99]
	v_mfma_f32_16x16x32_bf16 v[84:87], v[160:163], v[194:197], v[84:87]
	v_mfma_f32_16x16x32_bf16 v[80:83], v[168:171], v[194:197], v[80:83]
	v_mfma_f32_16x16x32_bf16 v[68:71], v[160:163], v[202:205], v[68:71]
	v_mfma_f32_16x16x32_bf16 v[64:67], v[168:171], v[202:205], v[64:67]
	s_setprio 0
	s_barrier
	s_mov_b32 m0, s55
	v_lshl_add_u64 v[206:207], v[206:207], 0, s[10:11]
	s_add_u32 s24, s24, 0x80080
	ds_read_b128 v[172:175], v136 offset:49152
	ds_read_b128 v[176:179], v136 offset:50176
	ds_read_b128 v[182:185], v136 offset:51200
	ds_read_b128 v[186:189], v136 offset:52224
	ds_read_b128 v[190:193], v136 offset:53248
	ds_read_b128 v[194:197], v136 offset:54272
	ds_read_b128 v[198:201], v136 offset:55296
	ds_read_b128 v[202:205], v136 offset:56320
	global_load_lds_dwordx4 v[206:207], off
	v_lshl_add_u64 v[206:207], v[208:209], 0, s[10:11]
	s_mov_b32 m0, s56
	s_addc_u32 s25, s25, 0
	global_load_lds_dwordx4 v[206:207], off
	v_lshl_add_u64 v[206:207], s[24:25], 0, v[128:129]
	s_mov_b32 m0, s57
	s_nop 0
	global_load_lds_dwordx4 v[206:207], off
	v_lshl_add_u64 v[206:207], s[24:25], 0, v[130:131]
	s_mov_b32 m0, s58
	s_nop 0
	global_load_lds_dwordx4 v[206:207], off
	v_lshl_add_u64 v[206:207], v[210:211], 0, s[10:11]
	s_mov_b32 m0, s28
	s_nop 0
	global_load_lds_dwordx4 v[206:207], off
	v_lshl_add_u64 v[206:207], v[212:213], 0, s[10:11]
	s_mov_b32 m0, s29
	s_nop 0
	global_load_lds_dwordx4 v[206:207], off
	s_waitcnt vmcnt(8)
	s_waitcnt lgkmcnt(0)
	s_barrier
	s_setprio 1
	v_mfma_f32_16x16x32_bf16 v[60:63], v[140:143], v[172:175], v[60:63]
	v_mfma_f32_16x16x32_bf16 v[56:59], v[148:151], v[172:175], v[56:59]
	v_mfma_f32_16x16x32_bf16 v[44:47], v[140:143], v[182:185], v[44:47]
	v_mfma_f32_16x16x32_bf16 v[40:43], v[148:151], v[182:185], v[40:43]
	v_mfma_f32_16x16x32_bf16 v[28:31], v[140:143], v[190:193], v[28:31]
	v_mfma_f32_16x16x32_bf16 v[24:27], v[148:151], v[190:193], v[24:27]
	v_mfma_f32_16x16x32_bf16 v[12:15], v[140:143], v[198:201], v[12:15]
	v_mfma_f32_16x16x32_bf16 v[8:11], v[148:151], v[198:201], v[8:11]
	v_mfma_f32_16x16x32_bf16 v[60:63], v[144:147], v[176:179], v[60:63]
	v_mfma_f32_16x16x32_bf16 v[56:59], v[152:155], v[176:179], v[56:59]
	v_mfma_f32_16x16x32_bf16 v[44:47], v[144:147], v[186:189], v[44:47]
	v_mfma_f32_16x16x32_bf16 v[40:43], v[152:155], v[186:189], v[40:43]
	v_mfma_f32_16x16x32_bf16 v[28:31], v[144:147], v[194:197], v[28:31]
	v_mfma_f32_16x16x32_bf16 v[24:27], v[152:155], v[194:197], v[24:27]
	v_mfma_f32_16x16x32_bf16 v[12:15], v[144:147], v[202:205], v[12:15]
	v_mfma_f32_16x16x32_bf16 v[8:11], v[152:155], v[202:205], v[8:11]
	v_mfma_f32_16x16x32_bf16 v[52:55], v[156:159], v[172:175], v[52:55]
	v_mfma_f32_16x16x32_bf16 v[48:51], v[164:167], v[172:175], v[48:51]
	v_mfma_f32_16x16x32_bf16 v[36:39], v[156:159], v[182:185], v[36:39]
	v_mfma_f32_16x16x32_bf16 v[32:35], v[164:167], v[182:185], v[32:35]
	v_mfma_f32_16x16x32_bf16 v[20:23], v[156:159], v[190:193], v[20:23]
	v_mfma_f32_16x16x32_bf16 v[16:19], v[164:167], v[190:193], v[16:19]
	v_mfma_f32_16x16x32_bf16 v[4:7], v[156:159], v[198:201], v[4:7]
	v_mfma_f32_16x16x32_bf16 v[0:3], v[164:167], v[198:201], v[0:3]
	v_mfma_f32_16x16x32_bf16 v[52:55], v[160:163], v[176:179], v[52:55]
	v_mfma_f32_16x16x32_bf16 v[48:51], v[168:171], v[176:179], v[48:51]
	v_mfma_f32_16x16x32_bf16 v[36:39], v[160:163], v[186:189], v[36:39]
	v_mfma_f32_16x16x32_bf16 v[32:35], v[168:171], v[186:189], v[32:35]
	v_mfma_f32_16x16x32_bf16 v[20:23], v[160:163], v[194:197], v[20:23]
	v_mfma_f32_16x16x32_bf16 v[16:19], v[168:171], v[194:197], v[16:19]
	v_mfma_f32_16x16x32_bf16 v[4:7], v[160:163], v[202:205], v[4:7]
	v_mfma_f32_16x16x32_bf16 v[0:3], v[168:171], v[202:205], v[0:3]
	s_setprio 0
	s_barrier
	s_add_i32 s34, s34, 2
	s_add_u32 s16, s16, 0x100
	s_addc_u32 s17, s17, 0
	s_cmp_ge_i32 s34, s30
	s_cbranch_scc0 .LBB0_667
	v_mov_b32_e32 v129, v127

.LBB0_878:
	s_mov_b64 s[6:7], s[54:55]
	ds_read_b128 v[140:143], v147
	ds_read_b128 v[150:153], v147 offset:1024
	ds_read_b128 v[154:157], v147 offset:2048
	ds_read_b128 v[158:161], v147 offset:3072
	ds_read_b128 v[162:165], v148
	ds_read_b128 v[166:169], v148 offset:1024
	ds_read_b128 v[170:173], v148 offset:2048
	ds_read_b128 v[174:177], v148 offset:3072
	s_add_u32 s5, s16, s6
	s_addc_u32 s8, s17, s7
	s_add_u32 s9, s5, 0x100
	s_addc_u32 s28, s8, 0
	s_add_u32 s6, s36, s6
	s_addc_u32 s7, s37, s7
	s_add_u32 s6, s6, 0x100
	s_addc_u32 s7, s7, 0
	s_cmp_eq_u32 s75, s4
	s_cselect_b32 s71, s65, s28
	s_cselect_b32 s70, s64, s9
	s_cselect_b32 s69, s67, s7
	s_cselect_b32 s68, s66, s6
	s_add_u32 s6, s5, 0x80080
	s_addc_u32 s7, s8, 0
	v_lshl_add_u64 v[178:179], s[6:7], 0, v[134:135]
	s_add_i32 m0, s23, 0xc000
	ds_read_b128 v[182:185], v149
	ds_read_b128 v[186:189], v149 offset:1024
	ds_read_b128 v[190:193], v149 offset:2048
	ds_read_b128 v[194:197], v149 offset:3072
	ds_read_b128 v[198:201], v149 offset:4096
	ds_read_b128 v[202:205], v149 offset:5120
	ds_read_b128 v[206:209], v149 offset:6144
	ds_read_b128 v[210:213], v149 offset:7168
	global_load_lds_dwordx4 v[178:179], off
	v_lshl_add_u64 v[178:179], s[6:7], 0, v[130:131]
	s_add_i32 m0, s23, 0xe000
	s_nop 0
	global_load_lds_dwordx4 v[178:179], off
	s_waitcnt vmcnt(8)
	s_waitcnt lgkmcnt(0)
	s_barrier
	s_setprio 1
	v_mfma_f32_16x16x32_bf16 v[120:123], v[140:143], v[182:185], v[120:123]
	v_mfma_f32_16x16x32_bf16 v[116:119], v[154:157], v[182:185], v[116:119]
	v_mfma_f32_16x16x32_bf16 v[108:111], v[140:143], v[190:193], v[108:111]
	v_mfma_f32_16x16x32_bf16 v[100:103], v[154:157], v[190:193], v[100:103]
	v_mfma_f32_16x16x32_bf16 v[92:95], v[140:143], v[198:201], v[92:95]
	v_mfma_f32_16x16x32_bf16 v[84:87], v[154:157], v[198:201], v[84:87]
	v_mfma_f32_16x16x32_bf16 v[76:79], v[140:143], v[206:209], v[76:79]
	v_mfma_f32_16x16x32_bf16 v[68:71], v[154:157], v[206:209], v[68:71]
	v_mfma_f32_16x16x32_bf16 v[120:123], v[150:153], v[186:189], v[120:123]
	v_mfma_f32_16x16x32_bf16 v[116:119], v[158:161], v[186:189], v[116:119]
	v_mfma_f32_16x16x32_bf16 v[108:111], v[150:153], v[194:197], v[108:111]
	v_mfma_f32_16x16x32_bf16 v[100:103], v[158:161], v[194:197], v[100:103]
	v_mfma_f32_16x16x32_bf16 v[92:95], v[150:153], v[202:205], v[92:95]
	v_mfma_f32_16x16x32_bf16 v[84:87], v[158:161], v[202:205], v[84:87]
	v_mfma_f32_16x16x32_bf16 v[76:79], v[150:153], v[210:213], v[76:79]
	v_mfma_f32_16x16x32_bf16 v[68:71], v[158:161], v[210:213], v[68:71]
	v_mfma_f32_16x16x32_bf16 v[124:127], v[162:165], v[182:185], v[124:127]
	v_mfma_f32_16x16x32_bf16 v[112:115], v[170:173], v[182:185], v[112:115]
	v_mfma_f32_16x16x32_bf16 v[104:107], v[162:165], v[190:193], v[104:107]
	v_mfma_f32_16x16x32_bf16 v[96:99], v[170:173], v[190:193], v[96:99]
	v_mfma_f32_16x16x32_bf16 v[88:91], v[162:165], v[198:201], v[88:91]
	v_mfma_f32_16x16x32_bf16 v[80:83], v[170:173], v[198:201], v[80:83]
	v_mfma_f32_16x16x32_bf16 v[72:75], v[162:165], v[206:209], v[72:75]
	v_mfma_f32_16x16x32_bf16 v[64:67], v[170:173], v[206:209], v[64:67]
	v_mfma_f32_16x16x32_bf16 v[124:127], v[166:169], v[186:189], v[124:127]
	v_mfma_f32_16x16x32_bf16 v[112:115], v[174:177], v[186:189], v[112:115]
	v_mfma_f32_16x16x32_bf16 v[104:107], v[166:169], v[194:197], v[104:107]
	v_mfma_f32_16x16x32_bf16 v[96:99], v[174:177], v[194:197], v[96:99]
	v_mfma_f32_16x16x32_bf16 v[88:91], v[166:169], v[202:205], v[88:91]
	v_mfma_f32_16x16x32_bf16 v[80:83], v[174:177], v[202:205], v[80:83]
	v_mfma_f32_16x16x32_bf16 v[72:75], v[166:169], v[210:213], v[72:75]
	v_mfma_f32_16x16x32_bf16 v[64:67], v[174:177], v[210:213], v[64:67]
	s_setprio 0
	s_barrier
	s_add_i32 s5, s76, s18
	v_lshl_add_u64 v[178:179], s[68:69], 0, v[132:133]
	s_mov_b32 m0, s5
	ds_read_b128 v[182:185], v149 offset:16384
	ds_read_b128 v[186:189], v149 offset:17408
	ds_read_b128 v[190:193], v149 offset:18432
	ds_read_b128 v[194:197], v149 offset:19456
	ds_read_b128 v[198:201], v149 offset:20480
	ds_read_b128 v[202:205], v149 offset:21504
	ds_read_b128 v[206:209], v149 offset:22528
	ds_read_b128 v[210:213], v149 offset:23552
	global_load_lds_dwordx4 v[178:179], off
	s_add_i32 m0, s5, 0x2000
	s_add_u32 s6, s68, 0x80000
	v_lshl_add_u64 v[214:215], s[68:69], 0, v[128:129]
	s_addc_u32 s7, s69, 0
	s_add_i32 s5, s77, s18
	global_load_lds_dwordx4 v[214:215], off
	v_lshl_add_u64 v[216:217], s[6:7], 0, v[132:133]
	s_mov_b32 m0, s5
	v_lshl_add_u64 v[218:219], s[70:71], 0, v[130:131]
	global_load_lds_dwordx4 v[216:217], off
	v_lshl_add_u64 v[216:217], s[6:7], 0, v[128:129]
	s_add_i32 m0, s5, 0x2000
	s_nop 0
	global_load_lds_dwordx4 v[216:217], off
	v_lshl_add_u64 v[216:217], s[70:71], 0, v[134:135]
	s_mov_b32 m0, s23
	s_nop 0
	global_load_lds_dwordx4 v[216:217], off
	s_mov_b32 m0, s30
	s_nop 0
	global_load_lds_dwordx4 v[218:219], off
	s_waitcnt vmcnt(8)
	s_waitcnt lgkmcnt(0)
	s_barrier
	s_setprio 1
	v_mfma_f32_16x16x32_bf16 v[60:63], v[140:143], v[182:185], v[60:63]
	v_mfma_f32_16x16x32_bf16 v[52:55], v[154:157], v[182:185], v[52:55]
	v_mfma_f32_16x16x32_bf16 v[44:47], v[140:143], v[190:193], v[44:47]
	v_mfma_f32_16x16x32_bf16 v[36:39], v[154:157], v[190:193], v[36:39]
	v_mfma_f32_16x16x32_bf16 v[28:31], v[140:143], v[198:201], v[28:31]
	v_mfma_f32_16x16x32_bf16 v[20:23], v[154:157], v[198:201], v[20:23]
	v_mfma_f32_16x16x32_bf16 v[12:15], v[140:143], v[206:209], v[12:15]
	v_mfma_f32_16x16x32_bf16 v[4:7], v[154:157], v[206:209], v[4:7]
	v_mfma_f32_16x16x32_bf16 v[60:63], v[150:153], v[186:189], v[60:63]
	v_mfma_f32_16x16x32_bf16 v[52:55], v[158:161], v[186:189], v[52:55]
	v_mfma_f32_16x16x32_bf16 v[44:47], v[150:153], v[194:197], v[44:47]
	v_mfma_f32_16x16x32_bf16 v[36:39], v[158:161], v[194:197], v[36:39]
	v_mfma_f32_16x16x32_bf16 v[28:31], v[150:153], v[202:205], v[28:31]
	v_mfma_f32_16x16x32_bf16 v[20:23], v[158:161], v[202:205], v[20:23]
	v_mfma_f32_16x16x32_bf16 v[12:15], v[150:153], v[210:213], v[12:15]
	v_mfma_f32_16x16x32_bf16 v[4:7], v[158:161], v[210:213], v[4:7]
	v_mfma_f32_16x16x32_bf16 v[56:59], v[162:165], v[182:185], v[56:59]
	v_mfma_f32_16x16x32_bf16 v[48:51], v[170:173], v[182:185], v[48:51]
	v_mfma_f32_16x16x32_bf16 v[40:43], v[162:165], v[190:193], v[40:43]
	v_mfma_f32_16x16x32_bf16 v[32:35], v[170:173], v[190:193], v[32:35]
	v_mfma_f32_16x16x32_bf16 v[24:27], v[162:165], v[198:201], v[24:27]
	v_mfma_f32_16x16x32_bf16 v[16:19], v[170:173], v[198:201], v[16:19]
	v_mfma_f32_16x16x32_bf16 v[8:11], v[162:165], v[206:209], v[8:11]
	v_mfma_f32_16x16x32_bf16 v[0:3], v[170:173], v[206:209], v[0:3]
	v_mfma_f32_16x16x32_bf16 v[56:59], v[166:169], v[186:189], v[56:59]
	v_mfma_f32_16x16x32_bf16 v[48:51], v[174:177], v[186:189], v[48:51]
	v_mfma_f32_16x16x32_bf16 v[40:43], v[166:169], v[194:197], v[40:43]
	v_mfma_f32_16x16x32_bf16 v[32:35], v[174:177], v[194:197], v[32:35]
	v_mfma_f32_16x16x32_bf16 v[24:27], v[166:169], v[202:205], v[24:27]
	v_mfma_f32_16x16x32_bf16 v[16:19], v[174:177], v[202:205], v[16:19]
	v_mfma_f32_16x16x32_bf16 v[8:11], v[166:169], v[210:213], v[8:11]
	v_mfma_f32_16x16x32_bf16 v[0:3], v[174:177], v[210:213], v[0:3]
	s_setprio 0
	s_barrier
	s_add_i32 s5, 0, 0x18000
	s_add_i32 s8, 0, 0x1c000
	v_add_u32_e32 v158, s5, v146
	v_add_u32_e32 v174, s8, v146
	ds_read_b128 v[140:143], v158
	ds_read_b128 v[150:153], v158 offset:1024
	ds_read_b128 v[154:157], v158 offset:2048
	ds_read_b128 v[158:161], v158 offset:3072
	ds_read_b128 v[162:165], v174
	ds_read_b128 v[166:169], v174 offset:1024
	ds_read_b128 v[170:173], v174 offset:2048
	ds_read_b128 v[174:177], v174 offset:3072
	s_add_u32 s6, s70, 0x80000
	s_addc_u32 s7, s71, 0
	s_mov_b32 m0, s31
	v_lshl_add_u64 v[220:221], s[6:7], 0, v[134:135]
	ds_read_b128 v[182:185], v149 offset:32768
	ds_read_b128 v[186:189], v149 offset:33792
	ds_read_b128 v[190:193], v149 offset:34816
	ds_read_b128 v[194:197], v149 offset:35840
	ds_read_b128 v[198:201], v149 offset:36864
	ds_read_b128 v[202:205], v149 offset:37888
	ds_read_b128 v[206:209], v149 offset:38912
	ds_read_b128 v[210:213], v149 offset:39936
	global_load_lds_dwordx4 v[220:221], off
	v_lshl_add_u64 v[220:221], s[6:7], 0, v[130:131]
	s_mov_b32 m0, s56
	s_nop 0
	global_load_lds_dwordx4 v[220:221], off
	s_waitcnt vmcnt(8)
	s_waitcnt lgkmcnt(0)
	s_barrier
	s_setprio 1
	v_mfma_f32_16x16x32_bf16 v[120:123], v[140:143], v[182:185], v[120:123]
	v_mfma_f32_16x16x32_bf16 v[116:119], v[154:157], v[182:185], v[116:119]
	v_mfma_f32_16x16x32_bf16 v[108:111], v[140:143], v[190:193], v[108:111]
	v_mfma_f32_16x16x32_bf16 v[100:103], v[154:157], v[190:193], v[100:103]
	v_mfma_f32_16x16x32_bf16 v[92:95], v[140:143], v[198:201], v[92:95]
	v_mfma_f32_16x16x32_bf16 v[84:87], v[154:157], v[198:201], v[84:87]
	v_mfma_f32_16x16x32_bf16 v[76:79], v[140:143], v[206:209], v[76:79]
	v_mfma_f32_16x16x32_bf16 v[68:71], v[154:157], v[206:209], v[68:71]
	v_mfma_f32_16x16x32_bf16 v[120:123], v[150:153], v[186:189], v[120:123]
	v_mfma_f32_16x16x32_bf16 v[116:119], v[158:161], v[186:189], v[116:119]
	v_mfma_f32_16x16x32_bf16 v[108:111], v[150:153], v[194:197], v[108:111]
	v_mfma_f32_16x16x32_bf16 v[100:103], v[158:161], v[194:197], v[100:103]
	v_mfma_f32_16x16x32_bf16 v[92:95], v[150:153], v[202:205], v[92:95]
	v_mfma_f32_16x16x32_bf16 v[84:87], v[158:161], v[202:205], v[84:87]
	v_mfma_f32_16x16x32_bf16 v[76:79], v[150:153], v[210:213], v[76:79]
	v_mfma_f32_16x16x32_bf16 v[68:71], v[158:161], v[210:213], v[68:71]
	v_mfma_f32_16x16x32_bf16 v[124:127], v[162:165], v[182:185], v[124:127]
	v_mfma_f32_16x16x32_bf16 v[112:115], v[170:173], v[182:185], v[112:115]
	v_mfma_f32_16x16x32_bf16 v[104:107], v[162:165], v[190:193], v[104:107]
	v_mfma_f32_16x16x32_bf16 v[96:99], v[170:173], v[190:193], v[96:99]
	v_mfma_f32_16x16x32_bf16 v[88:91], v[162:165], v[198:201], v[88:91]
	v_mfma_f32_16x16x32_bf16 v[80:83], v[170:173], v[198:201], v[80:83]
	v_mfma_f32_16x16x32_bf16 v[72:75], v[162:165], v[206:209], v[72:75]
	v_mfma_f32_16x16x32_bf16 v[64:67], v[170:173], v[206:209], v[64:67]
	v_mfma_f32_16x16x32_bf16 v[124:127], v[166:169], v[186:189], v[124:127]
	v_mfma_f32_16x16x32_bf16 v[112:115], v[174:177], v[186:189], v[112:115]
	v_mfma_f32_16x16x32_bf16 v[104:107], v[166:169], v[194:197], v[104:107]
	v_mfma_f32_16x16x32_bf16 v[96:99], v[174:177], v[194:197], v[96:99]
	v_mfma_f32_16x16x32_bf16 v[88:91], v[166:169], v[202:205], v[88:91]
	v_mfma_f32_16x16x32_bf16 v[80:83], v[174:177], v[202:205], v[80:83]
	v_mfma_f32_16x16x32_bf16 v[72:75], v[166:169], v[210:213], v[72:75]
	v_mfma_f32_16x16x32_bf16 v[64:67], v[174:177], v[210:213], v[64:67]
	s_setprio 0
	s_barrier
	s_add_i32 s5, s5, s18
	v_lshl_add_u64 v[178:179], v[178:179], 0, s[34:35]
	s_mov_b32 m0, s5
	ds_read_b128 v[182:185], v149 offset:49152
	ds_read_b128 v[186:189], v149 offset:50176
	ds_read_b128 v[190:193], v149 offset:51200
	ds_read_b128 v[194:197], v149 offset:52224
	ds_read_b128 v[198:201], v149 offset:53248
	ds_read_b128 v[202:205], v149 offset:54272
	ds_read_b128 v[206:209], v149 offset:55296
	ds_read_b128 v[210:213], v149 offset:56320
	global_load_lds_dwordx4 v[178:179], off
	s_add_i32 m0, s5, 0x2000
	s_add_u32 s6, s68, 0x80080
	v_lshl_add_u64 v[178:179], v[214:215], 0, s[34:35]
	s_addc_u32 s7, s69, 0
	s_add_i32 s5, s8, s18
	global_load_lds_dwordx4 v[178:179], off
	v_lshl_add_u64 v[178:179], s[6:7], 0, v[132:133]
	s_mov_b32 m0, s5
	s_nop 0
	global_load_lds_dwordx4 v[178:179], off
	v_lshl_add_u64 v[178:179], s[6:7], 0, v[128:129]
	s_add_i32 m0, s5, 0x2000
	s_nop 0
	global_load_lds_dwordx4 v[178:179], off
	v_lshl_add_u64 v[178:179], v[216:217], 0, s[34:35]
	s_mov_b32 m0, s73
	s_nop 0
	global_load_lds_dwordx4 v[178:179], off
	v_lshl_add_u64 v[178:179], v[218:219], 0, s[34:35]
	s_mov_b32 m0, s74
	s_nop 0
	global_load_lds_dwordx4 v[178:179], off
	s_waitcnt vmcnt(8)
	s_waitcnt lgkmcnt(0)
	s_barrier
	s_setprio 1
	v_mfma_f32_16x16x32_bf16 v[60:63], v[140:143], v[182:185], v[60:63]
	v_mfma_f32_16x16x32_bf16 v[52:55], v[154:157], v[182:185], v[52:55]
	v_mfma_f32_16x16x32_bf16 v[44:47], v[140:143], v[190:193], v[44:47]
	v_mfma_f32_16x16x32_bf16 v[36:39], v[154:157], v[190:193], v[36:39]
	v_mfma_f32_16x16x32_bf16 v[28:31], v[140:143], v[198:201], v[28:31]
	v_mfma_f32_16x16x32_bf16 v[20:23], v[154:157], v[198:201], v[20:23]
	v_mfma_f32_16x16x32_bf16 v[12:15], v[140:143], v[206:209], v[12:15]
	v_mfma_f32_16x16x32_bf16 v[4:7], v[154:157], v[206:209], v[4:7]
	v_mfma_f32_16x16x32_bf16 v[60:63], v[150:153], v[186:189], v[60:63]
	v_mfma_f32_16x16x32_bf16 v[52:55], v[158:161], v[186:189], v[52:55]
	v_mfma_f32_16x16x32_bf16 v[44:47], v[150:153], v[194:197], v[44:47]
	v_mfma_f32_16x16x32_bf16 v[36:39], v[158:161], v[194:197], v[36:39]
	v_mfma_f32_16x16x32_bf16 v[28:31], v[150:153], v[202:205], v[28:31]
	v_mfma_f32_16x16x32_bf16 v[20:23], v[158:161], v[202:205], v[20:23]
	v_mfma_f32_16x16x32_bf16 v[12:15], v[150:153], v[210:213], v[12:15]
	v_mfma_f32_16x16x32_bf16 v[4:7], v[158:161], v[210:213], v[4:7]
	v_mfma_f32_16x16x32_bf16 v[56:59], v[162:165], v[182:185], v[56:59]
	v_mfma_f32_16x16x32_bf16 v[48:51], v[170:173], v[182:185], v[48:51]
	v_mfma_f32_16x16x32_bf16 v[40:43], v[162:165], v[190:193], v[40:43]
	v_mfma_f32_16x16x32_bf16 v[32:35], v[170:173], v[190:193], v[32:35]
	v_mfma_f32_16x16x32_bf16 v[24:27], v[162:165], v[198:201], v[24:27]
	v_mfma_f32_16x16x32_bf16 v[16:19], v[170:173], v[198:201], v[16:19]
	v_mfma_f32_16x16x32_bf16 v[8:11], v[162:165], v[206:209], v[8:11]
	v_mfma_f32_16x16x32_bf16 v[0:3], v[170:173], v[206:209], v[0:3]
	v_mfma_f32_16x16x32_bf16 v[56:59], v[166:169], v[186:189], v[56:59]
	v_mfma_f32_16x16x32_bf16 v[48:51], v[174:177], v[186:189], v[48:51]
	v_mfma_f32_16x16x32_bf16 v[40:43], v[166:169], v[194:197], v[40:43]
	v_mfma_f32_16x16x32_bf16 v[32:35], v[174:177], v[194:197], v[32:35]
	v_mfma_f32_16x16x32_bf16 v[24:27], v[166:169], v[202:205], v[24:27]
	v_mfma_f32_16x16x32_bf16 v[16:19], v[174:177], v[202:205], v[16:19]
	v_mfma_f32_16x16x32_bf16 v[8:11], v[166:169], v[210:213], v[8:11]
	v_mfma_f32_16x16x32_bf16 v[0:3], v[174:177], v[210:213], v[0:3]
	s_setprio 0
	s_barrier
	s_add_i32 s4, s4, 2
	s_add_u32 s54, s54, 0x100
	s_addc_u32 s55, s55, 0
	s_cmp_ge_i32 s4, s57
	s_cbranch_scc0 .LBB0_878

.LBB0_951:
	s_mov_b64 s[6:7], s[36:37]
	ds_read_b128 v[136:139], v183
	ds_read_b128 v[140:143], v183 offset:1024
	ds_read_b128 v[144:147], v183 offset:2048
	ds_read_b128 v[148:151], v183 offset:3072
	ds_read_b128 v[152:155], v184
	ds_read_b128 v[156:159], v184 offset:1024
	ds_read_b128 v[160:163], v184 offset:2048
	ds_read_b128 v[164:167], v184 offset:3072
	s_add_u32 s5, s2, s6
	s_addc_u32 s8, s3, s7
	s_add_u32 s9, s5, 0x100
	s_addc_u32 s28, s8, 0
	s_add_u32 s6, s16, s6
	s_addc_u32 s7, s17, s7
	s_add_u32 s6, s6, 0x100
	s_addc_u32 s7, s7, 0
	s_cmp_eq_u32 s70, s4
	s_cselect_b32 s63, s59, s28
	s_cselect_b32 s62, s58, s9
	s_cselect_b32 s55, s61, s7
	s_cselect_b32 s54, s60, s6
	s_add_u32 s6, s5, 0x160080
	s_addc_u32 s7, s8, 0
	v_lshl_add_u64 v[176:177], s[6:7], 0, v[128:129]
	s_add_i32 m0, s31, 0xc000
	ds_read_b128 v[168:171], v185
	ds_read_b128 v[172:175], v185 offset:1024
	ds_read_b128 v[186:189], v185 offset:2048
	ds_read_b128 v[190:193], v185 offset:3072
	ds_read_b128 v[194:197], v185 offset:4096
	ds_read_b128 v[198:201], v185 offset:5120
	ds_read_b128 v[202:205], v185 offset:6144
	ds_read_b128 v[206:209], v185 offset:7168
	global_load_lds_dwordx4 v[176:177], off
	v_lshl_add_u64 v[176:177], s[6:7], 0, v[130:131]
	s_add_i32 m0, s31, 0xe000
	s_nop 0
	global_load_lds_dwordx4 v[176:177], off
	s_waitcnt vmcnt(8)
	s_waitcnt lgkmcnt(0)
	s_barrier
	s_setprio 1
	v_mfma_f32_16x16x32_bf16 v[124:127], v[136:139], v[168:171], v[124:127]
	v_mfma_f32_16x16x32_bf16 v[120:123], v[144:147], v[168:171], v[120:123]
	v_mfma_f32_16x16x32_bf16 v[116:119], v[136:139], v[186:189], v[116:119]
	v_mfma_f32_16x16x32_bf16 v[112:115], v[144:147], v[186:189], v[112:115]
	v_mfma_f32_16x16x32_bf16 v[104:107], v[136:139], v[194:197], v[104:107]
	v_mfma_f32_16x16x32_bf16 v[96:99], v[144:147], v[194:197], v[96:99]
	v_mfma_f32_16x16x32_bf16 v[88:91], v[136:139], v[202:205], v[88:91]
	v_mfma_f32_16x16x32_bf16 v[80:83], v[144:147], v[202:205], v[80:83]
	v_mfma_f32_16x16x32_bf16 v[124:127], v[140:143], v[172:175], v[124:127]
	v_mfma_f32_16x16x32_bf16 v[120:123], v[148:151], v[172:175], v[120:123]
	v_mfma_f32_16x16x32_bf16 v[116:119], v[140:143], v[190:193], v[116:119]
	v_mfma_f32_16x16x32_bf16 v[112:115], v[148:151], v[190:193], v[112:115]
	v_mfma_f32_16x16x32_bf16 v[104:107], v[140:143], v[198:201], v[104:107]
	v_mfma_f32_16x16x32_bf16 v[96:99], v[148:151], v[198:201], v[96:99]
	v_mfma_f32_16x16x32_bf16 v[88:91], v[140:143], v[206:209], v[88:91]
	v_mfma_f32_16x16x32_bf16 v[80:83], v[148:151], v[206:209], v[80:83]
	v_mfma_f32_16x16x32_bf16 v[108:111], v[152:155], v[168:171], v[108:111]
	v_mfma_f32_16x16x32_bf16 v[100:103], v[160:163], v[168:171], v[100:103]
	v_mfma_f32_16x16x32_bf16 v[92:95], v[152:155], v[186:189], v[92:95]
	v_mfma_f32_16x16x32_bf16 v[84:87], v[160:163], v[186:189], v[84:87]
	v_mfma_f32_16x16x32_bf16 v[76:79], v[152:155], v[194:197], v[76:79]
	v_mfma_f32_16x16x32_bf16 v[72:75], v[160:163], v[194:197], v[72:75]
	v_mfma_f32_16x16x32_bf16 v[68:71], v[152:155], v[202:205], v[68:71]
	v_mfma_f32_16x16x32_bf16 v[64:67], v[160:163], v[202:205], v[64:67]
	v_mfma_f32_16x16x32_bf16 v[108:111], v[156:159], v[172:175], v[108:111]
	v_mfma_f32_16x16x32_bf16 v[100:103], v[164:167], v[172:175], v[100:103]
	v_mfma_f32_16x16x32_bf16 v[92:95], v[156:159], v[190:193], v[92:95]
	v_mfma_f32_16x16x32_bf16 v[84:87], v[164:167], v[190:193], v[84:87]
	v_mfma_f32_16x16x32_bf16 v[76:79], v[156:159], v[198:201], v[76:79]
	v_mfma_f32_16x16x32_bf16 v[72:75], v[164:167], v[198:201], v[72:75]
	v_mfma_f32_16x16x32_bf16 v[68:71], v[156:159], v[206:209], v[68:71]
	v_mfma_f32_16x16x32_bf16 v[64:67], v[164:167], v[206:209], v[64:67]
	s_setprio 0
	s_barrier
	s_add_i32 s5, s71, s30
	v_lshl_add_u64 v[176:177], s[54:55], 0, v[128:129]
	s_mov_b32 m0, s5
	ds_read_b128 v[168:171], v185 offset:16384
	ds_read_b128 v[172:175], v185 offset:17408
	ds_read_b128 v[186:189], v185 offset:18432
	ds_read_b128 v[190:193], v185 offset:19456
	ds_read_b128 v[194:197], v185 offset:20480
	ds_read_b128 v[198:201], v185 offset:21504
	ds_read_b128 v[202:205], v185 offset:22528
	ds_read_b128 v[206:209], v185 offset:23552
	global_load_lds_dwordx4 v[176:177], off
	s_add_i32 m0, s5, 0x2000
	s_add_u32 s6, s54, 0x160000
	v_lshl_add_u64 v[210:211], s[54:55], 0, v[130:131]
	s_addc_u32 s7, s55, 0
	s_add_i32 s5, s72, s30
	global_load_lds_dwordx4 v[210:211], off
	v_lshl_add_u64 v[212:213], s[6:7], 0, v[128:129]
	s_mov_b32 m0, s5
	v_lshl_add_u64 v[214:215], s[62:63], 0, v[130:131]
	global_load_lds_dwordx4 v[212:213], off
	v_lshl_add_u64 v[212:213], s[6:7], 0, v[130:131]
	s_add_i32 m0, s5, 0x2000
	s_nop 0
	global_load_lds_dwordx4 v[212:213], off
	v_lshl_add_u64 v[212:213], s[62:63], 0, v[128:129]
	s_mov_b32 m0, s31
	s_nop 0
	global_load_lds_dwordx4 v[212:213], off
	s_mov_b32 m0, s56
	s_nop 0
	global_load_lds_dwordx4 v[214:215], off
	s_waitcnt vmcnt(8)
	s_waitcnt lgkmcnt(0)
	s_barrier
	s_setprio 1
	v_mfma_f32_16x16x32_bf16 v[60:63], v[136:139], v[168:171], v[60:63]
	v_mfma_f32_16x16x32_bf16 v[56:59], v[144:147], v[168:171], v[56:59]
	v_mfma_f32_16x16x32_bf16 v[52:55], v[136:139], v[186:189], v[52:55]
	v_mfma_f32_16x16x32_bf16 v[48:51], v[144:147], v[186:189], v[48:51]
	v_mfma_f32_16x16x32_bf16 v[40:43], v[136:139], v[194:197], v[40:43]
	v_mfma_f32_16x16x32_bf16 v[32:35], v[144:147], v[194:197], v[32:35]
	v_mfma_f32_16x16x32_bf16 v[24:27], v[136:139], v[202:205], v[24:27]
	v_mfma_f32_16x16x32_bf16 v[16:19], v[144:147], v[202:205], v[16:19]
	v_mfma_f32_16x16x32_bf16 v[60:63], v[140:143], v[172:175], v[60:63]
	v_mfma_f32_16x16x32_bf16 v[56:59], v[148:151], v[172:175], v[56:59]
	v_mfma_f32_16x16x32_bf16 v[52:55], v[140:143], v[190:193], v[52:55]
	v_mfma_f32_16x16x32_bf16 v[48:51], v[148:151], v[190:193], v[48:51]
	v_mfma_f32_16x16x32_bf16 v[40:43], v[140:143], v[198:201], v[40:43]
	v_mfma_f32_16x16x32_bf16 v[32:35], v[148:151], v[198:201], v[32:35]
	v_mfma_f32_16x16x32_bf16 v[24:27], v[140:143], v[206:209], v[24:27]
	v_mfma_f32_16x16x32_bf16 v[16:19], v[148:151], v[206:209], v[16:19]
	v_mfma_f32_16x16x32_bf16 v[44:47], v[152:155], v[168:171], v[44:47]
	v_mfma_f32_16x16x32_bf16 v[36:39], v[160:163], v[168:171], v[36:39]
	v_mfma_f32_16x16x32_bf16 v[28:31], v[152:155], v[186:189], v[28:31]
	v_mfma_f32_16x16x32_bf16 v[20:23], v[160:163], v[186:189], v[20:23]
	v_mfma_f32_16x16x32_bf16 v[12:15], v[152:155], v[194:197], v[12:15]
	v_mfma_f32_16x16x32_bf16 v[8:11], v[160:163], v[194:197], v[8:11]
	v_mfma_f32_16x16x32_bf16 v[4:7], v[152:155], v[202:205], v[4:7]
	v_mfma_f32_16x16x32_bf16 v[0:3], v[160:163], v[202:205], v[0:3]
	v_mfma_f32_16x16x32_bf16 v[44:47], v[156:159], v[172:175], v[44:47]
	v_mfma_f32_16x16x32_bf16 v[36:39], v[164:167], v[172:175], v[36:39]
	v_mfma_f32_16x16x32_bf16 v[28:31], v[156:159], v[190:193], v[28:31]
	v_mfma_f32_16x16x32_bf16 v[20:23], v[164:167], v[190:193], v[20:23]
	v_mfma_f32_16x16x32_bf16 v[12:15], v[156:159], v[198:201], v[12:15]
	v_mfma_f32_16x16x32_bf16 v[8:11], v[164:167], v[198:201], v[8:11]
	v_mfma_f32_16x16x32_bf16 v[4:7], v[156:159], v[206:209], v[4:7]
	v_mfma_f32_16x16x32_bf16 v[0:3], v[164:167], v[206:209], v[0:3]
	s_setprio 0
	s_barrier
	s_add_i32 s5, 0, 0x18000
	v_add_u32_e32 v132, s5, v182
	s_add_i32 s8, 0, 0x1c000
	ds_read_b128 v[136:139], v132
	ds_read_b128 v[140:143], v132 offset:1024
	ds_read_b128 v[144:147], v132 offset:2048
	ds_read_b128 v[148:151], v132 offset:3072
	v_add_u32_e32 v132, s8, v182
	ds_read_b128 v[152:155], v132
	ds_read_b128 v[156:159], v132 offset:1024
	ds_read_b128 v[160:163], v132 offset:2048
	ds_read_b128 v[164:167], v132 offset:3072
	s_add_u32 s6, s62, 0x160000
	s_addc_u32 s7, s63, 0
	s_mov_b32 m0, s57
	v_lshl_add_u64 v[216:217], s[6:7], 0, v[128:129]
	ds_read_b128 v[168:171], v185 offset:32768
	ds_read_b128 v[172:175], v185 offset:33792
	ds_read_b128 v[186:189], v185 offset:34816
	ds_read_b128 v[190:193], v185 offset:35840
	ds_read_b128 v[194:197], v185 offset:36864
	ds_read_b128 v[198:201], v185 offset:37888
	ds_read_b128 v[202:205], v185 offset:38912
	ds_read_b128 v[206:209], v185 offset:39936
	global_load_lds_dwordx4 v[216:217], off
	v_lshl_add_u64 v[216:217], s[6:7], 0, v[130:131]
	s_mov_b32 m0, s64
	s_nop 0
	global_load_lds_dwordx4 v[216:217], off
	s_waitcnt vmcnt(8)
	s_waitcnt lgkmcnt(0)
	s_barrier
	s_setprio 1
	v_mfma_f32_16x16x32_bf16 v[124:127], v[136:139], v[168:171], v[124:127]
	v_mfma_f32_16x16x32_bf16 v[120:123], v[144:147], v[168:171], v[120:123]
	v_mfma_f32_16x16x32_bf16 v[116:119], v[136:139], v[186:189], v[116:119]
	v_mfma_f32_16x16x32_bf16 v[112:115], v[144:147], v[186:189], v[112:115]
	v_mfma_f32_16x16x32_bf16 v[104:107], v[136:139], v[194:197], v[104:107]
	v_mfma_f32_16x16x32_bf16 v[96:99], v[144:147], v[194:197], v[96:99]
	v_mfma_f32_16x16x32_bf16 v[88:91], v[136:139], v[202:205], v[88:91]
	v_mfma_f32_16x16x32_bf16 v[80:83], v[144:147], v[202:205], v[80:83]
	v_mfma_f32_16x16x32_bf16 v[124:127], v[140:143], v[172:175], v[124:127]
	v_mfma_f32_16x16x32_bf16 v[120:123], v[148:151], v[172:175], v[120:123]
	v_mfma_f32_16x16x32_bf16 v[116:119], v[140:143], v[190:193], v[116:119]
	v_mfma_f32_16x16x32_bf16 v[112:115], v[148:151], v[190:193], v[112:115]
	v_mfma_f32_16x16x32_bf16 v[104:107], v[140:143], v[198:201], v[104:107]
	v_mfma_f32_16x16x32_bf16 v[96:99], v[148:151], v[198:201], v[96:99]
	v_mfma_f32_16x16x32_bf16 v[88:91], v[140:143], v[206:209], v[88:91]
	v_mfma_f32_16x16x32_bf16 v[80:83], v[148:151], v[206:209], v[80:83]
	v_mfma_f32_16x16x32_bf16 v[108:111], v[152:155], v[168:171], v[108:111]
	v_mfma_f32_16x16x32_bf16 v[100:103], v[160:163], v[168:171], v[100:103]
	v_mfma_f32_16x16x32_bf16 v[92:95], v[152:155], v[186:189], v[92:95]
	v_mfma_f32_16x16x32_bf16 v[84:87], v[160:163], v[186:189], v[84:87]
	v_mfma_f32_16x16x32_bf16 v[76:79], v[152:155], v[194:197], v[76:79]
	v_mfma_f32_16x16x32_bf16 v[72:75], v[160:163], v[194:197], v[72:75]
	v_mfma_f32_16x16x32_bf16 v[68:71], v[152:155], v[202:205], v[68:71]
	v_mfma_f32_16x16x32_bf16 v[64:67], v[160:163], v[202:205], v[64:67]
	v_mfma_f32_16x16x32_bf16 v[108:111], v[156:159], v[172:175], v[108:111]
	v_mfma_f32_16x16x32_bf16 v[100:103], v[164:167], v[172:175], v[100:103]
	v_mfma_f32_16x16x32_bf16 v[92:95], v[156:159], v[190:193], v[92:95]
	v_mfma_f32_16x16x32_bf16 v[84:87], v[164:167], v[190:193], v[84:87]
	v_mfma_f32_16x16x32_bf16 v[76:79], v[156:159], v[198:201], v[76:79]
	v_mfma_f32_16x16x32_bf16 v[72:75], v[164:167], v[198:201], v[72:75]
	v_mfma_f32_16x16x32_bf16 v[68:71], v[156:159], v[206:209], v[68:71]
	v_mfma_f32_16x16x32_bf16 v[64:67], v[164:167], v[206:209], v[64:67]
	s_setprio 0
	s_barrier
	s_add_i32 s5, s5, s30
	v_lshl_add_u64 v[176:177], v[176:177], 0, s[14:15]
	s_mov_b32 m0, s5
	ds_read_b128 v[168:171], v185 offset:49152
	ds_read_b128 v[172:175], v185 offset:50176
	ds_read_b128 v[186:189], v185 offset:51200
	ds_read_b128 v[190:193], v185 offset:52224
	ds_read_b128 v[194:197], v185 offset:53248
	ds_read_b128 v[198:201], v185 offset:54272
	ds_read_b128 v[202:205], v185 offset:55296
	ds_read_b128 v[206:209], v185 offset:56320
	global_load_lds_dwordx4 v[176:177], off
	s_add_i32 m0, s5, 0x2000
	s_add_u32 s6, s54, 0x160080
	v_lshl_add_u64 v[176:177], v[210:211], 0, s[14:15]
	s_addc_u32 s7, s55, 0
	s_add_i32 s5, s8, s30
	global_load_lds_dwordx4 v[176:177], off
	v_lshl_add_u64 v[176:177], s[6:7], 0, v[128:129]
	s_mov_b32 m0, s5
	s_nop 0
	global_load_lds_dwordx4 v[176:177], off
	v_lshl_add_u64 v[176:177], s[6:7], 0, v[130:131]
	s_add_i32 m0, s5, 0x2000
	s_nop 0
	global_load_lds_dwordx4 v[176:177], off
	v_lshl_add_u64 v[176:177], v[212:213], 0, s[14:15]
	s_mov_b32 m0, s68
	s_nop 0
	global_load_lds_dwordx4 v[176:177], off
	v_lshl_add_u64 v[176:177], v[214:215], 0, s[14:15]
	s_mov_b32 m0, s69
	s_nop 0
	global_load_lds_dwordx4 v[176:177], off
	s_waitcnt vmcnt(8)
	s_waitcnt lgkmcnt(0)
	s_barrier
	s_setprio 1
	v_mfma_f32_16x16x32_bf16 v[60:63], v[136:139], v[168:171], v[60:63]
	v_mfma_f32_16x16x32_bf16 v[56:59], v[144:147], v[168:171], v[56:59]
	v_mfma_f32_16x16x32_bf16 v[52:55], v[136:139], v[186:189], v[52:55]
	v_mfma_f32_16x16x32_bf16 v[48:51], v[144:147], v[186:189], v[48:51]
	v_mfma_f32_16x16x32_bf16 v[40:43], v[136:139], v[194:197], v[40:43]
	v_mfma_f32_16x16x32_bf16 v[32:35], v[144:147], v[194:197], v[32:35]
	v_mfma_f32_16x16x32_bf16 v[24:27], v[136:139], v[202:205], v[24:27]
	v_mfma_f32_16x16x32_bf16 v[16:19], v[144:147], v[202:205], v[16:19]
	v_mfma_f32_16x16x32_bf16 v[60:63], v[140:143], v[172:175], v[60:63]
	v_mfma_f32_16x16x32_bf16 v[56:59], v[148:151], v[172:175], v[56:59]
	v_mfma_f32_16x16x32_bf16 v[52:55], v[140:143], v[190:193], v[52:55]
	v_mfma_f32_16x16x32_bf16 v[48:51], v[148:151], v[190:193], v[48:51]
	v_mfma_f32_16x16x32_bf16 v[40:43], v[140:143], v[198:201], v[40:43]
	v_mfma_f32_16x16x32_bf16 v[32:35], v[148:151], v[198:201], v[32:35]
	v_mfma_f32_16x16x32_bf16 v[24:27], v[140:143], v[206:209], v[24:27]
	v_mfma_f32_16x16x32_bf16 v[16:19], v[148:151], v[206:209], v[16:19]
	v_mfma_f32_16x16x32_bf16 v[44:47], v[152:155], v[168:171], v[44:47]
	v_mfma_f32_16x16x32_bf16 v[36:39], v[160:163], v[168:171], v[36:39]
	v_mfma_f32_16x16x32_bf16 v[28:31], v[152:155], v[186:189], v[28:31]
	v_mfma_f32_16x16x32_bf16 v[20:23], v[160:163], v[186:189], v[20:23]
	v_mfma_f32_16x16x32_bf16 v[12:15], v[152:155], v[194:197], v[12:15]
	v_mfma_f32_16x16x32_bf16 v[8:11], v[160:163], v[194:197], v[8:11]
	v_mfma_f32_16x16x32_bf16 v[4:7], v[152:155], v[202:205], v[4:7]
	v_mfma_f32_16x16x32_bf16 v[0:3], v[160:163], v[202:205], v[0:3]
	v_mfma_f32_16x16x32_bf16 v[44:47], v[156:159], v[172:175], v[44:47]
	v_mfma_f32_16x16x32_bf16 v[36:39], v[164:167], v[172:175], v[36:39]
	v_mfma_f32_16x16x32_bf16 v[28:31], v[156:159], v[190:193], v[28:31]
	v_mfma_f32_16x16x32_bf16 v[20:23], v[164:167], v[190:193], v[20:23]
	v_mfma_f32_16x16x32_bf16 v[12:15], v[156:159], v[198:201], v[12:15]
	v_mfma_f32_16x16x32_bf16 v[8:11], v[164:167], v[198:201], v[8:11]
	v_mfma_f32_16x16x32_bf16 v[4:7], v[156:159], v[206:209], v[4:7]
	v_mfma_f32_16x16x32_bf16 v[0:3], v[164:167], v[206:209], v[0:3]
	s_setprio 0
	s_barrier
	s_add_i32 s4, s4, 2
	s_add_u32 s36, s36, 0x100
	s_addc_u32 s37, s37, 0
	s_cmp_ge_i32 s4, s65
	s_cbranch_scc0 .LBB0_951
	v_pk_add_f32 v[160:161], v[126:127], 0 op_sel_hi:[1,0]
	v_pk_add_f32 v[162:163], v[124:125], 0 op_sel_hi:[1,0]
	v_pk_add_f32 v[158:159], v[122:123], 0 op_sel_hi:[1,0]
	v_pk_add_f32 v[156:157], v[120:121], 0 op_sel_hi:[1,0]
	v_pk_add_f32 v[170:171], v[110:111], 0 op_sel_hi:[1,0]
	v_pk_add_f32 v[168:169], v[108:109], 0 op_sel_hi:[1,0]
	v_pk_add_f32 v[166:167], v[102:103], 0 op_sel_hi:[1,0]
	v_pk_add_f32 v[164:165], v[100:101], 0 op_sel_hi:[1,0]
	v_pk_add_f32 v[138:139], v[118:119], 0 op_sel_hi:[1,0]
	v_pk_add_f32 v[140:141], v[116:117], 0 op_sel_hi:[1,0]
	v_pk_add_f32 v[142:143], v[114:115], 0 op_sel_hi:[1,0]
	v_pk_add_f32 v[144:145], v[112:113], 0 op_sel_hi:[1,0]
	v_pk_add_f32 v[146:147], v[94:95], 0 op_sel_hi:[1,0]
	v_pk_add_f32 v[148:149], v[92:93], 0 op_sel_hi:[1,0]
	v_pk_add_f32 v[150:151], v[86:87], 0 op_sel_hi:[1,0]
	v_pk_add_f32 v[152:153], v[84:85], 0 op_sel_hi:[1,0]
	v_pk_add_f32 v[120:121], v[106:107], 0 op_sel_hi:[1,0]
	v_pk_add_f32 v[118:119], v[104:105], 0 op_sel_hi:[1,0]
	v_pk_add_f32 v[116:117], v[98:99], 0 op_sel_hi:[1,0]
	v_pk_add_f32 v[114:115], v[96:97], 0 op_sel_hi:[1,0]
	v_pk_add_f32 v[136:137], v[78:79], 0 op_sel_hi:[1,0]
	v_pk_add_f32 v[126:127], v[76:77], 0 op_sel_hi:[1,0]
	v_pk_add_f32 v[124:125], v[74:75], 0 op_sel_hi:[1,0]
	v_pk_add_f32 v[122:123], v[72:73], 0 op_sel_hi:[1,0]
	v_pk_add_f32 v[96:97], v[90:91], 0 op_sel_hi:[1,0]
	v_pk_add_f32 v[98:99], v[88:89], 0 op_sel_hi:[1,0]
	v_pk_add_f32 v[100:101], v[82:83], 0 op_sel_hi:[1,0]
	v_pk_add_f32 v[102:103], v[80:81], 0 op_sel_hi:[1,0]
	v_pk_add_f32 v[104:105], v[70:71], 0 op_sel_hi:[1,0]
	v_pk_add_f32 v[106:107], v[68:69], 0 op_sel_hi:[1,0]
	v_pk_add_f32 v[108:109], v[66:67], 0 op_sel_hi:[1,0]
	v_pk_add_f32 v[110:111], v[64:65], 0 op_sel_hi:[1,0]
	v_pk_add_f32 v[86:87], v[62:63], 0 op_sel_hi:[1,0]
	v_pk_add_f32 v[84:85], v[60:61], 0 op_sel_hi:[1,0]
	v_pk_add_f32 v[82:83], v[58:59], 0 op_sel_hi:[1,0]
	v_pk_add_f32 v[80:81], v[56:57], 0 op_sel_hi:[1,0]
	v_pk_add_f32 v[94:95], v[46:47], 0 op_sel_hi:[1,0]
	v_pk_add_f32 v[92:93], v[44:45], 0 op_sel_hi:[1,0]
	v_pk_add_f32 v[90:91], v[38:39], 0 op_sel_hi:[1,0]
	v_pk_add_f32 v[88:89], v[36:37], 0 op_sel_hi:[1,0]
	v_pk_add_f32 v[64:65], v[54:55], 0 op_sel_hi:[1,0]
	v_pk_add_f32 v[66:67], v[52:53], 0 op_sel_hi:[1,0]
	v_pk_add_f32 v[68:69], v[50:51], 0 op_sel_hi:[1,0]
	v_pk_add_f32 v[70:71], v[48:49], 0 op_sel_hi:[1,0]
	v_pk_add_f32 v[72:73], v[30:31], 0 op_sel_hi:[1,0]
	v_pk_add_f32 v[74:75], v[28:29], 0 op_sel_hi:[1,0]
	v_pk_add_f32 v[76:77], v[22:23], 0 op_sel_hi:[1,0]
	v_pk_add_f32 v[78:79], v[20:21], 0 op_sel_hi:[1,0]
	v_pk_add_f32 v[54:55], v[42:43], 0 op_sel_hi:[1,0]
	v_pk_add_f32 v[52:53], v[40:41], 0 op_sel_hi:[1,0]
	v_pk_add_f32 v[50:51], v[34:35], 0 op_sel_hi:[1,0]
	v_pk_add_f32 v[48:49], v[32:33], 0 op_sel_hi:[1,0]
	v_pk_add_f32 v[62:63], v[14:15], 0 op_sel_hi:[1,0]
	v_pk_add_f32 v[60:61], v[12:13], 0 op_sel_hi:[1,0]
	v_pk_add_f32 v[58:59], v[10:11], 0 op_sel_hi:[1,0]
	v_pk_add_f32 v[56:57], v[8:9], 0 op_sel_hi:[1,0]
	v_pk_add_f32 v[32:33], v[26:27], 0 op_sel_hi:[1,0]
	v_pk_add_f32 v[34:35], v[24:25], 0 op_sel_hi:[1,0]
	v_pk_add_f32 v[36:37], v[18:19], 0 op_sel_hi:[1,0]
	v_pk_add_f32 v[38:39], v[16:17], 0 op_sel_hi:[1,0]
	v_pk_add_f32 v[40:41], v[6:7], 0 op_sel_hi:[1,0]
	v_pk_add_f32 v[42:43], v[4:5], 0 op_sel_hi:[1,0]
	v_pk_add_f32 v[44:45], v[2:3], 0 op_sel_hi:[1,0]
	v_pk_add_f32 v[46:47], v[0:1], 0 op_sel_hi:[1,0]

.LBB0_983:
	s_mov_b64 s[34:35], s[16:17]
	ds_read_b128 v[140:143], v134
	ds_read_b128 v[144:147], v134 offset:1024
	ds_read_b128 v[148:151], v134 offset:2048
	ds_read_b128 v[152:155], v134 offset:3072
	ds_read_b128 v[156:159], v135
	ds_read_b128 v[160:163], v135 offset:1024
	ds_read_b128 v[164:167], v135 offset:2048
	ds_read_b128 v[168:171], v135 offset:3072
	s_add_u32 s40, s0, s34
	s_addc_u32 s41, s1, s35
	s_add_u32 s36, s40, 0x100
	s_addc_u32 s37, s41, 0
	s_add_u32 s34, s2, s34
	s_addc_u32 s35, s3, s35
	s_add_u32 s34, s34, 0x100
	s_addc_u32 s35, s35, 0
	s_cmp_eq_u32 s39, s52
	s_cselect_b32 s37, s13, s37
	s_cselect_b32 s36, s12, s36
	s_cselect_b32 s35, s15, s35
	s_cselect_b32 s34, s14, s34
	s_add_u32 s40, s40, 0x160080
	s_addc_u32 s41, s41, 0
	s_mov_b32 m0, s53
	v_lshl_add_u64 v[206:207], s[40:41], 0, v[128:129]
	ds_read_b128 v[172:175], v136
	ds_read_b128 v[176:179], v136 offset:1024
	ds_read_b128 v[182:185], v136 offset:2048
	ds_read_b128 v[186:189], v136 offset:3072
	ds_read_b128 v[190:193], v136 offset:4096
	ds_read_b128 v[194:197], v136 offset:5120
	ds_read_b128 v[198:201], v136 offset:6144
	ds_read_b128 v[202:205], v136 offset:7168
	global_load_lds_dwordx4 v[206:207], off
	v_lshl_add_u64 v[206:207], s[40:41], 0, v[130:131]
	s_mov_b32 m0, s54
	s_nop 0
	global_load_lds_dwordx4 v[206:207], off
	s_waitcnt vmcnt(8)
	s_waitcnt lgkmcnt(0)
	s_barrier
	s_setprio 1
	v_mfma_f32_16x16x32_bf16 v[124:127], v[140:143], v[172:175], v[124:127]
	v_mfma_f32_16x16x32_bf16 v[120:123], v[148:151], v[172:175], v[120:123]
	v_mfma_f32_16x16x32_bf16 v[108:111], v[140:143], v[182:185], v[108:111]
	v_mfma_f32_16x16x32_bf16 v[104:107], v[148:151], v[182:185], v[104:107]
	v_mfma_f32_16x16x32_bf16 v[92:95], v[140:143], v[190:193], v[92:95]
	v_mfma_f32_16x16x32_bf16 v[88:91], v[148:151], v[190:193], v[88:91]
	v_mfma_f32_16x16x32_bf16 v[76:79], v[140:143], v[198:201], v[76:79]
	v_mfma_f32_16x16x32_bf16 v[72:75], v[148:151], v[198:201], v[72:75]
	v_mfma_f32_16x16x32_bf16 v[124:127], v[144:147], v[176:179], v[124:127]
	v_mfma_f32_16x16x32_bf16 v[120:123], v[152:155], v[176:179], v[120:123]
	v_mfma_f32_16x16x32_bf16 v[108:111], v[144:147], v[186:189], v[108:111]
	v_mfma_f32_16x16x32_bf16 v[104:107], v[152:155], v[186:189], v[104:107]
	v_mfma_f32_16x16x32_bf16 v[92:95], v[144:147], v[194:197], v[92:95]
	v_mfma_f32_16x16x32_bf16 v[88:91], v[152:155], v[194:197], v[88:91]
	v_mfma_f32_16x16x32_bf16 v[76:79], v[144:147], v[202:205], v[76:79]
	v_mfma_f32_16x16x32_bf16 v[72:75], v[152:155], v[202:205], v[72:75]
	v_mfma_f32_16x16x32_bf16 v[116:119], v[156:159], v[172:175], v[116:119]
	v_mfma_f32_16x16x32_bf16 v[112:115], v[164:167], v[172:175], v[112:115]
	v_mfma_f32_16x16x32_bf16 v[100:103], v[156:159], v[182:185], v[100:103]
	v_mfma_f32_16x16x32_bf16 v[96:99], v[164:167], v[182:185], v[96:99]
	v_mfma_f32_16x16x32_bf16 v[84:87], v[156:159], v[190:193], v[84:87]
	v_mfma_f32_16x16x32_bf16 v[80:83], v[164:167], v[190:193], v[80:83]
	v_mfma_f32_16x16x32_bf16 v[68:71], v[156:159], v[198:201], v[68:71]
	v_mfma_f32_16x16x32_bf16 v[64:67], v[164:167], v[198:201], v[64:67]
	v_mfma_f32_16x16x32_bf16 v[116:119], v[160:163], v[176:179], v[116:119]
	v_mfma_f32_16x16x32_bf16 v[112:115], v[168:171], v[176:179], v[112:115]
	v_mfma_f32_16x16x32_bf16 v[100:103], v[160:163], v[186:189], v[100:103]
	v_mfma_f32_16x16x32_bf16 v[96:99], v[168:171], v[186:189], v[96:99]
	v_mfma_f32_16x16x32_bf16 v[84:87], v[160:163], v[194:197], v[84:87]
	v_mfma_f32_16x16x32_bf16 v[80:83], v[168:171], v[194:197], v[80:83]
	v_mfma_f32_16x16x32_bf16 v[68:71], v[160:163], v[202:205], v[68:71]
	v_mfma_f32_16x16x32_bf16 v[64:67], v[168:171], v[202:205], v[64:67]
	s_setprio 0
	s_barrier
	s_mov_b32 m0, s55
	v_lshl_add_u64 v[206:207], s[34:35], 0, v[128:129]
	s_add_u32 s40, s34, 0x160000
	ds_read_b128 v[172:175], v136 offset:16384
	ds_read_b128 v[176:179], v136 offset:17408
	ds_read_b128 v[182:185], v136 offset:18432
	ds_read_b128 v[186:189], v136 offset:19456
	ds_read_b128 v[190:193], v136 offset:20480
	ds_read_b128 v[194:197], v136 offset:21504
	ds_read_b128 v[198:201], v136 offset:22528
	ds_read_b128 v[202:205], v136 offset:23552
	global_load_lds_dwordx4 v[206:207], off
	v_lshl_add_u64 v[208:209], s[34:35], 0, v[130:131]
	s_mov_b32 m0, s56
	s_addc_u32 s41, s35, 0
	global_load_lds_dwordx4 v[208:209], off
	v_lshl_add_u64 v[210:211], s[40:41], 0, v[128:129]
	s_mov_b32 m0, s57
	v_lshl_add_u64 v[212:213], s[36:37], 0, v[130:131]
	global_load_lds_dwordx4 v[210:211], off
	v_lshl_add_u64 v[210:211], s[40:41], 0, v[130:131]
	s_mov_b32 m0, s58
	s_nop 0
	global_load_lds_dwordx4 v[210:211], off
	v_lshl_add_u64 v[210:211], s[36:37], 0, v[128:129]
	s_mov_b32 m0, s9
	s_nop 0
	global_load_lds_dwordx4 v[210:211], off
	s_mov_b32 m0, s23
	s_nop 0
	global_load_lds_dwordx4 v[212:213], off
	s_waitcnt vmcnt(8)
	s_waitcnt lgkmcnt(0)
	s_barrier
	s_setprio 1
	v_mfma_f32_16x16x32_bf16 v[60:63], v[140:143], v[172:175], v[60:63]
	v_mfma_f32_16x16x32_bf16 v[56:59], v[148:151], v[172:175], v[56:59]
	v_mfma_f32_16x16x32_bf16 v[44:47], v[140:143], v[182:185], v[44:47]
	v_mfma_f32_16x16x32_bf16 v[40:43], v[148:151], v[182:185], v[40:43]
	v_mfma_f32_16x16x32_bf16 v[28:31], v[140:143], v[190:193], v[28:31]
	v_mfma_f32_16x16x32_bf16 v[24:27], v[148:151], v[190:193], v[24:27]
	v_mfma_f32_16x16x32_bf16 v[12:15], v[140:143], v[198:201], v[12:15]
	v_mfma_f32_16x16x32_bf16 v[8:11], v[148:151], v[198:201], v[8:11]
	v_mfma_f32_16x16x32_bf16 v[60:63], v[144:147], v[176:179], v[60:63]
	v_mfma_f32_16x16x32_bf16 v[56:59], v[152:155], v[176:179], v[56:59]
	v_mfma_f32_16x16x32_bf16 v[44:47], v[144:147], v[186:189], v[44:47]
	v_mfma_f32_16x16x32_bf16 v[40:43], v[152:155], v[186:189], v[40:43]
	v_mfma_f32_16x16x32_bf16 v[28:31], v[144:147], v[194:197], v[28:31]
	v_mfma_f32_16x16x32_bf16 v[24:27], v[152:155], v[194:197], v[24:27]
	v_mfma_f32_16x16x32_bf16 v[12:15], v[144:147], v[202:205], v[12:15]
	v_mfma_f32_16x16x32_bf16 v[8:11], v[152:155], v[202:205], v[8:11]
	v_mfma_f32_16x16x32_bf16 v[52:55], v[156:159], v[172:175], v[52:55]
	v_mfma_f32_16x16x32_bf16 v[48:51], v[164:167], v[172:175], v[48:51]
	v_mfma_f32_16x16x32_bf16 v[36:39], v[156:159], v[182:185], v[36:39]
	v_mfma_f32_16x16x32_bf16 v[32:35], v[164:167], v[182:185], v[32:35]
	v_mfma_f32_16x16x32_bf16 v[20:23], v[156:159], v[190:193], v[20:23]
	v_mfma_f32_16x16x32_bf16 v[16:19], v[164:167], v[190:193], v[16:19]
	v_mfma_f32_16x16x32_bf16 v[4:7], v[156:159], v[198:201], v[4:7]
	v_mfma_f32_16x16x32_bf16 v[0:3], v[164:167], v[198:201], v[0:3]
	v_mfma_f32_16x16x32_bf16 v[52:55], v[160:163], v[176:179], v[52:55]
	v_mfma_f32_16x16x32_bf16 v[48:51], v[168:171], v[176:179], v[48:51]
	v_mfma_f32_16x16x32_bf16 v[36:39], v[160:163], v[186:189], v[36:39]
	v_mfma_f32_16x16x32_bf16 v[32:35], v[168:171], v[186:189], v[32:35]
	v_mfma_f32_16x16x32_bf16 v[20:23], v[160:163], v[194:197], v[20:23]
	v_mfma_f32_16x16x32_bf16 v[16:19], v[168:171], v[194:197], v[16:19]
	v_mfma_f32_16x16x32_bf16 v[4:7], v[160:163], v[202:205], v[4:7]
	v_mfma_f32_16x16x32_bf16 v[0:3], v[168:171], v[202:205], v[0:3]
	s_setprio 0
	s_barrier
	ds_read_b128 v[140:143], v137
	ds_read_b128 v[144:147], v137 offset:1024
	ds_read_b128 v[148:151], v137 offset:2048
	ds_read_b128 v[152:155], v137 offset:3072
	ds_read_b128 v[156:159], v138
	ds_read_b128 v[160:163], v138 offset:1024
	ds_read_b128 v[164:167], v138 offset:2048
	ds_read_b128 v[168:171], v138 offset:3072
	s_add_u32 s36, s36, 0x160000
	s_addc_u32 s37, s37, 0
	s_mov_b32 m0, s28
	v_lshl_add_u64 v[214:215], s[36:37], 0, v[128:129]
	ds_read_b128 v[172:175], v136 offset:32768
	ds_read_b128 v[176:179], v136 offset:33792
	ds_read_b128 v[182:185], v136 offset:34816
	ds_read_b128 v[186:189], v136 offset:35840
	ds_read_b128 v[190:193], v136 offset:36864
	ds_read_b128 v[194:197], v136 offset:37888
	ds_read_b128 v[198:201], v136 offset:38912
	ds_read_b128 v[202:205], v136 offset:39936
	global_load_lds_dwordx4 v[214:215], off
	v_lshl_add_u64 v[214:215], s[36:37], 0, v[130:131]
	s_mov_b32 m0, s29
	s_nop 0
	global_load_lds_dwordx4 v[214:215], off
	s_waitcnt vmcnt(8)
	s_waitcnt lgkmcnt(0)
	s_barrier
	s_setprio 1
	v_mfma_f32_16x16x32_bf16 v[124:127], v[140:143], v[172:175], v[124:127]
	v_mfma_f32_16x16x32_bf16 v[120:123], v[148:151], v[172:175], v[120:123]
	v_mfma_f32_16x16x32_bf16 v[108:111], v[140:143], v[182:185], v[108:111]
	v_mfma_f32_16x16x32_bf16 v[104:107], v[148:151], v[182:185], v[104:107]
	v_mfma_f32_16x16x32_bf16 v[92:95], v[140:143], v[190:193], v[92:95]
	v_mfma_f32_16x16x32_bf16 v[88:91], v[148:151], v[190:193], v[88:91]
	v_mfma_f32_16x16x32_bf16 v[76:79], v[140:143], v[198:201], v[76:79]
	v_mfma_f32_16x16x32_bf16 v[72:75], v[148:151], v[198:201], v[72:75]
	v_mfma_f32_16x16x32_bf16 v[124:127], v[144:147], v[176:179], v[124:127]
	v_mfma_f32_16x16x32_bf16 v[120:123], v[152:155], v[176:179], v[120:123]
	v_mfma_f32_16x16x32_bf16 v[108:111], v[144:147], v[186:189], v[108:111]
	v_mfma_f32_16x16x32_bf16 v[104:107], v[152:155], v[186:189], v[104:107]
	v_mfma_f32_16x16x32_bf16 v[92:95], v[144:147], v[194:197], v[92:95]
	v_mfma_f32_16x16x32_bf16 v[88:91], v[152:155], v[194:197], v[88:91]
	v_mfma_f32_16x16x32_bf16 v[76:79], v[144:147], v[202:205], v[76:79]
	v_mfma_f32_16x16x32_bf16 v[72:75], v[152:155], v[202:205], v[72:75]
	v_mfma_f32_16x16x32_bf16 v[116:119], v[156:159], v[172:175], v[116:119]
	v_mfma_f32_16x16x32_bf16 v[112:115], v[164:167], v[172:175], v[112:115]
	v_mfma_f32_16x16x32_bf16 v[100:103], v[156:159], v[182:185], v[100:103]
	v_mfma_f32_16x16x32_bf16 v[96:99], v[164:167], v[182:185], v[96:99]
	v_mfma_f32_16x16x32_bf16 v[84:87], v[156:159], v[190:193], v[84:87]
	v_mfma_f32_16x16x32_bf16 v[80:83], v[164:167], v[190:193], v[80:83]
	v_mfma_f32_16x16x32_bf16 v[68:71], v[156:159], v[198:201], v[68:71]
	v_mfma_f32_16x16x32_bf16 v[64:67], v[164:167], v[198:201], v[64:67]
	v_mfma_f32_16x16x32_bf16 v[116:119], v[160:163], v[176:179], v[116:119]
	v_mfma_f32_16x16x32_bf16 v[112:115], v[168:171], v[176:179], v[112:115]
	v_mfma_f32_16x16x32_bf16 v[100:103], v[160:163], v[186:189], v[100:103]
	v_mfma_f32_16x16x32_bf16 v[96:99], v[168:171], v[186:189], v[96:99]
	v_mfma_f32_16x16x32_bf16 v[84:87], v[160:163], v[194:197], v[84:87]
	v_mfma_f32_16x16x32_bf16 v[80:83], v[168:171], v[194:197], v[80:83]
	v_mfma_f32_16x16x32_bf16 v[68:71], v[160:163], v[202:205], v[68:71]
	v_mfma_f32_16x16x32_bf16 v[64:67], v[168:171], v[202:205], v[64:67]
	s_setprio 0
	s_barrier
	s_mov_b32 m0, s59
	v_lshl_add_u64 v[206:207], v[206:207], 0, s[10:11]
	s_add_u32 s34, s34, 0x160080
	ds_read_b128 v[172:175], v136 offset:49152
	ds_read_b128 v[176:179], v136 offset:50176
	ds_read_b128 v[182:185], v136 offset:51200
	ds_read_b128 v[186:189], v136 offset:52224
	ds_read_b128 v[190:193], v136 offset:53248
	ds_read_b128 v[194:197], v136 offset:54272
	ds_read_b128 v[198:201], v136 offset:55296
	ds_read_b128 v[202:205], v136 offset:56320
	global_load_lds_dwordx4 v[206:207], off
	v_lshl_add_u64 v[206:207], v[208:209], 0, s[10:11]
	s_mov_b32 m0, s60
	s_addc_u32 s35, s35, 0
	global_load_lds_dwordx4 v[206:207], off
	v_lshl_add_u64 v[206:207], s[34:35], 0, v[128:129]
	s_mov_b32 m0, s61
	s_nop 0
	global_load_lds_dwordx4 v[206:207], off
	v_lshl_add_u64 v[206:207], s[34:35], 0, v[130:131]
	s_mov_b32 m0, s62
	s_nop 0
	global_load_lds_dwordx4 v[206:207], off
	v_lshl_add_u64 v[206:207], v[210:211], 0, s[10:11]
	s_mov_b32 m0, s30
	s_nop 0
	global_load_lds_dwordx4 v[206:207], off
	v_lshl_add_u64 v[206:207], v[212:213], 0, s[10:11]
	s_mov_b32 m0, s31
	s_nop 0
	global_load_lds_dwordx4 v[206:207], off
	s_waitcnt vmcnt(8)
	s_waitcnt lgkmcnt(0)
	s_barrier
	s_setprio 1
	v_mfma_f32_16x16x32_bf16 v[60:63], v[140:143], v[172:175], v[60:63]
	v_mfma_f32_16x16x32_bf16 v[56:59], v[148:151], v[172:175], v[56:59]
	v_mfma_f32_16x16x32_bf16 v[44:47], v[140:143], v[182:185], v[44:47]
	v_mfma_f32_16x16x32_bf16 v[40:43], v[148:151], v[182:185], v[40:43]
	v_mfma_f32_16x16x32_bf16 v[28:31], v[140:143], v[190:193], v[28:31]
	v_mfma_f32_16x16x32_bf16 v[24:27], v[148:151], v[190:193], v[24:27]
	v_mfma_f32_16x16x32_bf16 v[12:15], v[140:143], v[198:201], v[12:15]
	v_mfma_f32_16x16x32_bf16 v[8:11], v[148:151], v[198:201], v[8:11]
	v_mfma_f32_16x16x32_bf16 v[60:63], v[144:147], v[176:179], v[60:63]
	v_mfma_f32_16x16x32_bf16 v[56:59], v[152:155], v[176:179], v[56:59]
	v_mfma_f32_16x16x32_bf16 v[44:47], v[144:147], v[186:189], v[44:47]
	v_mfma_f32_16x16x32_bf16 v[40:43], v[152:155], v[186:189], v[40:43]
	v_mfma_f32_16x16x32_bf16 v[28:31], v[144:147], v[194:197], v[28:31]
	v_mfma_f32_16x16x32_bf16 v[24:27], v[152:155], v[194:197], v[24:27]
	v_mfma_f32_16x16x32_bf16 v[12:15], v[144:147], v[202:205], v[12:15]
	v_mfma_f32_16x16x32_bf16 v[8:11], v[152:155], v[202:205], v[8:11]
	v_mfma_f32_16x16x32_bf16 v[52:55], v[156:159], v[172:175], v[52:55]
	v_mfma_f32_16x16x32_bf16 v[48:51], v[164:167], v[172:175], v[48:51]
	v_mfma_f32_16x16x32_bf16 v[36:39], v[156:159], v[182:185], v[36:39]
	v_mfma_f32_16x16x32_bf16 v[32:35], v[164:167], v[182:185], v[32:35]
	v_mfma_f32_16x16x32_bf16 v[20:23], v[156:159], v[190:193], v[20:23]
	v_mfma_f32_16x16x32_bf16 v[16:19], v[164:167], v[190:193], v[16:19]
	v_mfma_f32_16x16x32_bf16 v[4:7], v[156:159], v[198:201], v[4:7]
	v_mfma_f32_16x16x32_bf16 v[0:3], v[164:167], v[198:201], v[0:3]
	v_mfma_f32_16x16x32_bf16 v[52:55], v[160:163], v[176:179], v[52:55]
	v_mfma_f32_16x16x32_bf16 v[48:51], v[168:171], v[176:179], v[48:51]
	v_mfma_f32_16x16x32_bf16 v[36:39], v[160:163], v[186:189], v[36:39]
	v_mfma_f32_16x16x32_bf16 v[32:35], v[168:171], v[186:189], v[32:35]
	v_mfma_f32_16x16x32_bf16 v[20:23], v[160:163], v[194:197], v[20:23]
	v_mfma_f32_16x16x32_bf16 v[16:19], v[168:171], v[194:197], v[16:19]
	v_mfma_f32_16x16x32_bf16 v[4:7], v[160:163], v[202:205], v[4:7]
	v_mfma_f32_16x16x32_bf16 v[0:3], v[168:171], v[202:205], v[0:3]
	s_setprio 0
	s_barrier
	s_add_i32 s52, s52, 2
	s_add_u32 s16, s16, 0x100
	s_addc_u32 s17, s17, 0
	s_cmp_ge_i32 s52, s38
	s_cbranch_scc0 .LBB0_983
	v_mov_b32_e32 v129, v127

.LBB0_1193:
	s_mov_b64 s[6:7], s[14:15]
	ds_read_b128 v[128:131], v191
	ds_read_b128 v[132:135], v191 offset:1024
	ds_read_b128 v[136:139], v191 offset:2048
	ds_read_b128 v[140:143], v191 offset:3072
	ds_read_b128 v[144:147], v192
	ds_read_b128 v[148:151], v192 offset:1024
	ds_read_b128 v[168:171], v192 offset:2048
	ds_read_b128 v[172:175], v192 offset:3072
	s_add_u32 s5, s2, s6
	s_addc_u32 s8, s3, s7
	s_add_u32 s9, s5, 0x100
	s_addc_u32 s16, s8, 0
	s_add_u32 s6, s12, s6
	s_addc_u32 s7, s13, s7
	s_add_u32 s6, s6, 0x100
	s_addc_u32 s7, s7, 0
	s_cmp_eq_u32 s93, s4
	s_cselect_b32 s37, s81, s16
	s_cselect_b32 s36, s80, s9
	s_cselect_b32 s17, s83, s7
	s_cselect_b32 s16, s82, s6
	s_add_u32 s6, s5, 0x80080
	s_addc_u32 s7, s8, 0
	v_lshl_add_u64 v[186:187], s[6:7], 0, v[152:153]
	s_add_i32 m0, s19, 0xc000
	ds_read_b128 v[176:179], v193
	ds_read_b128 v[182:185], v193 offset:1024
	ds_read_b128 v[196:199], v193 offset:2048
	ds_read_b128 v[200:203], v193 offset:3072
	ds_read_b128 v[204:207], v193 offset:4096
	ds_read_b128 v[208:211], v193 offset:5120
	ds_read_b128 v[212:215], v193 offset:6144
	ds_read_b128 v[216:219], v193 offset:7168
	global_load_lds_dwordx4 v[186:187], off
	v_lshl_add_u64 v[186:187], s[6:7], 0, v[156:157]
	s_add_i32 m0, s19, 0xe000
	s_nop 0
	global_load_lds_dwordx4 v[186:187], off
	s_waitcnt vmcnt(8)
	s_waitcnt lgkmcnt(0)
	s_barrier
	s_setprio 1
	v_mfma_f32_16x16x32_bf16 v[120:123], v[128:131], v[176:179], v[120:123]
	v_mfma_f32_16x16x32_bf16 v[124:127], v[136:139], v[176:179], v[124:127]
	v_mfma_f32_16x16x32_bf16 v[108:111], v[128:131], v[196:199], v[108:111]
	v_mfma_f32_16x16x32_bf16 v[104:107], v[136:139], v[196:199], v[104:107]
	v_mfma_f32_16x16x32_bf16 v[92:95], v[128:131], v[204:207], v[92:95]
	v_mfma_f32_16x16x32_bf16 v[88:91], v[136:139], v[204:207], v[88:91]
	v_mfma_f32_16x16x32_bf16 v[76:79], v[128:131], v[212:215], v[76:79]
	v_mfma_f32_16x16x32_bf16 v[72:75], v[136:139], v[212:215], v[72:75]
	v_mfma_f32_16x16x32_bf16 v[120:123], v[132:135], v[182:185], v[120:123]
	v_mfma_f32_16x16x32_bf16 v[124:127], v[140:143], v[182:185], v[124:127]
	v_mfma_f32_16x16x32_bf16 v[108:111], v[132:135], v[200:203], v[108:111]
	v_mfma_f32_16x16x32_bf16 v[104:107], v[140:143], v[200:203], v[104:107]
	v_mfma_f32_16x16x32_bf16 v[92:95], v[132:135], v[208:211], v[92:95]
	v_mfma_f32_16x16x32_bf16 v[88:91], v[140:143], v[208:211], v[88:91]
	v_mfma_f32_16x16x32_bf16 v[76:79], v[132:135], v[216:219], v[76:79]
	v_mfma_f32_16x16x32_bf16 v[72:75], v[140:143], v[216:219], v[72:75]
	v_mfma_f32_16x16x32_bf16 v[116:119], v[144:147], v[176:179], v[116:119]
	v_mfma_f32_16x16x32_bf16 v[112:115], v[168:171], v[176:179], v[112:115]
	v_mfma_f32_16x16x32_bf16 v[100:103], v[144:147], v[196:199], v[100:103]
	v_mfma_f32_16x16x32_bf16 v[96:99], v[168:171], v[196:199], v[96:99]
	v_mfma_f32_16x16x32_bf16 v[84:87], v[144:147], v[204:207], v[84:87]
	v_mfma_f32_16x16x32_bf16 v[80:83], v[168:171], v[204:207], v[80:83]
	v_mfma_f32_16x16x32_bf16 v[68:71], v[144:147], v[212:215], v[68:71]
	v_mfma_f32_16x16x32_bf16 v[64:67], v[168:171], v[212:215], v[64:67]
	v_mfma_f32_16x16x32_bf16 v[116:119], v[148:151], v[182:185], v[116:119]
	v_mfma_f32_16x16x32_bf16 v[112:115], v[172:175], v[182:185], v[112:115]
	v_mfma_f32_16x16x32_bf16 v[100:103], v[148:151], v[200:203], v[100:103]
	v_mfma_f32_16x16x32_bf16 v[96:99], v[172:175], v[200:203], v[96:99]
	v_mfma_f32_16x16x32_bf16 v[84:87], v[148:151], v[208:211], v[84:87]
	v_mfma_f32_16x16x32_bf16 v[80:83], v[172:175], v[208:211], v[80:83]
	v_mfma_f32_16x16x32_bf16 v[68:71], v[148:151], v[216:219], v[68:71]
	v_mfma_f32_16x16x32_bf16 v[64:67], v[172:175], v[216:219], v[64:67]
	s_setprio 0
	s_barrier
	s_add_i32 s5, s95, s18
	v_lshl_add_u64 v[186:187], s[16:17], 0, v[154:155]
	s_mov_b32 m0, s5
	ds_read_b128 v[176:179], v193 offset:16384
	ds_read_b128 v[182:185], v193 offset:17408
	ds_read_b128 v[196:199], v193 offset:18432
	ds_read_b128 v[200:203], v193 offset:19456
	ds_read_b128 v[204:207], v193 offset:20480
	ds_read_b128 v[208:211], v193 offset:21504
	ds_read_b128 v[212:215], v193 offset:22528
	ds_read_b128 v[216:219], v193 offset:23552
	global_load_lds_dwordx4 v[186:187], off
	s_add_i32 m0, s5, 0x2000
	s_add_u32 s6, s16, 0x80000
	v_lshl_add_u64 v[220:221], s[16:17], 0, v[158:159]
	s_addc_u32 s7, s17, 0
	s_add_i32 s5, s96, s18
	global_load_lds_dwordx4 v[220:221], off
	v_lshl_add_u64 v[222:223], s[6:7], 0, v[154:155]
	s_mov_b32 m0, s5
	v_lshl_add_u64 v[224:225], s[36:37], 0, v[156:157]
	global_load_lds_dwordx4 v[222:223], off
	v_lshl_add_u64 v[222:223], s[6:7], 0, v[158:159]
	s_add_i32 m0, s5, 0x2000
	s_nop 0
	global_load_lds_dwordx4 v[222:223], off
	v_lshl_add_u64 v[222:223], s[36:37], 0, v[152:153]
	s_mov_b32 m0, s19
	s_nop 0
	global_load_lds_dwordx4 v[222:223], off
	s_mov_b32 m0, s23
	s_nop 0
	global_load_lds_dwordx4 v[224:225], off
	s_waitcnt vmcnt(8)
	s_waitcnt lgkmcnt(0)
	s_barrier
	s_setprio 1
	v_mfma_f32_16x16x32_bf16 v[60:63], v[128:131], v[176:179], v[60:63]
	v_mfma_f32_16x16x32_bf16 v[56:59], v[136:139], v[176:179], v[56:59]
	v_mfma_f32_16x16x32_bf16 v[44:47], v[128:131], v[196:199], v[44:47]
	v_mfma_f32_16x16x32_bf16 v[40:43], v[136:139], v[196:199], v[40:43]
	v_mfma_f32_16x16x32_bf16 v[28:31], v[128:131], v[204:207], v[28:31]
	v_mfma_f32_16x16x32_bf16 v[24:27], v[136:139], v[204:207], v[24:27]
	v_mfma_f32_16x16x32_bf16 v[12:15], v[128:131], v[212:215], v[12:15]
	v_mfma_f32_16x16x32_bf16 v[8:11], v[136:139], v[212:215], v[8:11]
	v_mfma_f32_16x16x32_bf16 v[60:63], v[132:135], v[182:185], v[60:63]
	v_mfma_f32_16x16x32_bf16 v[56:59], v[140:143], v[182:185], v[56:59]
	v_mfma_f32_16x16x32_bf16 v[44:47], v[132:135], v[200:203], v[44:47]
	v_mfma_f32_16x16x32_bf16 v[40:43], v[140:143], v[200:203], v[40:43]
	v_mfma_f32_16x16x32_bf16 v[28:31], v[132:135], v[208:211], v[28:31]
	v_mfma_f32_16x16x32_bf16 v[24:27], v[140:143], v[208:211], v[24:27]
	v_mfma_f32_16x16x32_bf16 v[12:15], v[132:135], v[216:219], v[12:15]
	v_mfma_f32_16x16x32_bf16 v[8:11], v[140:143], v[216:219], v[8:11]
	v_mfma_f32_16x16x32_bf16 v[52:55], v[144:147], v[176:179], v[52:55]
	v_mfma_f32_16x16x32_bf16 v[48:51], v[168:171], v[176:179], v[48:51]
	v_mfma_f32_16x16x32_bf16 v[36:39], v[144:147], v[196:199], v[36:39]
	v_mfma_f32_16x16x32_bf16 v[32:35], v[168:171], v[196:199], v[32:35]
	v_mfma_f32_16x16x32_bf16 v[20:23], v[144:147], v[204:207], v[20:23]
	v_mfma_f32_16x16x32_bf16 v[16:19], v[168:171], v[204:207], v[16:19]
	v_mfma_f32_16x16x32_bf16 v[4:7], v[144:147], v[212:215], v[4:7]
	v_mfma_f32_16x16x32_bf16 v[0:3], v[168:171], v[212:215], v[0:3]
	v_mfma_f32_16x16x32_bf16 v[52:55], v[148:151], v[182:185], v[52:55]
	v_mfma_f32_16x16x32_bf16 v[48:51], v[172:175], v[182:185], v[48:51]
	v_mfma_f32_16x16x32_bf16 v[36:39], v[148:151], v[200:203], v[36:39]
	v_mfma_f32_16x16x32_bf16 v[32:35], v[172:175], v[200:203], v[32:35]
	v_mfma_f32_16x16x32_bf16 v[20:23], v[148:151], v[208:211], v[20:23]
	v_mfma_f32_16x16x32_bf16 v[16:19], v[172:175], v[208:211], v[16:19]
	v_mfma_f32_16x16x32_bf16 v[4:7], v[148:151], v[216:219], v[4:7]
	v_mfma_f32_16x16x32_bf16 v[0:3], v[172:175], v[216:219], v[0:3]
	s_setprio 0
	s_barrier
	s_add_i32 s5, 0, 0x18000
	s_add_i32 s8, 0, 0x1c000
	v_add_u32_e32 v140, s5, v190
	v_add_u32_e32 v160, s8, v190
	ds_read_b128 v[128:131], v140
	ds_read_b128 v[132:135], v140 offset:1024
	ds_read_b128 v[136:139], v140 offset:2048
	ds_read_b128 v[140:143], v140 offset:3072
	ds_read_b128 v[144:147], v160
	ds_read_b128 v[148:151], v160 offset:1024
	ds_read_b128 v[168:171], v160 offset:2048
	ds_read_b128 v[172:175], v160 offset:3072
	s_add_u32 s6, s36, 0x80000
	s_addc_u32 s7, s37, 0
	s_mov_b32 m0, s54
	v_lshl_add_u64 v[226:227], s[6:7], 0, v[152:153]
	ds_read_b128 v[176:179], v193 offset:32768
	ds_read_b128 v[182:185], v193 offset:33792
	ds_read_b128 v[196:199], v193 offset:34816
	ds_read_b128 v[200:203], v193 offset:35840
	ds_read_b128 v[204:207], v193 offset:36864
	ds_read_b128 v[208:211], v193 offset:37888
	ds_read_b128 v[212:215], v193 offset:38912
	ds_read_b128 v[216:219], v193 offset:39936
	global_load_lds_dwordx4 v[226:227], off
	v_lshl_add_u64 v[226:227], s[6:7], 0, v[156:157]
	s_mov_b32 m0, s55
	s_nop 0
	global_load_lds_dwordx4 v[226:227], off
	s_waitcnt vmcnt(8)
	s_waitcnt lgkmcnt(0)
	s_barrier
	s_setprio 1
	v_mfma_f32_16x16x32_bf16 v[120:123], v[128:131], v[176:179], v[120:123]
	v_mfma_f32_16x16x32_bf16 v[124:127], v[136:139], v[176:179], v[124:127]
	v_mfma_f32_16x16x32_bf16 v[108:111], v[128:131], v[196:199], v[108:111]
	v_mfma_f32_16x16x32_bf16 v[104:107], v[136:139], v[196:199], v[104:107]
	v_mfma_f32_16x16x32_bf16 v[92:95], v[128:131], v[204:207], v[92:95]
	v_mfma_f32_16x16x32_bf16 v[88:91], v[136:139], v[204:207], v[88:91]
	v_mfma_f32_16x16x32_bf16 v[76:79], v[128:131], v[212:215], v[76:79]
	v_mfma_f32_16x16x32_bf16 v[72:75], v[136:139], v[212:215], v[72:75]
	v_mfma_f32_16x16x32_bf16 v[120:123], v[132:135], v[182:185], v[120:123]
	v_mfma_f32_16x16x32_bf16 v[124:127], v[140:143], v[182:185], v[124:127]
	v_mfma_f32_16x16x32_bf16 v[108:111], v[132:135], v[200:203], v[108:111]
	v_mfma_f32_16x16x32_bf16 v[104:107], v[140:143], v[200:203], v[104:107]
	v_mfma_f32_16x16x32_bf16 v[92:95], v[132:135], v[208:211], v[92:95]
	v_mfma_f32_16x16x32_bf16 v[88:91], v[140:143], v[208:211], v[88:91]
	v_mfma_f32_16x16x32_bf16 v[76:79], v[132:135], v[216:219], v[76:79]
	v_mfma_f32_16x16x32_bf16 v[72:75], v[140:143], v[216:219], v[72:75]
	v_mfma_f32_16x16x32_bf16 v[116:119], v[144:147], v[176:179], v[116:119]
	v_mfma_f32_16x16x32_bf16 v[112:115], v[168:171], v[176:179], v[112:115]
	v_mfma_f32_16x16x32_bf16 v[100:103], v[144:147], v[196:199], v[100:103]
	v_mfma_f32_16x16x32_bf16 v[96:99], v[168:171], v[196:199], v[96:99]
	v_mfma_f32_16x16x32_bf16 v[84:87], v[144:147], v[204:207], v[84:87]
	v_mfma_f32_16x16x32_bf16 v[80:83], v[168:171], v[204:207], v[80:83]
	v_mfma_f32_16x16x32_bf16 v[68:71], v[144:147], v[212:215], v[68:71]
	v_mfma_f32_16x16x32_bf16 v[64:67], v[168:171], v[212:215], v[64:67]
	v_mfma_f32_16x16x32_bf16 v[116:119], v[148:151], v[182:185], v[116:119]
	v_mfma_f32_16x16x32_bf16 v[112:115], v[172:175], v[182:185], v[112:115]
	v_mfma_f32_16x16x32_bf16 v[100:103], v[148:151], v[200:203], v[100:103]
	v_mfma_f32_16x16x32_bf16 v[96:99], v[172:175], v[200:203], v[96:99]
	v_mfma_f32_16x16x32_bf16 v[84:87], v[148:151], v[208:211], v[84:87]
	v_mfma_f32_16x16x32_bf16 v[80:83], v[172:175], v[208:211], v[80:83]
	v_mfma_f32_16x16x32_bf16 v[68:71], v[148:151], v[216:219], v[68:71]
	v_mfma_f32_16x16x32_bf16 v[64:67], v[172:175], v[216:219], v[64:67]
	s_setprio 0
	s_barrier
	s_add_i32 s5, s5, s18
	v_lshl_add_u64 v[186:187], v[186:187], 0, s[64:65]
	s_mov_b32 m0, s5
	ds_read_b128 v[176:179], v193 offset:49152
	ds_read_b128 v[182:185], v193 offset:50176
	ds_read_b128 v[196:199], v193 offset:51200
	ds_read_b128 v[200:203], v193 offset:52224
	ds_read_b128 v[204:207], v193 offset:53248
	ds_read_b128 v[208:211], v193 offset:54272
	ds_read_b128 v[212:215], v193 offset:55296
	ds_read_b128 v[216:219], v193 offset:56320
	global_load_lds_dwordx4 v[186:187], off
	s_add_i32 m0, s5, 0x2000
	s_add_u32 s6, s16, 0x80080
	v_lshl_add_u64 v[186:187], v[220:221], 0, s[64:65]
	s_addc_u32 s7, s17, 0
	s_add_i32 s5, s8, s18
	global_load_lds_dwordx4 v[186:187], off
	v_lshl_add_u64 v[186:187], s[6:7], 0, v[154:155]
	s_mov_b32 m0, s5
	s_nop 0
	global_load_lds_dwordx4 v[186:187], off
	v_lshl_add_u64 v[186:187], s[6:7], 0, v[158:159]
	s_add_i32 m0, s5, 0x2000
	s_nop 0
	global_load_lds_dwordx4 v[186:187], off
	v_lshl_add_u64 v[186:187], v[222:223], 0, s[64:65]
	s_mov_b32 m0, s90
	s_nop 0
	global_load_lds_dwordx4 v[186:187], off
	v_lshl_add_u64 v[186:187], v[224:225], 0, s[64:65]
	s_mov_b32 m0, s91
	s_nop 0
	global_load_lds_dwordx4 v[186:187], off
	s_waitcnt vmcnt(8)
	s_waitcnt lgkmcnt(0)
	s_barrier
	s_setprio 1
	v_mfma_f32_16x16x32_bf16 v[60:63], v[128:131], v[176:179], v[60:63]
	v_mfma_f32_16x16x32_bf16 v[56:59], v[136:139], v[176:179], v[56:59]
	v_mfma_f32_16x16x32_bf16 v[44:47], v[128:131], v[196:199], v[44:47]
	v_mfma_f32_16x16x32_bf16 v[40:43], v[136:139], v[196:199], v[40:43]
	v_mfma_f32_16x16x32_bf16 v[28:31], v[128:131], v[204:207], v[28:31]
	v_mfma_f32_16x16x32_bf16 v[24:27], v[136:139], v[204:207], v[24:27]
	v_mfma_f32_16x16x32_bf16 v[12:15], v[128:131], v[212:215], v[12:15]
	v_mfma_f32_16x16x32_bf16 v[8:11], v[136:139], v[212:215], v[8:11]
	v_mfma_f32_16x16x32_bf16 v[60:63], v[132:135], v[182:185], v[60:63]
	v_mfma_f32_16x16x32_bf16 v[56:59], v[140:143], v[182:185], v[56:59]
	v_mfma_f32_16x16x32_bf16 v[44:47], v[132:135], v[200:203], v[44:47]
	v_mfma_f32_16x16x32_bf16 v[40:43], v[140:143], v[200:203], v[40:43]
	v_mfma_f32_16x16x32_bf16 v[28:31], v[132:135], v[208:211], v[28:31]
	v_mfma_f32_16x16x32_bf16 v[24:27], v[140:143], v[208:211], v[24:27]
	v_mfma_f32_16x16x32_bf16 v[12:15], v[132:135], v[216:219], v[12:15]
	v_mfma_f32_16x16x32_bf16 v[8:11], v[140:143], v[216:219], v[8:11]
	v_mfma_f32_16x16x32_bf16 v[52:55], v[144:147], v[176:179], v[52:55]
	v_mfma_f32_16x16x32_bf16 v[48:51], v[168:171], v[176:179], v[48:51]
	v_mfma_f32_16x16x32_bf16 v[36:39], v[144:147], v[196:199], v[36:39]
	v_mfma_f32_16x16x32_bf16 v[32:35], v[168:171], v[196:199], v[32:35]
	v_mfma_f32_16x16x32_bf16 v[20:23], v[144:147], v[204:207], v[20:23]
	v_mfma_f32_16x16x32_bf16 v[16:19], v[168:171], v[204:207], v[16:19]
	v_mfma_f32_16x16x32_bf16 v[4:7], v[144:147], v[212:215], v[4:7]
	v_mfma_f32_16x16x32_bf16 v[0:3], v[168:171], v[212:215], v[0:3]
	v_mfma_f32_16x16x32_bf16 v[52:55], v[148:151], v[182:185], v[52:55]
	v_mfma_f32_16x16x32_bf16 v[48:51], v[172:175], v[182:185], v[48:51]
	v_mfma_f32_16x16x32_bf16 v[36:39], v[148:151], v[200:203], v[36:39]
	v_mfma_f32_16x16x32_bf16 v[32:35], v[172:175], v[200:203], v[32:35]
	v_mfma_f32_16x16x32_bf16 v[20:23], v[148:151], v[208:211], v[20:23]
	v_mfma_f32_16x16x32_bf16 v[16:19], v[172:175], v[208:211], v[16:19]
	v_mfma_f32_16x16x32_bf16 v[4:7], v[148:151], v[216:219], v[4:7]
	v_mfma_f32_16x16x32_bf16 v[0:3], v[172:175], v[216:219], v[0:3]
	s_setprio 0
	s_barrier
	s_add_i32 s4, s4, 2
	s_add_u32 s14, s14, 0x100
	s_addc_u32 s15, s15, 0
	s_cmp_ge_i32 s4, s84
	s_cbranch_scc0 .LBB0_1193

.LBB0_1249:
	s_mov_b64 s[6:7], s[70:71]
	ds_read_b128 v[140:143], v151
	ds_read_b128 v[144:147], v151 offset:1024
	ds_read_b128 v[154:157], v151 offset:2048
	ds_read_b128 v[158:161], v151 offset:3072
	ds_read_b128 v[162:165], v152
	ds_read_b128 v[166:169], v152 offset:1024
	ds_read_b128 v[170:173], v152 offset:2048
	ds_read_b128 v[174:177], v152 offset:3072
	s_add_u32 s5, s66, s6
	s_addc_u32 s8, s67, s7
	s_add_u32 s9, s5, 0x100
	s_addc_u32 s28, s8, 0
	s_add_u32 s6, s68, s6
	s_addc_u32 s7, s69, s7
	s_add_u32 s6, s6, 0x100
	s_addc_u32 s7, s7, 0
	s_cmp_eq_u32 s80, s4
	s_cselect_b32 s75, s63, s28
	s_cselect_b32 s74, s62, s9
	s_cselect_b32 s73, s65, s7
	s_cselect_b32 s72, s64, s6
	s_add_u32 s6, s5, 0x80080
	s_addc_u32 s7, s8, 0
	v_lshl_add_u64 v[178:179], s[6:7], 0, v[134:135]
	s_add_i32 m0, s23, 0xc000
	ds_read_b128 v[182:185], v153
	ds_read_b128 v[186:189], v153 offset:1024
	ds_read_b128 v[190:193], v153 offset:2048
	ds_read_b128 v[194:197], v153 offset:3072
	ds_read_b128 v[198:201], v153 offset:4096
	ds_read_b128 v[202:205], v153 offset:5120
	ds_read_b128 v[206:209], v153 offset:6144
	ds_read_b128 v[210:213], v153 offset:7168
	global_load_lds_dwordx4 v[178:179], off
	v_lshl_add_u64 v[178:179], s[6:7], 0, v[130:131]
	s_add_i32 m0, s23, 0xe000
	s_nop 0
	global_load_lds_dwordx4 v[178:179], off
	s_waitcnt vmcnt(8)
	s_waitcnt lgkmcnt(0)
	s_barrier
	s_setprio 1
	v_mfma_f32_16x16x32_bf16 v[124:127], v[140:143], v[182:185], v[124:127]
	v_mfma_f32_16x16x32_bf16 v[120:123], v[154:157], v[182:185], v[120:123]
	v_mfma_f32_16x16x32_bf16 v[116:119], v[140:143], v[190:193], v[116:119]
	v_mfma_f32_16x16x32_bf16 v[112:115], v[154:157], v[190:193], v[112:115]
	v_mfma_f32_16x16x32_bf16 v[104:107], v[140:143], v[198:201], v[104:107]
	v_mfma_f32_16x16x32_bf16 v[96:99], v[154:157], v[198:201], v[96:99]
	v_mfma_f32_16x16x32_bf16 v[88:91], v[140:143], v[206:209], v[88:91]
	v_mfma_f32_16x16x32_bf16 v[80:83], v[154:157], v[206:209], v[80:83]
	v_mfma_f32_16x16x32_bf16 v[124:127], v[144:147], v[186:189], v[124:127]
	v_mfma_f32_16x16x32_bf16 v[120:123], v[158:161], v[186:189], v[120:123]
	v_mfma_f32_16x16x32_bf16 v[116:119], v[144:147], v[194:197], v[116:119]
	v_mfma_f32_16x16x32_bf16 v[112:115], v[158:161], v[194:197], v[112:115]
	v_mfma_f32_16x16x32_bf16 v[104:107], v[144:147], v[202:205], v[104:107]
	v_mfma_f32_16x16x32_bf16 v[96:99], v[158:161], v[202:205], v[96:99]
	v_mfma_f32_16x16x32_bf16 v[88:91], v[144:147], v[210:213], v[88:91]
	v_mfma_f32_16x16x32_bf16 v[80:83], v[158:161], v[210:213], v[80:83]
	v_mfma_f32_16x16x32_bf16 v[108:111], v[162:165], v[182:185], v[108:111]
	v_mfma_f32_16x16x32_bf16 v[100:103], v[170:173], v[182:185], v[100:103]
	v_mfma_f32_16x16x32_bf16 v[92:95], v[162:165], v[190:193], v[92:95]
	v_mfma_f32_16x16x32_bf16 v[84:87], v[170:173], v[190:193], v[84:87]
	v_mfma_f32_16x16x32_bf16 v[76:79], v[162:165], v[198:201], v[76:79]
	v_mfma_f32_16x16x32_bf16 v[72:75], v[170:173], v[198:201], v[72:75]
	v_mfma_f32_16x16x32_bf16 v[68:71], v[162:165], v[206:209], v[68:71]
	v_mfma_f32_16x16x32_bf16 v[64:67], v[170:173], v[206:209], v[64:67]
	v_mfma_f32_16x16x32_bf16 v[108:111], v[166:169], v[186:189], v[108:111]
	v_mfma_f32_16x16x32_bf16 v[100:103], v[174:177], v[186:189], v[100:103]
	v_mfma_f32_16x16x32_bf16 v[92:95], v[166:169], v[194:197], v[92:95]
	v_mfma_f32_16x16x32_bf16 v[84:87], v[174:177], v[194:197], v[84:87]
	v_mfma_f32_16x16x32_bf16 v[76:79], v[166:169], v[202:205], v[76:79]
	v_mfma_f32_16x16x32_bf16 v[72:75], v[174:177], v[202:205], v[72:75]
	v_mfma_f32_16x16x32_bf16 v[68:71], v[166:169], v[210:213], v[68:71]
	v_mfma_f32_16x16x32_bf16 v[64:67], v[174:177], v[210:213], v[64:67]
	s_setprio 0
	s_barrier
	s_add_i32 s5, s81, s18
	v_lshl_add_u64 v[178:179], s[72:73], 0, v[132:133]
	s_mov_b32 m0, s5
	ds_read_b128 v[182:185], v153 offset:16384
	ds_read_b128 v[186:189], v153 offset:17408
	ds_read_b128 v[190:193], v153 offset:18432
	ds_read_b128 v[194:197], v153 offset:19456
	ds_read_b128 v[198:201], v153 offset:20480
	ds_read_b128 v[202:205], v153 offset:21504
	ds_read_b128 v[206:209], v153 offset:22528
	ds_read_b128 v[210:213], v153 offset:23552
	global_load_lds_dwordx4 v[178:179], off
	s_add_i32 m0, s5, 0x2000
	s_add_u32 s6, s72, 0x80000
	v_lshl_add_u64 v[214:215], s[72:73], 0, v[128:129]
	s_addc_u32 s7, s73, 0
	s_add_i32 s5, s82, s18
	global_load_lds_dwordx4 v[214:215], off
	v_lshl_add_u64 v[216:217], s[6:7], 0, v[132:133]
	s_mov_b32 m0, s5
	v_lshl_add_u64 v[218:219], s[74:75], 0, v[130:131]
	global_load_lds_dwordx4 v[216:217], off
	v_lshl_add_u64 v[216:217], s[6:7], 0, v[128:129]
	s_add_i32 m0, s5, 0x2000
	s_nop 0
	global_load_lds_dwordx4 v[216:217], off
	v_lshl_add_u64 v[216:217], s[74:75], 0, v[134:135]
	s_mov_b32 m0, s23
	s_nop 0
	global_load_lds_dwordx4 v[216:217], off
	s_mov_b32 m0, s30
	s_nop 0
	global_load_lds_dwordx4 v[218:219], off
	s_waitcnt vmcnt(8)
	s_waitcnt lgkmcnt(0)
	s_barrier
	s_setprio 1
	v_mfma_f32_16x16x32_bf16 v[60:63], v[140:143], v[182:185], v[60:63]
	v_mfma_f32_16x16x32_bf16 v[56:59], v[154:157], v[182:185], v[56:59]
	v_mfma_f32_16x16x32_bf16 v[52:55], v[140:143], v[190:193], v[52:55]
	v_mfma_f32_16x16x32_bf16 v[48:51], v[154:157], v[190:193], v[48:51]
	v_mfma_f32_16x16x32_bf16 v[40:43], v[140:143], v[198:201], v[40:43]
	v_mfma_f32_16x16x32_bf16 v[32:35], v[154:157], v[198:201], v[32:35]
	v_mfma_f32_16x16x32_bf16 v[24:27], v[140:143], v[206:209], v[24:27]
	v_mfma_f32_16x16x32_bf16 v[16:19], v[154:157], v[206:209], v[16:19]
	v_mfma_f32_16x16x32_bf16 v[60:63], v[144:147], v[186:189], v[60:63]
	v_mfma_f32_16x16x32_bf16 v[56:59], v[158:161], v[186:189], v[56:59]
	v_mfma_f32_16x16x32_bf16 v[52:55], v[144:147], v[194:197], v[52:55]
	v_mfma_f32_16x16x32_bf16 v[48:51], v[158:161], v[194:197], v[48:51]
	v_mfma_f32_16x16x32_bf16 v[40:43], v[144:147], v[202:205], v[40:43]
	v_mfma_f32_16x16x32_bf16 v[32:35], v[158:161], v[202:205], v[32:35]
	v_mfma_f32_16x16x32_bf16 v[24:27], v[144:147], v[210:213], v[24:27]
	v_mfma_f32_16x16x32_bf16 v[16:19], v[158:161], v[210:213], v[16:19]
	v_mfma_f32_16x16x32_bf16 v[44:47], v[162:165], v[182:185], v[44:47]
	v_mfma_f32_16x16x32_bf16 v[36:39], v[170:173], v[182:185], v[36:39]
	v_mfma_f32_16x16x32_bf16 v[28:31], v[162:165], v[190:193], v[28:31]
	v_mfma_f32_16x16x32_bf16 v[20:23], v[170:173], v[190:193], v[20:23]
	v_mfma_f32_16x16x32_bf16 v[12:15], v[162:165], v[198:201], v[12:15]
	v_mfma_f32_16x16x32_bf16 v[8:11], v[170:173], v[198:201], v[8:11]
	v_mfma_f32_16x16x32_bf16 v[4:7], v[162:165], v[206:209], v[4:7]
	v_mfma_f32_16x16x32_bf16 v[0:3], v[170:173], v[206:209], v[0:3]
	v_mfma_f32_16x16x32_bf16 v[44:47], v[166:169], v[186:189], v[44:47]
	v_mfma_f32_16x16x32_bf16 v[36:39], v[174:177], v[186:189], v[36:39]
	v_mfma_f32_16x16x32_bf16 v[28:31], v[166:169], v[194:197], v[28:31]
	v_mfma_f32_16x16x32_bf16 v[20:23], v[174:177], v[194:197], v[20:23]
	v_mfma_f32_16x16x32_bf16 v[12:15], v[166:169], v[202:205], v[12:15]
	v_mfma_f32_16x16x32_bf16 v[8:11], v[174:177], v[202:205], v[8:11]
	v_mfma_f32_16x16x32_bf16 v[4:7], v[166:169], v[210:213], v[4:7]
	v_mfma_f32_16x16x32_bf16 v[0:3], v[174:177], v[210:213], v[0:3]
	s_setprio 0
	s_barrier
	s_add_i32 s5, 0, 0x18000
	s_add_i32 s8, 0, 0x1c000
	v_add_u32_e32 v158, s5, v150
	v_add_u32_e32 v174, s8, v150
	ds_read_b128 v[140:143], v158
	ds_read_b128 v[144:147], v158 offset:1024
	ds_read_b128 v[154:157], v158 offset:2048
	ds_read_b128 v[158:161], v158 offset:3072
	ds_read_b128 v[162:165], v174
	ds_read_b128 v[166:169], v174 offset:1024
	ds_read_b128 v[170:173], v174 offset:2048
	ds_read_b128 v[174:177], v174 offset:3072
	s_add_u32 s6, s74, 0x80000
	s_addc_u32 s7, s75, 0
	s_mov_b32 m0, s31
	v_lshl_add_u64 v[220:221], s[6:7], 0, v[134:135]
	ds_read_b128 v[182:185], v153 offset:32768
	ds_read_b128 v[186:189], v153 offset:33792
	ds_read_b128 v[190:193], v153 offset:34816
	ds_read_b128 v[194:197], v153 offset:35840
	ds_read_b128 v[198:201], v153 offset:36864
	ds_read_b128 v[202:205], v153 offset:37888
	ds_read_b128 v[206:209], v153 offset:38912
	ds_read_b128 v[210:213], v153 offset:39936
	global_load_lds_dwordx4 v[220:221], off
	v_lshl_add_u64 v[220:221], s[6:7], 0, v[130:131]
	s_mov_b32 m0, s56
	s_nop 0
	global_load_lds_dwordx4 v[220:221], off
	s_waitcnt vmcnt(8)
	s_waitcnt lgkmcnt(0)
	s_barrier
	s_setprio 1
	v_mfma_f32_16x16x32_bf16 v[124:127], v[140:143], v[182:185], v[124:127]
	v_mfma_f32_16x16x32_bf16 v[120:123], v[154:157], v[182:185], v[120:123]
	v_mfma_f32_16x16x32_bf16 v[116:119], v[140:143], v[190:193], v[116:119]
	v_mfma_f32_16x16x32_bf16 v[112:115], v[154:157], v[190:193], v[112:115]
	v_mfma_f32_16x16x32_bf16 v[104:107], v[140:143], v[198:201], v[104:107]
	v_mfma_f32_16x16x32_bf16 v[96:99], v[154:157], v[198:201], v[96:99]
	v_mfma_f32_16x16x32_bf16 v[88:91], v[140:143], v[206:209], v[88:91]
	v_mfma_f32_16x16x32_bf16 v[80:83], v[154:157], v[206:209], v[80:83]
	v_mfma_f32_16x16x32_bf16 v[124:127], v[144:147], v[186:189], v[124:127]
	v_mfma_f32_16x16x32_bf16 v[120:123], v[158:161], v[186:189], v[120:123]
	v_mfma_f32_16x16x32_bf16 v[116:119], v[144:147], v[194:197], v[116:119]
	v_mfma_f32_16x16x32_bf16 v[112:115], v[158:161], v[194:197], v[112:115]
	v_mfma_f32_16x16x32_bf16 v[104:107], v[144:147], v[202:205], v[104:107]
	v_mfma_f32_16x16x32_bf16 v[96:99], v[158:161], v[202:205], v[96:99]
	v_mfma_f32_16x16x32_bf16 v[88:91], v[144:147], v[210:213], v[88:91]
	v_mfma_f32_16x16x32_bf16 v[80:83], v[158:161], v[210:213], v[80:83]
	v_mfma_f32_16x16x32_bf16 v[108:111], v[162:165], v[182:185], v[108:111]
	v_mfma_f32_16x16x32_bf16 v[100:103], v[170:173], v[182:185], v[100:103]
	v_mfma_f32_16x16x32_bf16 v[92:95], v[162:165], v[190:193], v[92:95]
	v_mfma_f32_16x16x32_bf16 v[84:87], v[170:173], v[190:193], v[84:87]
	v_mfma_f32_16x16x32_bf16 v[76:79], v[162:165], v[198:201], v[76:79]
	v_mfma_f32_16x16x32_bf16 v[72:75], v[170:173], v[198:201], v[72:75]
	v_mfma_f32_16x16x32_bf16 v[68:71], v[162:165], v[206:209], v[68:71]
	v_mfma_f32_16x16x32_bf16 v[64:67], v[170:173], v[206:209], v[64:67]
	v_mfma_f32_16x16x32_bf16 v[108:111], v[166:169], v[186:189], v[108:111]
	v_mfma_f32_16x16x32_bf16 v[100:103], v[174:177], v[186:189], v[100:103]
	v_mfma_f32_16x16x32_bf16 v[92:95], v[166:169], v[194:197], v[92:95]
	v_mfma_f32_16x16x32_bf16 v[84:87], v[174:177], v[194:197], v[84:87]
	v_mfma_f32_16x16x32_bf16 v[76:79], v[166:169], v[202:205], v[76:79]
	v_mfma_f32_16x16x32_bf16 v[72:75], v[174:177], v[202:205], v[72:75]
	v_mfma_f32_16x16x32_bf16 v[68:71], v[166:169], v[210:213], v[68:71]
	v_mfma_f32_16x16x32_bf16 v[64:67], v[174:177], v[210:213], v[64:67]
	s_setprio 0
	s_barrier
	s_add_i32 s5, s5, s18
	v_lshl_add_u64 v[178:179], v[178:179], 0, s[2:3]
	s_mov_b32 m0, s5
	ds_read_b128 v[182:185], v153 offset:49152
	ds_read_b128 v[186:189], v153 offset:50176
	ds_read_b128 v[190:193], v153 offset:51200
	ds_read_b128 v[194:197], v153 offset:52224
	ds_read_b128 v[198:201], v153 offset:53248
	ds_read_b128 v[202:205], v153 offset:54272
	ds_read_b128 v[206:209], v153 offset:55296
	ds_read_b128 v[210:213], v153 offset:56320
	global_load_lds_dwordx4 v[178:179], off
	s_add_i32 m0, s5, 0x2000
	s_add_u32 s6, s72, 0x80080
	v_lshl_add_u64 v[178:179], v[214:215], 0, s[2:3]
	s_addc_u32 s7, s73, 0
	s_add_i32 s5, s8, s18
	global_load_lds_dwordx4 v[178:179], off
	v_lshl_add_u64 v[178:179], s[6:7], 0, v[132:133]
	s_mov_b32 m0, s5
	s_nop 0
	global_load_lds_dwordx4 v[178:179], off
	v_lshl_add_u64 v[178:179], s[6:7], 0, v[128:129]
	s_add_i32 m0, s5, 0x2000
	s_nop 0
	global_load_lds_dwordx4 v[178:179], off
	v_lshl_add_u64 v[178:179], v[216:217], 0, s[2:3]
	s_mov_b32 m0, s77
	s_nop 0
	global_load_lds_dwordx4 v[178:179], off
	v_lshl_add_u64 v[178:179], v[218:219], 0, s[2:3]
	s_mov_b32 m0, s79
	s_nop 0
	global_load_lds_dwordx4 v[178:179], off
	s_waitcnt vmcnt(8)
	s_waitcnt lgkmcnt(0)
	s_barrier
	s_setprio 1
	v_mfma_f32_16x16x32_bf16 v[60:63], v[140:143], v[182:185], v[60:63]
	v_mfma_f32_16x16x32_bf16 v[56:59], v[154:157], v[182:185], v[56:59]
	v_mfma_f32_16x16x32_bf16 v[52:55], v[140:143], v[190:193], v[52:55]
	v_mfma_f32_16x16x32_bf16 v[48:51], v[154:157], v[190:193], v[48:51]
	v_mfma_f32_16x16x32_bf16 v[40:43], v[140:143], v[198:201], v[40:43]
	v_mfma_f32_16x16x32_bf16 v[32:35], v[154:157], v[198:201], v[32:35]
	v_mfma_f32_16x16x32_bf16 v[24:27], v[140:143], v[206:209], v[24:27]
	v_mfma_f32_16x16x32_bf16 v[16:19], v[154:157], v[206:209], v[16:19]
	v_mfma_f32_16x16x32_bf16 v[60:63], v[144:147], v[186:189], v[60:63]
	v_mfma_f32_16x16x32_bf16 v[56:59], v[158:161], v[186:189], v[56:59]
	v_mfma_f32_16x16x32_bf16 v[52:55], v[144:147], v[194:197], v[52:55]
	v_mfma_f32_16x16x32_bf16 v[48:51], v[158:161], v[194:197], v[48:51]
	v_mfma_f32_16x16x32_bf16 v[40:43], v[144:147], v[202:205], v[40:43]
	v_mfma_f32_16x16x32_bf16 v[32:35], v[158:161], v[202:205], v[32:35]
	v_mfma_f32_16x16x32_bf16 v[24:27], v[144:147], v[210:213], v[24:27]
	v_mfma_f32_16x16x32_bf16 v[16:19], v[158:161], v[210:213], v[16:19]
	v_mfma_f32_16x16x32_bf16 v[44:47], v[162:165], v[182:185], v[44:47]
	v_mfma_f32_16x16x32_bf16 v[36:39], v[170:173], v[182:185], v[36:39]
	v_mfma_f32_16x16x32_bf16 v[28:31], v[162:165], v[190:193], v[28:31]
	v_mfma_f32_16x16x32_bf16 v[20:23], v[170:173], v[190:193], v[20:23]
	v_mfma_f32_16x16x32_bf16 v[12:15], v[162:165], v[198:201], v[12:15]
	v_mfma_f32_16x16x32_bf16 v[8:11], v[170:173], v[198:201], v[8:11]
	v_mfma_f32_16x16x32_bf16 v[4:7], v[162:165], v[206:209], v[4:7]
	v_mfma_f32_16x16x32_bf16 v[0:3], v[170:173], v[206:209], v[0:3]
	v_mfma_f32_16x16x32_bf16 v[44:47], v[166:169], v[186:189], v[44:47]
	v_mfma_f32_16x16x32_bf16 v[36:39], v[174:177], v[186:189], v[36:39]
	v_mfma_f32_16x16x32_bf16 v[28:31], v[166:169], v[194:197], v[28:31]
	v_mfma_f32_16x16x32_bf16 v[20:23], v[174:177], v[194:197], v[20:23]
	v_mfma_f32_16x16x32_bf16 v[12:15], v[166:169], v[202:205], v[12:15]
	v_mfma_f32_16x16x32_bf16 v[8:11], v[174:177], v[202:205], v[8:11]
	v_mfma_f32_16x16x32_bf16 v[4:7], v[166:169], v[210:213], v[4:7]
	v_mfma_f32_16x16x32_bf16 v[0:3], v[174:177], v[210:213], v[0:3]
	s_setprio 0
	s_barrier
	s_add_i32 s4, s4, 2
	s_add_u32 s70, s70, 0x100
	s_addc_u32 s71, s71, 0
	s_cmp_ge_i32 s4, s57
	s_cbranch_scc0 .LBB0_1249
	v_pk_add_f32 v[126:127], v[126:127], 0 op_sel_hi:[1,0]
	v_pk_add_f32 v[124:125], v[124:125], 0 op_sel_hi:[1,0]
	v_pk_add_f32 v[122:123], v[122:123], 0 op_sel_hi:[1,0]
	v_pk_add_f32 v[120:121], v[120:121], 0 op_sel_hi:[1,0]
	v_pk_add_f32 v[140:141], v[110:111], 0 op_sel_hi:[1,0]
	v_pk_add_f32 v[142:143], v[108:109], 0 op_sel_hi:[1,0]
	v_pk_add_f32 v[144:145], v[102:103], 0 op_sel_hi:[1,0]
	v_pk_add_f32 v[146:147], v[100:101], 0 op_sel_hi:[1,0]
	v_pk_add_f32 v[100:101], v[118:119], 0 op_sel_hi:[1,0]
	v_pk_add_f32 v[102:103], v[116:117], 0 op_sel_hi:[1,0]
	v_pk_add_f32 v[108:109], v[114:115], 0 op_sel_hi:[1,0]
	v_pk_add_f32 v[110:111], v[112:113], 0 op_sel_hi:[1,0]
	v_pk_add_f32 v[112:113], v[94:95], 0 op_sel_hi:[1,0]
	v_pk_add_f32 v[114:115], v[92:93], 0 op_sel_hi:[1,0]
	v_pk_add_f32 v[116:117], v[86:87], 0 op_sel_hi:[1,0]
	v_pk_add_f32 v[118:119], v[84:85], 0 op_sel_hi:[1,0]
	v_pk_add_f32 v[84:85], v[106:107], 0 op_sel_hi:[1,0]
	v_pk_add_f32 v[86:87], v[104:105], 0 op_sel_hi:[1,0]
	v_pk_add_f32 v[92:93], v[98:99], 0 op_sel_hi:[1,0]
	v_pk_add_f32 v[94:95], v[96:97], 0 op_sel_hi:[1,0]
	v_pk_add_f32 v[96:97], v[78:79], 0 op_sel_hi:[1,0]
	v_pk_add_f32 v[98:99], v[76:77], 0 op_sel_hi:[1,0]
	v_pk_add_f32 v[104:105], v[74:75], 0 op_sel_hi:[1,0]
	v_pk_add_f32 v[106:107], v[72:73], 0 op_sel_hi:[1,0]
	v_pk_add_f32 v[72:73], v[90:91], 0 op_sel_hi:[1,0]
	v_pk_add_f32 v[74:75], v[88:89], 0 op_sel_hi:[1,0]
	v_pk_add_f32 v[76:77], v[82:83], 0 op_sel_hi:[1,0]
	v_pk_add_f32 v[78:79], v[80:81], 0 op_sel_hi:[1,0]
	v_pk_add_f32 v[70:71], v[70:71], 0 op_sel_hi:[1,0]
	v_pk_add_f32 v[68:69], v[68:69], 0 op_sel_hi:[1,0]
	v_pk_add_f32 v[66:67], v[66:67], 0 op_sel_hi:[1,0]
	v_pk_add_f32 v[64:65], v[64:65], 0 op_sel_hi:[1,0]
	v_pk_add_f32 v[62:63], v[62:63], 0 op_sel_hi:[1,0]
	v_pk_add_f32 v[60:61], v[60:61], 0 op_sel_hi:[1,0]
	v_pk_add_f32 v[58:59], v[58:59], 0 op_sel_hi:[1,0]
	v_pk_add_f32 v[56:57], v[56:57], 0 op_sel_hi:[1,0]
	v_pk_add_f32 v[80:81], v[46:47], 0 op_sel_hi:[1,0]
	v_pk_add_f32 v[82:83], v[44:45], 0 op_sel_hi:[1,0]
	v_pk_add_f32 v[88:89], v[38:39], 0 op_sel_hi:[1,0]
	v_pk_add_f32 v[90:91], v[36:37], 0 op_sel_hi:[1,0]
	v_pk_add_f32 v[36:37], v[54:55], 0 op_sel_hi:[1,0]
	v_pk_add_f32 v[38:39], v[52:53], 0 op_sel_hi:[1,0]
	v_pk_add_f32 v[44:45], v[50:51], 0 op_sel_hi:[1,0]
	v_pk_add_f32 v[46:47], v[48:49], 0 op_sel_hi:[1,0]
	v_pk_add_f32 v[48:49], v[30:31], 0 op_sel_hi:[1,0]
	v_pk_add_f32 v[50:51], v[28:29], 0 op_sel_hi:[1,0]
	v_pk_add_f32 v[52:53], v[22:23], 0 op_sel_hi:[1,0]
	v_pk_add_f32 v[54:55], v[20:21], 0 op_sel_hi:[1,0]
	v_pk_add_f32 v[20:21], v[42:43], 0 op_sel_hi:[1,0]
	v_pk_add_f32 v[22:23], v[40:41], 0 op_sel_hi:[1,0]
	v_pk_add_f32 v[28:29], v[34:35], 0 op_sel_hi:[1,0]
	v_pk_add_f32 v[30:31], v[32:33], 0 op_sel_hi:[1,0]
	v_pk_add_f32 v[32:33], v[14:15], 0 op_sel_hi:[1,0]
	v_pk_add_f32 v[34:35], v[12:13], 0 op_sel_hi:[1,0]
	v_pk_add_f32 v[40:41], v[10:11], 0 op_sel_hi:[1,0]
	v_pk_add_f32 v[42:43], v[8:9], 0 op_sel_hi:[1,0]
	v_pk_add_f32 v[8:9], v[26:27], 0 op_sel_hi:[1,0]
	v_pk_add_f32 v[10:11], v[24:25], 0 op_sel_hi:[1,0]
	v_pk_add_f32 v[12:13], v[18:19], 0 op_sel_hi:[1,0]
	v_pk_add_f32 v[14:15], v[16:17], 0 op_sel_hi:[1,0]
	v_pk_add_f32 v[6:7], v[6:7], 0 op_sel_hi:[1,0]
	v_pk_add_f32 v[4:5], v[4:5], 0 op_sel_hi:[1,0]
	v_pk_add_f32 v[2:3], v[2:3], 0 op_sel_hi:[1,0]
	v_pk_add_f32 v[0:1], v[0:1], 0 op_sel_hi:[1,0]

.LBB0_1323:
	s_mov_b64 s[42:43], s[72:73]
	s_add_u32 s44, s70, s42
	s_addc_u32 s45, s71, s43
	s_add_u32 s48, s44, 0x100
	s_addc_u32 s49, s45, 0
	s_add_u32 s42, s68, s42
	s_addc_u32 s43, s69, s43
	s_add_u32 s42, s42, 0x100
	s_addc_u32 s43, s43, 0
	s_add_i32 s50, 0, 0x10000
	s_cmp_eq_u32 s9, s86
	s_cselect_b32 s77, s65, s49
	s_cselect_b32 s76, s64, s48
	s_cselect_b32 s75, s67, s43
	s_cselect_b32 s74, s66, s42
	s_add_i32 s48, 0, 0x14000
	v_add_u32_e32 v152, s50, v138
	v_add_u32_e32 v168, s48, v138
	ds_read_b128 v[140:143], v152
	ds_read_b128 v[144:147], v152 offset:1024
	ds_read_b128 v[148:151], v152 offset:2048
	ds_read_b128 v[152:155], v152 offset:3072
	ds_read_b128 v[156:159], v168
	ds_read_b128 v[160:163], v168 offset:1024
	ds_read_b128 v[164:167], v168 offset:2048
	ds_read_b128 v[168:171], v168 offset:3072
	s_add_u32 s42, s44, 0x100080
	s_addc_u32 s43, s45, 0
	v_lshl_add_u64 v[186:187], s[42:43], 0, v[134:135]
	s_add_i32 m0, s93, 0xc000
	ds_read_b128 v[172:175], v139
	ds_read_b128 v[176:179], v139 offset:1024
	ds_read_b128 v[182:185], v139 offset:2048
	ds_read_b128 v[190:193], v139 offset:3072
	ds_read_b128 v[194:197], v139 offset:4096
	ds_read_b128 v[198:201], v139 offset:5120
	ds_read_b128 v[202:205], v139 offset:6144
	ds_read_b128 v[206:209], v139 offset:7168
	global_load_lds_dwordx4 v[186:187], off
	v_lshl_add_u64 v[186:187], s[42:43], 0, v[132:133]
	s_add_i32 m0, s93, 0xe000
	s_nop 0
	global_load_lds_dwordx4 v[186:187], off
	s_waitcnt vmcnt(8)
	s_waitcnt lgkmcnt(0)
	s_barrier
	s_setprio 1
	v_mfma_f32_16x16x32_bf16 v[126:129], v[140:143], v[172:175], v[126:129]
	v_mfma_f32_16x16x32_bf16 v[122:125], v[148:151], v[172:175], v[122:125]
	v_mfma_f32_16x16x32_bf16 v[110:113], v[140:143], v[182:185], v[110:113]
	v_mfma_f32_16x16x32_bf16 v[106:109], v[148:151], v[182:185], v[106:109]
	v_mfma_f32_16x16x32_bf16 v[94:97], v[140:143], v[194:197], v[94:97]
	v_mfma_f32_16x16x32_bf16 v[90:93], v[148:151], v[194:197], v[90:93]
	v_mfma_f32_16x16x32_bf16 v[78:81], v[140:143], v[202:205], v[78:81]
	v_mfma_f32_16x16x32_bf16 v[74:77], v[148:151], v[202:205], v[74:77]
	v_mfma_f32_16x16x32_bf16 v[126:129], v[144:147], v[176:179], v[126:129]
	v_mfma_f32_16x16x32_bf16 v[122:125], v[152:155], v[176:179], v[122:125]
	v_mfma_f32_16x16x32_bf16 v[110:113], v[144:147], v[190:193], v[110:113]
	v_mfma_f32_16x16x32_bf16 v[106:109], v[152:155], v[190:193], v[106:109]
	v_mfma_f32_16x16x32_bf16 v[94:97], v[144:147], v[198:201], v[94:97]
	v_mfma_f32_16x16x32_bf16 v[90:93], v[152:155], v[198:201], v[90:93]
	v_mfma_f32_16x16x32_bf16 v[78:81], v[144:147], v[206:209], v[78:81]
	v_mfma_f32_16x16x32_bf16 v[74:77], v[152:155], v[206:209], v[74:77]
	v_mfma_f32_16x16x32_bf16 v[118:121], v[156:159], v[172:175], v[118:121]
	v_mfma_f32_16x16x32_bf16 v[114:117], v[164:167], v[172:175], v[114:117]
	v_mfma_f32_16x16x32_bf16 v[102:105], v[156:159], v[182:185], v[102:105]
	v_mfma_f32_16x16x32_bf16 v[98:101], v[164:167], v[182:185], v[98:101]
	v_mfma_f32_16x16x32_bf16 v[86:89], v[156:159], v[194:197], v[86:89]
	v_mfma_f32_16x16x32_bf16 v[82:85], v[164:167], v[194:197], v[82:85]
	v_mfma_f32_16x16x32_bf16 v[70:73], v[156:159], v[202:205], v[70:73]
	v_mfma_f32_16x16x32_bf16 v[66:69], v[164:167], v[202:205], v[66:69]
	v_mfma_f32_16x16x32_bf16 v[118:121], v[160:163], v[176:179], v[118:121]
	v_mfma_f32_16x16x32_bf16 v[114:117], v[168:171], v[176:179], v[114:117]
	v_mfma_f32_16x16x32_bf16 v[102:105], v[160:163], v[190:193], v[102:105]
	v_mfma_f32_16x16x32_bf16 v[98:101], v[168:171], v[190:193], v[98:101]
	v_mfma_f32_16x16x32_bf16 v[86:89], v[160:163], v[198:201], v[86:89]
	v_mfma_f32_16x16x32_bf16 v[82:85], v[168:171], v[198:201], v[82:85]
	v_mfma_f32_16x16x32_bf16 v[70:73], v[160:163], v[206:209], v[70:73]
	v_mfma_f32_16x16x32_bf16 v[66:69], v[168:171], v[206:209], v[66:69]
	s_setprio 0
	s_barrier
	s_add_i32 s42, s50, s92
	v_lshl_add_u64 v[186:187], s[74:75], 0, v[0:1]
	s_mov_b32 m0, s42
	ds_read_b128 v[172:175], v139 offset:16384
	ds_read_b128 v[176:179], v139 offset:17408
	ds_read_b128 v[182:185], v139 offset:18432
	ds_read_b128 v[190:193], v139 offset:19456
	ds_read_b128 v[194:197], v139 offset:20480
	ds_read_b128 v[198:201], v139 offset:21504
	ds_read_b128 v[202:205], v139 offset:22528
	ds_read_b128 v[206:209], v139 offset:23552
	global_load_lds_dwordx4 v[186:187], off
	s_add_i32 m0, s42, 0x2000
	s_add_u32 s42, s74, 0x500000
	v_lshl_add_u64 v[210:211], s[74:75], 0, v[130:131]
	s_addc_u32 s43, s75, 0
	s_add_i32 s44, s48, s92
	global_load_lds_dwordx4 v[210:211], off
	v_lshl_add_u64 v[212:213], s[42:43], 0, v[0:1]
	s_mov_b32 m0, s44
	v_lshl_add_u64 v[214:215], s[76:77], 0, v[132:133]
	global_load_lds_dwordx4 v[212:213], off
	v_lshl_add_u64 v[212:213], s[42:43], 0, v[130:131]
	s_add_i32 m0, s44, 0x2000
	s_nop 0
	global_load_lds_dwordx4 v[212:213], off
	v_lshl_add_u64 v[212:213], s[76:77], 0, v[134:135]
	s_mov_b32 m0, s93
	s_nop 0
	global_load_lds_dwordx4 v[212:213], off
	s_mov_b32 m0, s94
	s_nop 0
	global_load_lds_dwordx4 v[214:215], off
	s_waitcnt vmcnt(8)
	s_waitcnt lgkmcnt(0)
	s_barrier
	s_setprio 1
	v_mfma_f32_16x16x32_bf16 v[62:65], v[140:143], v[172:175], v[62:65]
	v_mfma_f32_16x16x32_bf16 v[58:61], v[148:151], v[172:175], v[58:61]
	v_mfma_f32_16x16x32_bf16 v[46:49], v[140:143], v[182:185], v[46:49]
	v_mfma_f32_16x16x32_bf16 v[42:45], v[148:151], v[182:185], v[42:45]
	v_mfma_f32_16x16x32_bf16 v[30:33], v[140:143], v[194:197], v[30:33]
	v_mfma_f32_16x16x32_bf16 v[26:29], v[148:151], v[194:197], v[26:29]
	v_mfma_f32_16x16x32_bf16 v[14:17], v[140:143], v[202:205], v[14:17]
	v_mfma_f32_16x16x32_bf16 v[10:13], v[148:151], v[202:205], v[10:13]
	v_mfma_f32_16x16x32_bf16 v[62:65], v[144:147], v[176:179], v[62:65]
	v_mfma_f32_16x16x32_bf16 v[58:61], v[152:155], v[176:179], v[58:61]
	v_mfma_f32_16x16x32_bf16 v[46:49], v[144:147], v[190:193], v[46:49]
	v_mfma_f32_16x16x32_bf16 v[42:45], v[152:155], v[190:193], v[42:45]
	v_mfma_f32_16x16x32_bf16 v[30:33], v[144:147], v[198:201], v[30:33]
	v_mfma_f32_16x16x32_bf16 v[26:29], v[152:155], v[198:201], v[26:29]
	v_mfma_f32_16x16x32_bf16 v[14:17], v[144:147], v[206:209], v[14:17]
	v_mfma_f32_16x16x32_bf16 v[10:13], v[152:155], v[206:209], v[10:13]
	v_mfma_f32_16x16x32_bf16 v[54:57], v[156:159], v[172:175], v[54:57]
	v_mfma_f32_16x16x32_bf16 v[50:53], v[164:167], v[172:175], v[50:53]
	v_mfma_f32_16x16x32_bf16 v[38:41], v[156:159], v[182:185], v[38:41]
	v_mfma_f32_16x16x32_bf16 v[34:37], v[164:167], v[182:185], v[34:37]
	v_mfma_f32_16x16x32_bf16 v[22:25], v[156:159], v[194:197], v[22:25]
	v_mfma_f32_16x16x32_bf16 v[18:21], v[164:167], v[194:197], v[18:21]
	v_mfma_f32_16x16x32_bf16 v[6:9], v[156:159], v[202:205], v[6:9]
	v_mfma_f32_16x16x32_bf16 v[2:5], v[164:167], v[202:205], v[2:5]
	v_mfma_f32_16x16x32_bf16 v[54:57], v[160:163], v[176:179], v[54:57]
	v_mfma_f32_16x16x32_bf16 v[50:53], v[168:171], v[176:179], v[50:53]
	v_mfma_f32_16x16x32_bf16 v[38:41], v[160:163], v[190:193], v[38:41]
	v_mfma_f32_16x16x32_bf16 v[34:37], v[168:171], v[190:193], v[34:37]
	v_mfma_f32_16x16x32_bf16 v[22:25], v[160:163], v[198:201], v[22:25]
	v_mfma_f32_16x16x32_bf16 v[18:21], v[168:171], v[198:201], v[18:21]
	v_mfma_f32_16x16x32_bf16 v[6:9], v[160:163], v[206:209], v[6:9]
	v_mfma_f32_16x16x32_bf16 v[2:5], v[168:171], v[206:209], v[2:5]
	s_setprio 0
	s_barrier
	s_add_i32 s44, 0, 0x18000
	s_add_i32 s45, 0, 0x1c000
	v_add_u32_e32 v152, s44, v138
	v_add_u32_e32 v168, s45, v138
	ds_read_b128 v[140:143], v152
	ds_read_b128 v[144:147], v152 offset:1024
	ds_read_b128 v[148:151], v152 offset:2048
	ds_read_b128 v[152:155], v152 offset:3072
	ds_read_b128 v[156:159], v168
	ds_read_b128 v[160:163], v168 offset:1024
	ds_read_b128 v[164:167], v168 offset:2048
	ds_read_b128 v[168:171], v168 offset:3072
	s_add_u32 s42, s76, 0x100000
	s_addc_u32 s43, s77, 0
	s_mov_b32 m0, s95
	v_lshl_add_u64 v[216:217], s[42:43], 0, v[134:135]
	ds_read_b128 v[172:175], v139 offset:32768
	ds_read_b128 v[176:179], v139 offset:33792
	ds_read_b128 v[182:185], v139 offset:34816
	ds_read_b128 v[190:193], v139 offset:35840
	ds_read_b128 v[194:197], v139 offset:36864
	ds_read_b128 v[198:201], v139 offset:37888
	ds_read_b128 v[202:205], v139 offset:38912
	ds_read_b128 v[206:209], v139 offset:39936
	global_load_lds_dwordx4 v[216:217], off
	v_lshl_add_u64 v[216:217], s[42:43], 0, v[132:133]
	s_mov_b32 m0, s96
	s_nop 0
	global_load_lds_dwordx4 v[216:217], off
	s_waitcnt vmcnt(8)
	s_waitcnt lgkmcnt(0)
	s_barrier
	s_setprio 1
	v_mfma_f32_16x16x32_bf16 v[126:129], v[140:143], v[172:175], v[126:129]
	v_mfma_f32_16x16x32_bf16 v[122:125], v[148:151], v[172:175], v[122:125]
	v_mfma_f32_16x16x32_bf16 v[110:113], v[140:143], v[182:185], v[110:113]
	v_mfma_f32_16x16x32_bf16 v[106:109], v[148:151], v[182:185], v[106:109]
	v_mfma_f32_16x16x32_bf16 v[94:97], v[140:143], v[194:197], v[94:97]
	v_mfma_f32_16x16x32_bf16 v[90:93], v[148:151], v[194:197], v[90:93]
	v_mfma_f32_16x16x32_bf16 v[78:81], v[140:143], v[202:205], v[78:81]
	v_mfma_f32_16x16x32_bf16 v[74:77], v[148:151], v[202:205], v[74:77]
	v_mfma_f32_16x16x32_bf16 v[126:129], v[144:147], v[176:179], v[126:129]
	v_mfma_f32_16x16x32_bf16 v[122:125], v[152:155], v[176:179], v[122:125]
	v_mfma_f32_16x16x32_bf16 v[110:113], v[144:147], v[190:193], v[110:113]
	v_mfma_f32_16x16x32_bf16 v[106:109], v[152:155], v[190:193], v[106:109]
	v_mfma_f32_16x16x32_bf16 v[94:97], v[144:147], v[198:201], v[94:97]
	v_mfma_f32_16x16x32_bf16 v[90:93], v[152:155], v[198:201], v[90:93]
	v_mfma_f32_16x16x32_bf16 v[78:81], v[144:147], v[206:209], v[78:81]
	v_mfma_f32_16x16x32_bf16 v[74:77], v[152:155], v[206:209], v[74:77]
	v_mfma_f32_16x16x32_bf16 v[118:121], v[156:159], v[172:175], v[118:121]
	v_mfma_f32_16x16x32_bf16 v[114:117], v[164:167], v[172:175], v[114:117]
	v_mfma_f32_16x16x32_bf16 v[102:105], v[156:159], v[182:185], v[102:105]
	v_mfma_f32_16x16x32_bf16 v[98:101], v[164:167], v[182:185], v[98:101]
	v_mfma_f32_16x16x32_bf16 v[86:89], v[156:159], v[194:197], v[86:89]
	v_mfma_f32_16x16x32_bf16 v[82:85], v[164:167], v[194:197], v[82:85]
	v_mfma_f32_16x16x32_bf16 v[70:73], v[156:159], v[202:205], v[70:73]
	v_mfma_f32_16x16x32_bf16 v[66:69], v[164:167], v[202:205], v[66:69]
	v_mfma_f32_16x16x32_bf16 v[118:121], v[160:163], v[176:179], v[118:121]
	v_mfma_f32_16x16x32_bf16 v[114:117], v[168:171], v[176:179], v[114:117]
	v_mfma_f32_16x16x32_bf16 v[102:105], v[160:163], v[190:193], v[102:105]
	v_mfma_f32_16x16x32_bf16 v[98:101], v[168:171], v[190:193], v[98:101]
	v_mfma_f32_16x16x32_bf16 v[86:89], v[160:163], v[198:201], v[86:89]
	v_mfma_f32_16x16x32_bf16 v[82:85], v[168:171], v[198:201], v[82:85]
	v_mfma_f32_16x16x32_bf16 v[70:73], v[160:163], v[206:209], v[70:73]
	v_mfma_f32_16x16x32_bf16 v[66:69], v[168:171], v[206:209], v[66:69]
	s_setprio 0
	s_barrier
	s_add_i32 s42, s44, s92
	v_lshl_add_u64 v[186:187], v[186:187], 0, s[62:63]
	s_mov_b32 m0, s42
	ds_read_b128 v[172:175], v139 offset:49152
	ds_read_b128 v[176:179], v139 offset:50176
	ds_read_b128 v[182:185], v139 offset:51200
	ds_read_b128 v[190:193], v139 offset:52224
	ds_read_b128 v[194:197], v139 offset:53248
	ds_read_b128 v[198:201], v139 offset:54272
	ds_read_b128 v[202:205], v139 offset:55296
	ds_read_b128 v[206:209], v139 offset:56320
	global_load_lds_dwordx4 v[186:187], off
	s_add_i32 m0, s42, 0x2000
	s_add_u32 s42, s74, 0x500080
	v_lshl_add_u64 v[186:187], v[210:211], 0, s[62:63]
	s_addc_u32 s43, s75, 0
	s_add_i32 s44, s45, s92
	global_load_lds_dwordx4 v[186:187], off
	v_lshl_add_u64 v[186:187], s[42:43], 0, v[0:1]
	s_mov_b32 m0, s44
	s_nop 0
	global_load_lds_dwordx4 v[186:187], off
	v_lshl_add_u64 v[186:187], s[42:43], 0, v[130:131]
	s_add_i32 m0, s44, 0x2000
	s_nop 0
	global_load_lds_dwordx4 v[186:187], off
	v_lshl_add_u64 v[186:187], v[212:213], 0, s[62:63]
	s_mov_b32 m0, s7
	s_nop 0
	global_load_lds_dwordx4 v[186:187], off
	v_lshl_add_u64 v[186:187], v[214:215], 0, s[62:63]
	s_mov_b32 m0, s8
	s_nop 0
	global_load_lds_dwordx4 v[186:187], off
	s_waitcnt vmcnt(8)
	s_waitcnt lgkmcnt(0)
	s_barrier
	s_setprio 1
	v_mfma_f32_16x16x32_bf16 v[62:65], v[140:143], v[172:175], v[62:65]
	v_mfma_f32_16x16x32_bf16 v[58:61], v[148:151], v[172:175], v[58:61]
	v_mfma_f32_16x16x32_bf16 v[46:49], v[140:143], v[182:185], v[46:49]
	v_mfma_f32_16x16x32_bf16 v[42:45], v[148:151], v[182:185], v[42:45]
	v_mfma_f32_16x16x32_bf16 v[30:33], v[140:143], v[194:197], v[30:33]
	v_mfma_f32_16x16x32_bf16 v[26:29], v[148:151], v[194:197], v[26:29]
	v_mfma_f32_16x16x32_bf16 v[14:17], v[140:143], v[202:205], v[14:17]
	v_mfma_f32_16x16x32_bf16 v[10:13], v[148:151], v[202:205], v[10:13]
	v_mfma_f32_16x16x32_bf16 v[62:65], v[144:147], v[176:179], v[62:65]
	v_mfma_f32_16x16x32_bf16 v[58:61], v[152:155], v[176:179], v[58:61]
	v_mfma_f32_16x16x32_bf16 v[46:49], v[144:147], v[190:193], v[46:49]
	v_mfma_f32_16x16x32_bf16 v[42:45], v[152:155], v[190:193], v[42:45]
	v_mfma_f32_16x16x32_bf16 v[30:33], v[144:147], v[198:201], v[30:33]
	v_mfma_f32_16x16x32_bf16 v[26:29], v[152:155], v[198:201], v[26:29]
	v_mfma_f32_16x16x32_bf16 v[14:17], v[144:147], v[206:209], v[14:17]
	v_mfma_f32_16x16x32_bf16 v[10:13], v[152:155], v[206:209], v[10:13]
	v_mfma_f32_16x16x32_bf16 v[54:57], v[156:159], v[172:175], v[54:57]
	v_mfma_f32_16x16x32_bf16 v[50:53], v[164:167], v[172:175], v[50:53]
	v_mfma_f32_16x16x32_bf16 v[38:41], v[156:159], v[182:185], v[38:41]
	v_mfma_f32_16x16x32_bf16 v[34:37], v[164:167], v[182:185], v[34:37]
	v_mfma_f32_16x16x32_bf16 v[22:25], v[156:159], v[194:197], v[22:25]
	v_mfma_f32_16x16x32_bf16 v[18:21], v[164:167], v[194:197], v[18:21]
	v_mfma_f32_16x16x32_bf16 v[6:9], v[156:159], v[202:205], v[6:9]
	v_mfma_f32_16x16x32_bf16 v[2:5], v[164:167], v[202:205], v[2:5]
	v_mfma_f32_16x16x32_bf16 v[54:57], v[160:163], v[176:179], v[54:57]
	v_mfma_f32_16x16x32_bf16 v[50:53], v[168:171], v[176:179], v[50:53]
	v_mfma_f32_16x16x32_bf16 v[38:41], v[160:163], v[190:193], v[38:41]
	v_mfma_f32_16x16x32_bf16 v[34:37], v[168:171], v[190:193], v[34:37]
	v_mfma_f32_16x16x32_bf16 v[22:25], v[160:163], v[198:201], v[22:25]
	v_mfma_f32_16x16x32_bf16 v[18:21], v[168:171], v[198:201], v[18:21]
	v_mfma_f32_16x16x32_bf16 v[6:9], v[160:163], v[206:209], v[6:9]
	v_mfma_f32_16x16x32_bf16 v[2:5], v[168:171], v[206:209], v[2:5]
	s_setprio 0
	s_barrier
	s_add_i32 s86, s86, 2
	s_add_u32 s72, s72, 0x100
	s_addc_u32 s73, s73, 0
	s_cmp_ge_i32 s86, s97
	s_cbranch_scc0 .LBB0_1323

.LBB0_1479:
	s_mov_b64 s[6:7], s[58:59]
	ds_read_b128 v[136:139], v183
	ds_read_b128 v[140:143], v183 offset:1024
	ds_read_b128 v[144:147], v183 offset:2048
	ds_read_b128 v[148:151], v183 offset:3072
	ds_read_b128 v[152:155], v184
	ds_read_b128 v[156:159], v184 offset:1024
	ds_read_b128 v[160:163], v184 offset:2048
	ds_read_b128 v[164:167], v184 offset:3072
	s_add_u32 s5, s36, s6
	s_addc_u32 s8, s37, s7
	s_add_u32 s9, s5, 0x100
	s_addc_u32 s17, s8, 0
	s_add_u32 s6, s54, s6
	s_addc_u32 s7, s55, s7
	s_add_u32 s6, s6, 0x100
	s_addc_u32 s7, s7, 0
	s_cmp_eq_u32 s72, s4
	s_cselect_b32 s63, s53, s17
	s_cselect_b32 s62, s52, s9
	s_cselect_b32 s61, s57, s7
	s_cselect_b32 s60, s56, s6
	s_add_u32 s6, s5, 0x100080
	s_addc_u32 s7, s8, 0
	v_lshl_add_u64 v[176:177], s[6:7], 0, v[128:129]
	s_add_i32 m0, s31, 0xc000
	ds_read_b128 v[168:171], v185
	ds_read_b128 v[172:175], v185 offset:1024
	ds_read_b128 v[186:189], v185 offset:2048
	ds_read_b128 v[190:193], v185 offset:3072
	ds_read_b128 v[194:197], v185 offset:4096
	ds_read_b128 v[198:201], v185 offset:5120
	ds_read_b128 v[202:205], v185 offset:6144
	ds_read_b128 v[206:209], v185 offset:7168
	global_load_lds_dwordx4 v[176:177], off
	v_lshl_add_u64 v[176:177], s[6:7], 0, v[130:131]
	s_add_i32 m0, s31, 0xe000
	s_nop 0
	global_load_lds_dwordx4 v[176:177], off
	s_waitcnt vmcnt(8)
	s_waitcnt lgkmcnt(0)
	s_barrier
	s_setprio 1
	v_mfma_f32_16x16x32_bf16 v[124:127], v[136:139], v[168:171], v[124:127]
	v_mfma_f32_16x16x32_bf16 v[120:123], v[144:147], v[168:171], v[120:123]
	v_mfma_f32_16x16x32_bf16 v[116:119], v[136:139], v[186:189], v[116:119]
	v_mfma_f32_16x16x32_bf16 v[112:115], v[144:147], v[186:189], v[112:115]
	v_mfma_f32_16x16x32_bf16 v[104:107], v[136:139], v[194:197], v[104:107]
	v_mfma_f32_16x16x32_bf16 v[96:99], v[144:147], v[194:197], v[96:99]
	v_mfma_f32_16x16x32_bf16 v[88:91], v[136:139], v[202:205], v[88:91]
	v_mfma_f32_16x16x32_bf16 v[80:83], v[144:147], v[202:205], v[80:83]
	v_mfma_f32_16x16x32_bf16 v[124:127], v[140:143], v[172:175], v[124:127]
	v_mfma_f32_16x16x32_bf16 v[120:123], v[148:151], v[172:175], v[120:123]
	v_mfma_f32_16x16x32_bf16 v[116:119], v[140:143], v[190:193], v[116:119]
	v_mfma_f32_16x16x32_bf16 v[112:115], v[148:151], v[190:193], v[112:115]
	v_mfma_f32_16x16x32_bf16 v[104:107], v[140:143], v[198:201], v[104:107]
	v_mfma_f32_16x16x32_bf16 v[96:99], v[148:151], v[198:201], v[96:99]
	v_mfma_f32_16x16x32_bf16 v[88:91], v[140:143], v[206:209], v[88:91]
	v_mfma_f32_16x16x32_bf16 v[80:83], v[148:151], v[206:209], v[80:83]
	v_mfma_f32_16x16x32_bf16 v[108:111], v[152:155], v[168:171], v[108:111]
	v_mfma_f32_16x16x32_bf16 v[100:103], v[160:163], v[168:171], v[100:103]
	v_mfma_f32_16x16x32_bf16 v[92:95], v[152:155], v[186:189], v[92:95]
	v_mfma_f32_16x16x32_bf16 v[84:87], v[160:163], v[186:189], v[84:87]
	v_mfma_f32_16x16x32_bf16 v[76:79], v[152:155], v[194:197], v[76:79]
	v_mfma_f32_16x16x32_bf16 v[72:75], v[160:163], v[194:197], v[72:75]
	v_mfma_f32_16x16x32_bf16 v[68:71], v[152:155], v[202:205], v[68:71]
	v_mfma_f32_16x16x32_bf16 v[64:67], v[160:163], v[202:205], v[64:67]
	v_mfma_f32_16x16x32_bf16 v[108:111], v[156:159], v[172:175], v[108:111]
	v_mfma_f32_16x16x32_bf16 v[100:103], v[164:167], v[172:175], v[100:103]
	v_mfma_f32_16x16x32_bf16 v[92:95], v[156:159], v[190:193], v[92:95]
	v_mfma_f32_16x16x32_bf16 v[84:87], v[164:167], v[190:193], v[84:87]
	v_mfma_f32_16x16x32_bf16 v[76:79], v[156:159], v[198:201], v[76:79]
	v_mfma_f32_16x16x32_bf16 v[72:75], v[164:167], v[198:201], v[72:75]
	v_mfma_f32_16x16x32_bf16 v[68:71], v[156:159], v[206:209], v[68:71]
	v_mfma_f32_16x16x32_bf16 v[64:67], v[164:167], v[206:209], v[64:67]
	s_setprio 0
	s_barrier
	s_add_i32 s5, s73, s30
	v_lshl_add_u64 v[176:177], s[60:61], 0, v[128:129]
	s_mov_b32 m0, s5
	ds_read_b128 v[168:171], v185 offset:16384
	ds_read_b128 v[172:175], v185 offset:17408
	ds_read_b128 v[186:189], v185 offset:18432
	ds_read_b128 v[190:193], v185 offset:19456
	ds_read_b128 v[194:197], v185 offset:20480
	ds_read_b128 v[198:201], v185 offset:21504
	ds_read_b128 v[202:205], v185 offset:22528
	ds_read_b128 v[206:209], v185 offset:23552
	global_load_lds_dwordx4 v[176:177], off
	s_add_i32 m0, s5, 0x2000
	s_add_u32 s6, s60, 0x100000
	v_lshl_add_u64 v[210:211], s[60:61], 0, v[130:131]
	s_addc_u32 s7, s61, 0
	s_add_i32 s5, s74, s30
	global_load_lds_dwordx4 v[210:211], off
	v_lshl_add_u64 v[212:213], s[6:7], 0, v[128:129]
	s_mov_b32 m0, s5
	v_lshl_add_u64 v[214:215], s[62:63], 0, v[130:131]
	global_load_lds_dwordx4 v[212:213], off
	v_lshl_add_u64 v[212:213], s[6:7], 0, v[130:131]
	s_add_i32 m0, s5, 0x2000
	s_nop 0
	global_load_lds_dwordx4 v[212:213], off
	v_lshl_add_u64 v[212:213], s[62:63], 0, v[128:129]
	s_mov_b32 m0, s31
	s_nop 0
	global_load_lds_dwordx4 v[212:213], off
	s_mov_b32 m0, s64
	s_nop 0
	global_load_lds_dwordx4 v[214:215], off
	s_waitcnt vmcnt(8)
	s_waitcnt lgkmcnt(0)
	s_barrier
	s_setprio 1
	v_mfma_f32_16x16x32_bf16 v[60:63], v[136:139], v[168:171], v[60:63]
	v_mfma_f32_16x16x32_bf16 v[56:59], v[144:147], v[168:171], v[56:59]
	v_mfma_f32_16x16x32_bf16 v[52:55], v[136:139], v[186:189], v[52:55]
	v_mfma_f32_16x16x32_bf16 v[48:51], v[144:147], v[186:189], v[48:51]
	v_mfma_f32_16x16x32_bf16 v[40:43], v[136:139], v[194:197], v[40:43]
	v_mfma_f32_16x16x32_bf16 v[32:35], v[144:147], v[194:197], v[32:35]
	v_mfma_f32_16x16x32_bf16 v[24:27], v[136:139], v[202:205], v[24:27]
	v_mfma_f32_16x16x32_bf16 v[16:19], v[144:147], v[202:205], v[16:19]
	v_mfma_f32_16x16x32_bf16 v[60:63], v[140:143], v[172:175], v[60:63]
	v_mfma_f32_16x16x32_bf16 v[56:59], v[148:151], v[172:175], v[56:59]
	v_mfma_f32_16x16x32_bf16 v[52:55], v[140:143], v[190:193], v[52:55]
	v_mfma_f32_16x16x32_bf16 v[48:51], v[148:151], v[190:193], v[48:51]
	v_mfma_f32_16x16x32_bf16 v[40:43], v[140:143], v[198:201], v[40:43]
	v_mfma_f32_16x16x32_bf16 v[32:35], v[148:151], v[198:201], v[32:35]
	v_mfma_f32_16x16x32_bf16 v[24:27], v[140:143], v[206:209], v[24:27]
	v_mfma_f32_16x16x32_bf16 v[16:19], v[148:151], v[206:209], v[16:19]
	v_mfma_f32_16x16x32_bf16 v[44:47], v[152:155], v[168:171], v[44:47]
	v_mfma_f32_16x16x32_bf16 v[36:39], v[160:163], v[168:171], v[36:39]
	v_mfma_f32_16x16x32_bf16 v[28:31], v[152:155], v[186:189], v[28:31]
	v_mfma_f32_16x16x32_bf16 v[20:23], v[160:163], v[186:189], v[20:23]
	v_mfma_f32_16x16x32_bf16 v[12:15], v[152:155], v[194:197], v[12:15]
	v_mfma_f32_16x16x32_bf16 v[8:11], v[160:163], v[194:197], v[8:11]
	v_mfma_f32_16x16x32_bf16 v[4:7], v[152:155], v[202:205], v[4:7]
	v_mfma_f32_16x16x32_bf16 v[0:3], v[160:163], v[202:205], v[0:3]
	v_mfma_f32_16x16x32_bf16 v[44:47], v[156:159], v[172:175], v[44:47]
	v_mfma_f32_16x16x32_bf16 v[36:39], v[164:167], v[172:175], v[36:39]
	v_mfma_f32_16x16x32_bf16 v[28:31], v[156:159], v[190:193], v[28:31]
	v_mfma_f32_16x16x32_bf16 v[20:23], v[164:167], v[190:193], v[20:23]
	v_mfma_f32_16x16x32_bf16 v[12:15], v[156:159], v[198:201], v[12:15]
	v_mfma_f32_16x16x32_bf16 v[8:11], v[164:167], v[198:201], v[8:11]
	v_mfma_f32_16x16x32_bf16 v[4:7], v[156:159], v[206:209], v[4:7]
	v_mfma_f32_16x16x32_bf16 v[0:3], v[164:167], v[206:209], v[0:3]
	s_setprio 0
	s_barrier
	s_add_i32 s5, 0, 0x18000
	v_add_u32_e32 v132, s5, v182
	s_add_i32 s8, 0, 0x1c000
	ds_read_b128 v[136:139], v132
	ds_read_b128 v[140:143], v132 offset:1024
	ds_read_b128 v[144:147], v132 offset:2048
	ds_read_b128 v[148:151], v132 offset:3072
	v_add_u32_e32 v132, s8, v182
	ds_read_b128 v[152:155], v132
	ds_read_b128 v[156:159], v132 offset:1024
	ds_read_b128 v[160:163], v132 offset:2048
	ds_read_b128 v[164:167], v132 offset:3072
	s_add_u32 s6, s62, 0x100000
	s_addc_u32 s7, s63, 0
	s_mov_b32 m0, s65
	v_lshl_add_u64 v[216:217], s[6:7], 0, v[128:129]
	ds_read_b128 v[168:171], v185 offset:32768
	ds_read_b128 v[172:175], v185 offset:33792
	ds_read_b128 v[186:189], v185 offset:34816
	ds_read_b128 v[190:193], v185 offset:35840
	ds_read_b128 v[194:197], v185 offset:36864
	ds_read_b128 v[198:201], v185 offset:37888
	ds_read_b128 v[202:205], v185 offset:38912
	ds_read_b128 v[206:209], v185 offset:39936
	global_load_lds_dwordx4 v[216:217], off
	v_lshl_add_u64 v[216:217], s[6:7], 0, v[130:131]
	s_mov_b32 m0, s66
	s_nop 0
	global_load_lds_dwordx4 v[216:217], off
	s_waitcnt vmcnt(8)
	s_waitcnt lgkmcnt(0)
	s_barrier
	s_setprio 1
	v_mfma_f32_16x16x32_bf16 v[124:127], v[136:139], v[168:171], v[124:127]
	v_mfma_f32_16x16x32_bf16 v[120:123], v[144:147], v[168:171], v[120:123]
	v_mfma_f32_16x16x32_bf16 v[116:119], v[136:139], v[186:189], v[116:119]
	v_mfma_f32_16x16x32_bf16 v[112:115], v[144:147], v[186:189], v[112:115]
	v_mfma_f32_16x16x32_bf16 v[104:107], v[136:139], v[194:197], v[104:107]
	v_mfma_f32_16x16x32_bf16 v[96:99], v[144:147], v[194:197], v[96:99]
	v_mfma_f32_16x16x32_bf16 v[88:91], v[136:139], v[202:205], v[88:91]
	v_mfma_f32_16x16x32_bf16 v[80:83], v[144:147], v[202:205], v[80:83]
	v_mfma_f32_16x16x32_bf16 v[124:127], v[140:143], v[172:175], v[124:127]
	v_mfma_f32_16x16x32_bf16 v[120:123], v[148:151], v[172:175], v[120:123]
	v_mfma_f32_16x16x32_bf16 v[116:119], v[140:143], v[190:193], v[116:119]
	v_mfma_f32_16x16x32_bf16 v[112:115], v[148:151], v[190:193], v[112:115]
	v_mfma_f32_16x16x32_bf16 v[104:107], v[140:143], v[198:201], v[104:107]
	v_mfma_f32_16x16x32_bf16 v[96:99], v[148:151], v[198:201], v[96:99]
	v_mfma_f32_16x16x32_bf16 v[88:91], v[140:143], v[206:209], v[88:91]
	v_mfma_f32_16x16x32_bf16 v[80:83], v[148:151], v[206:209], v[80:83]
	v_mfma_f32_16x16x32_bf16 v[108:111], v[152:155], v[168:171], v[108:111]
	v_mfma_f32_16x16x32_bf16 v[100:103], v[160:163], v[168:171], v[100:103]
	v_mfma_f32_16x16x32_bf16 v[92:95], v[152:155], v[186:189], v[92:95]
	v_mfma_f32_16x16x32_bf16 v[84:87], v[160:163], v[186:189], v[84:87]
	v_mfma_f32_16x16x32_bf16 v[76:79], v[152:155], v[194:197], v[76:79]
	v_mfma_f32_16x16x32_bf16 v[72:75], v[160:163], v[194:197], v[72:75]
	v_mfma_f32_16x16x32_bf16 v[68:71], v[152:155], v[202:205], v[68:71]
	v_mfma_f32_16x16x32_bf16 v[64:67], v[160:163], v[202:205], v[64:67]
	v_mfma_f32_16x16x32_bf16 v[108:111], v[156:159], v[172:175], v[108:111]
	v_mfma_f32_16x16x32_bf16 v[100:103], v[164:167], v[172:175], v[100:103]
	v_mfma_f32_16x16x32_bf16 v[92:95], v[156:159], v[190:193], v[92:95]
	v_mfma_f32_16x16x32_bf16 v[84:87], v[164:167], v[190:193], v[84:87]
	v_mfma_f32_16x16x32_bf16 v[76:79], v[156:159], v[198:201], v[76:79]
	v_mfma_f32_16x16x32_bf16 v[72:75], v[164:167], v[198:201], v[72:75]
	v_mfma_f32_16x16x32_bf16 v[68:71], v[156:159], v[206:209], v[68:71]
	v_mfma_f32_16x16x32_bf16 v[64:67], v[164:167], v[206:209], v[64:67]
	s_setprio 0
	s_barrier
	s_add_i32 s5, s5, s30
	v_lshl_add_u64 v[176:177], v[176:177], 0, s[14:15]
	s_mov_b32 m0, s5
	ds_read_b128 v[168:171], v185 offset:49152
	ds_read_b128 v[172:175], v185 offset:50176
	ds_read_b128 v[186:189], v185 offset:51200
	ds_read_b128 v[190:193], v185 offset:52224
	ds_read_b128 v[194:197], v185 offset:53248
	ds_read_b128 v[198:201], v185 offset:54272
	ds_read_b128 v[202:205], v185 offset:55296
	ds_read_b128 v[206:209], v185 offset:56320
	global_load_lds_dwordx4 v[176:177], off
	s_add_i32 m0, s5, 0x2000
	s_add_u32 s6, s60, 0x100080
	v_lshl_add_u64 v[176:177], v[210:211], 0, s[14:15]
	s_addc_u32 s7, s61, 0
	s_add_i32 s5, s8, s30
	global_load_lds_dwordx4 v[176:177], off
	v_lshl_add_u64 v[176:177], s[6:7], 0, v[128:129]
	s_mov_b32 m0, s5
	s_nop 0
	global_load_lds_dwordx4 v[176:177], off
	v_lshl_add_u64 v[176:177], s[6:7], 0, v[130:131]
	s_add_i32 m0, s5, 0x2000
	s_nop 0
	global_load_lds_dwordx4 v[176:177], off
	v_lshl_add_u64 v[176:177], v[212:213], 0, s[14:15]
	s_mov_b32 m0, s70
	s_nop 0
	global_load_lds_dwordx4 v[176:177], off
	v_lshl_add_u64 v[176:177], v[214:215], 0, s[14:15]
	s_mov_b32 m0, s71
	s_nop 0
	global_load_lds_dwordx4 v[176:177], off
	s_waitcnt vmcnt(8)
	s_waitcnt lgkmcnt(0)
	s_barrier
	s_setprio 1
	v_mfma_f32_16x16x32_bf16 v[60:63], v[136:139], v[168:171], v[60:63]
	v_mfma_f32_16x16x32_bf16 v[56:59], v[144:147], v[168:171], v[56:59]
	v_mfma_f32_16x16x32_bf16 v[52:55], v[136:139], v[186:189], v[52:55]
	v_mfma_f32_16x16x32_bf16 v[48:51], v[144:147], v[186:189], v[48:51]
	v_mfma_f32_16x16x32_bf16 v[40:43], v[136:139], v[194:197], v[40:43]
	v_mfma_f32_16x16x32_bf16 v[32:35], v[144:147], v[194:197], v[32:35]
	v_mfma_f32_16x16x32_bf16 v[24:27], v[136:139], v[202:205], v[24:27]
	v_mfma_f32_16x16x32_bf16 v[16:19], v[144:147], v[202:205], v[16:19]
	v_mfma_f32_16x16x32_bf16 v[60:63], v[140:143], v[172:175], v[60:63]
	v_mfma_f32_16x16x32_bf16 v[56:59], v[148:151], v[172:175], v[56:59]
	v_mfma_f32_16x16x32_bf16 v[52:55], v[140:143], v[190:193], v[52:55]
	v_mfma_f32_16x16x32_bf16 v[48:51], v[148:151], v[190:193], v[48:51]
	v_mfma_f32_16x16x32_bf16 v[40:43], v[140:143], v[198:201], v[40:43]
	v_mfma_f32_16x16x32_bf16 v[32:35], v[148:151], v[198:201], v[32:35]
	v_mfma_f32_16x16x32_bf16 v[24:27], v[140:143], v[206:209], v[24:27]
	v_mfma_f32_16x16x32_bf16 v[16:19], v[148:151], v[206:209], v[16:19]
	v_mfma_f32_16x16x32_bf16 v[44:47], v[152:155], v[168:171], v[44:47]
	v_mfma_f32_16x16x32_bf16 v[36:39], v[160:163], v[168:171], v[36:39]
	v_mfma_f32_16x16x32_bf16 v[28:31], v[152:155], v[186:189], v[28:31]
	v_mfma_f32_16x16x32_bf16 v[20:23], v[160:163], v[186:189], v[20:23]
	v_mfma_f32_16x16x32_bf16 v[12:15], v[152:155], v[194:197], v[12:15]
	v_mfma_f32_16x16x32_bf16 v[8:11], v[160:163], v[194:197], v[8:11]
	v_mfma_f32_16x16x32_bf16 v[4:7], v[152:155], v[202:205], v[4:7]
	v_mfma_f32_16x16x32_bf16 v[0:3], v[160:163], v[202:205], v[0:3]
	v_mfma_f32_16x16x32_bf16 v[44:47], v[156:159], v[172:175], v[44:47]
	v_mfma_f32_16x16x32_bf16 v[36:39], v[164:167], v[172:175], v[36:39]
	v_mfma_f32_16x16x32_bf16 v[28:31], v[156:159], v[190:193], v[28:31]
	v_mfma_f32_16x16x32_bf16 v[20:23], v[164:167], v[190:193], v[20:23]
	v_mfma_f32_16x16x32_bf16 v[12:15], v[156:159], v[198:201], v[12:15]
	v_mfma_f32_16x16x32_bf16 v[8:11], v[164:167], v[198:201], v[8:11]
	v_mfma_f32_16x16x32_bf16 v[4:7], v[156:159], v[206:209], v[4:7]
	v_mfma_f32_16x16x32_bf16 v[0:3], v[164:167], v[206:209], v[0:3]
	s_setprio 0
	s_barrier
	s_add_i32 s4, s4, 2
	s_add_u32 s58, s58, 0x100
	s_addc_u32 s59, s59, 0
	s_cmp_ge_i32 s4, s67
	s_cbranch_scc0 .LBB0_1479
	v_pk_add_f32 v[160:161], v[126:127], 0 op_sel_hi:[1,0]
	v_pk_add_f32 v[162:163], v[124:125], 0 op_sel_hi:[1,0]
	v_pk_add_f32 v[158:159], v[122:123], 0 op_sel_hi:[1,0]
	v_pk_add_f32 v[156:157], v[120:121], 0 op_sel_hi:[1,0]
	v_pk_add_f32 v[170:171], v[110:111], 0 op_sel_hi:[1,0]
	v_pk_add_f32 v[168:169], v[108:109], 0 op_sel_hi:[1,0]
	v_pk_add_f32 v[166:167], v[102:103], 0 op_sel_hi:[1,0]
	v_pk_add_f32 v[164:165], v[100:101], 0 op_sel_hi:[1,0]
	v_pk_add_f32 v[138:139], v[118:119], 0 op_sel_hi:[1,0]
	v_pk_add_f32 v[140:141], v[116:117], 0 op_sel_hi:[1,0]
	v_pk_add_f32 v[142:143], v[114:115], 0 op_sel_hi:[1,0]
	v_pk_add_f32 v[144:145], v[112:113], 0 op_sel_hi:[1,0]
	v_pk_add_f32 v[146:147], v[94:95], 0 op_sel_hi:[1,0]
	v_pk_add_f32 v[148:149], v[92:93], 0 op_sel_hi:[1,0]
	v_pk_add_f32 v[150:151], v[86:87], 0 op_sel_hi:[1,0]
	v_pk_add_f32 v[152:153], v[84:85], 0 op_sel_hi:[1,0]
	v_pk_add_f32 v[120:121], v[106:107], 0 op_sel_hi:[1,0]
	v_pk_add_f32 v[118:119], v[104:105], 0 op_sel_hi:[1,0]
	v_pk_add_f32 v[114:115], v[98:99], 0 op_sel_hi:[1,0]
	v_pk_add_f32 v[112:113], v[96:97], 0 op_sel_hi:[1,0]
	v_pk_add_f32 v[136:137], v[78:79], 0 op_sel_hi:[1,0]
	v_pk_add_f32 v[126:127], v[76:77], 0 op_sel_hi:[1,0]
	v_pk_add_f32 v[124:125], v[74:75], 0 op_sel_hi:[1,0]
	v_pk_add_f32 v[122:123], v[72:73], 0 op_sel_hi:[1,0]
	v_pk_add_f32 v[96:97], v[90:91], 0 op_sel_hi:[1,0]
	v_pk_add_f32 v[98:99], v[88:89], 0 op_sel_hi:[1,0]
	v_pk_add_f32 v[100:101], v[82:83], 0 op_sel_hi:[1,0]
	v_pk_add_f32 v[102:103], v[80:81], 0 op_sel_hi:[1,0]
	v_pk_add_f32 v[104:105], v[70:71], 0 op_sel_hi:[1,0]
	v_pk_add_f32 v[106:107], v[68:69], 0 op_sel_hi:[1,0]
	v_pk_add_f32 v[108:109], v[66:67], 0 op_sel_hi:[1,0]
	v_pk_add_f32 v[110:111], v[64:65], 0 op_sel_hi:[1,0]
	v_pk_add_f32 v[86:87], v[62:63], 0 op_sel_hi:[1,0]
	v_pk_add_f32 v[84:85], v[60:61], 0 op_sel_hi:[1,0]
	v_pk_add_f32 v[82:83], v[58:59], 0 op_sel_hi:[1,0]
	v_pk_add_f32 v[80:81], v[56:57], 0 op_sel_hi:[1,0]
	v_pk_add_f32 v[94:95], v[46:47], 0 op_sel_hi:[1,0]
	v_pk_add_f32 v[92:93], v[44:45], 0 op_sel_hi:[1,0]
	v_pk_add_f32 v[90:91], v[38:39], 0 op_sel_hi:[1,0]
	v_pk_add_f32 v[88:89], v[36:37], 0 op_sel_hi:[1,0]
	v_pk_add_f32 v[64:65], v[54:55], 0 op_sel_hi:[1,0]
	v_pk_add_f32 v[66:67], v[52:53], 0 op_sel_hi:[1,0]
	v_pk_add_f32 v[68:69], v[50:51], 0 op_sel_hi:[1,0]
	v_pk_add_f32 v[70:71], v[48:49], 0 op_sel_hi:[1,0]
	v_pk_add_f32 v[72:73], v[30:31], 0 op_sel_hi:[1,0]
	v_pk_add_f32 v[74:75], v[28:29], 0 op_sel_hi:[1,0]
	v_pk_add_f32 v[76:77], v[22:23], 0 op_sel_hi:[1,0]
	v_pk_add_f32 v[78:79], v[20:21], 0 op_sel_hi:[1,0]
	v_pk_add_f32 v[54:55], v[42:43], 0 op_sel_hi:[1,0]
	v_pk_add_f32 v[52:53], v[40:41], 0 op_sel_hi:[1,0]
	v_pk_add_f32 v[50:51], v[34:35], 0 op_sel_hi:[1,0]
	v_pk_add_f32 v[48:49], v[32:33], 0 op_sel_hi:[1,0]
	v_pk_add_f32 v[62:63], v[14:15], 0 op_sel_hi:[1,0]
	v_pk_add_f32 v[60:61], v[12:13], 0 op_sel_hi:[1,0]
	v_pk_add_f32 v[58:59], v[10:11], 0 op_sel_hi:[1,0]
	v_pk_add_f32 v[56:57], v[8:9], 0 op_sel_hi:[1,0]
	v_pk_add_f32 v[32:33], v[26:27], 0 op_sel_hi:[1,0]
	v_pk_add_f32 v[34:35], v[24:25], 0 op_sel_hi:[1,0]
	v_pk_add_f32 v[36:37], v[18:19], 0 op_sel_hi:[1,0]
	v_pk_add_f32 v[38:39], v[16:17], 0 op_sel_hi:[1,0]
	v_pk_add_f32 v[40:41], v[6:7], 0 op_sel_hi:[1,0]
	v_pk_add_f32 v[42:43], v[4:5], 0 op_sel_hi:[1,0]
	v_pk_add_f32 v[44:45], v[2:3], 0 op_sel_hi:[1,0]
	v_pk_add_f32 v[46:47], v[0:1], 0 op_sel_hi:[1,0]

.LBB0_1511:
	s_mov_b64 s[34:35], s[16:17]
	ds_read_b128 v[140:143], v134
	ds_read_b128 v[144:147], v134 offset:1024
	ds_read_b128 v[148:151], v134 offset:2048
	ds_read_b128 v[152:155], v134 offset:3072
	ds_read_b128 v[156:159], v135
	ds_read_b128 v[160:163], v135 offset:1024
	ds_read_b128 v[164:167], v135 offset:2048
	ds_read_b128 v[168:171], v135 offset:3072
	s_add_u32 s48, s0, s34
	s_addc_u32 s49, s1, s35
	s_add_u32 s36, s48, 0x100
	s_addc_u32 s37, s49, 0
	s_add_u32 s34, s2, s34
	s_addc_u32 s35, s3, s35
	s_add_u32 s34, s34, 0x100
	s_addc_u32 s35, s35, 0
	s_cmp_eq_u32 s38, s39
	s_cselect_b32 s37, s13, s37
	s_cselect_b32 s36, s12, s36
	s_cselect_b32 s35, s15, s35
	s_cselect_b32 s34, s14, s34
	s_add_u32 s48, s48, 0x100080
	s_addc_u32 s49, s49, 0
	s_mov_b32 m0, s40
	v_lshl_add_u64 v[206:207], s[48:49], 0, v[128:129]
	ds_read_b128 v[172:175], v136
	ds_read_b128 v[176:179], v136 offset:1024
	ds_read_b128 v[182:185], v136 offset:2048
	ds_read_b128 v[186:189], v136 offset:3072
	ds_read_b128 v[190:193], v136 offset:4096
	ds_read_b128 v[194:197], v136 offset:5120
	ds_read_b128 v[198:201], v136 offset:6144
	ds_read_b128 v[202:205], v136 offset:7168
	global_load_lds_dwordx4 v[206:207], off
	v_lshl_add_u64 v[206:207], s[48:49], 0, v[130:131]
	s_mov_b32 m0, s41
	s_nop 0
	global_load_lds_dwordx4 v[206:207], off
	s_waitcnt vmcnt(8)
	s_waitcnt lgkmcnt(0)
	s_barrier
	s_setprio 1
	v_mfma_f32_16x16x32_bf16 v[124:127], v[140:143], v[172:175], v[124:127]
	v_mfma_f32_16x16x32_bf16 v[120:123], v[148:151], v[172:175], v[120:123]
	v_mfma_f32_16x16x32_bf16 v[108:111], v[140:143], v[182:185], v[108:111]
	v_mfma_f32_16x16x32_bf16 v[104:107], v[148:151], v[182:185], v[104:107]
	v_mfma_f32_16x16x32_bf16 v[92:95], v[140:143], v[190:193], v[92:95]
	v_mfma_f32_16x16x32_bf16 v[88:91], v[148:151], v[190:193], v[88:91]
	v_mfma_f32_16x16x32_bf16 v[76:79], v[140:143], v[198:201], v[76:79]
	v_mfma_f32_16x16x32_bf16 v[72:75], v[148:151], v[198:201], v[72:75]
	v_mfma_f32_16x16x32_bf16 v[124:127], v[144:147], v[176:179], v[124:127]
	v_mfma_f32_16x16x32_bf16 v[120:123], v[152:155], v[176:179], v[120:123]
	v_mfma_f32_16x16x32_bf16 v[108:111], v[144:147], v[186:189], v[108:111]
	v_mfma_f32_16x16x32_bf16 v[104:107], v[152:155], v[186:189], v[104:107]
	v_mfma_f32_16x16x32_bf16 v[92:95], v[144:147], v[194:197], v[92:95]
	v_mfma_f32_16x16x32_bf16 v[88:91], v[152:155], v[194:197], v[88:91]
	v_mfma_f32_16x16x32_bf16 v[76:79], v[144:147], v[202:205], v[76:79]
	v_mfma_f32_16x16x32_bf16 v[72:75], v[152:155], v[202:205], v[72:75]
	v_mfma_f32_16x16x32_bf16 v[116:119], v[156:159], v[172:175], v[116:119]
	v_mfma_f32_16x16x32_bf16 v[112:115], v[164:167], v[172:175], v[112:115]
	v_mfma_f32_16x16x32_bf16 v[100:103], v[156:159], v[182:185], v[100:103]
	v_mfma_f32_16x16x32_bf16 v[96:99], v[164:167], v[182:185], v[96:99]
	v_mfma_f32_16x16x32_bf16 v[84:87], v[156:159], v[190:193], v[84:87]
	v_mfma_f32_16x16x32_bf16 v[80:83], v[164:167], v[190:193], v[80:83]
	v_mfma_f32_16x16x32_bf16 v[68:71], v[156:159], v[198:201], v[68:71]
	v_mfma_f32_16x16x32_bf16 v[64:67], v[164:167], v[198:201], v[64:67]
	v_mfma_f32_16x16x32_bf16 v[116:119], v[160:163], v[176:179], v[116:119]
	v_mfma_f32_16x16x32_bf16 v[112:115], v[168:171], v[176:179], v[112:115]
	v_mfma_f32_16x16x32_bf16 v[100:103], v[160:163], v[186:189], v[100:103]
	v_mfma_f32_16x16x32_bf16 v[96:99], v[168:171], v[186:189], v[96:99]
	v_mfma_f32_16x16x32_bf16 v[84:87], v[160:163], v[194:197], v[84:87]
	v_mfma_f32_16x16x32_bf16 v[80:83], v[168:171], v[194:197], v[80:83]
	v_mfma_f32_16x16x32_bf16 v[68:71], v[160:163], v[202:205], v[68:71]
	v_mfma_f32_16x16x32_bf16 v[64:67], v[168:171], v[202:205], v[64:67]
	s_setprio 0
	s_barrier
	s_mov_b32 m0, s42
	v_lshl_add_u64 v[206:207], s[34:35], 0, v[128:129]
	s_add_u32 s48, s34, 0x100000
	ds_read_b128 v[172:175], v136 offset:16384
	ds_read_b128 v[176:179], v136 offset:17408
	ds_read_b128 v[182:185], v136 offset:18432
	ds_read_b128 v[186:189], v136 offset:19456
	ds_read_b128 v[190:193], v136 offset:20480
	ds_read_b128 v[194:197], v136 offset:21504
	ds_read_b128 v[198:201], v136 offset:22528
	ds_read_b128 v[202:205], v136 offset:23552
	global_load_lds_dwordx4 v[206:207], off
	v_lshl_add_u64 v[208:209], s[34:35], 0, v[130:131]
	s_mov_b32 m0, s43
	s_addc_u32 s49, s35, 0
	global_load_lds_dwordx4 v[208:209], off
	v_lshl_add_u64 v[210:211], s[48:49], 0, v[128:129]
	s_mov_b32 m0, s44
	v_lshl_add_u64 v[212:213], s[36:37], 0, v[130:131]
	global_load_lds_dwordx4 v[210:211], off
	v_lshl_add_u64 v[210:211], s[48:49], 0, v[130:131]
	s_mov_b32 m0, s45
	s_nop 0
	global_load_lds_dwordx4 v[210:211], off
	v_lshl_add_u64 v[210:211], s[36:37], 0, v[128:129]
	s_mov_b32 m0, s8
	s_nop 0
	global_load_lds_dwordx4 v[210:211], off
	s_mov_b32 m0, s9
	s_nop 0
	global_load_lds_dwordx4 v[212:213], off
	s_waitcnt vmcnt(8)
	s_waitcnt lgkmcnt(0)
	s_barrier
	s_setprio 1
	v_mfma_f32_16x16x32_bf16 v[60:63], v[140:143], v[172:175], v[60:63]
	v_mfma_f32_16x16x32_bf16 v[56:59], v[148:151], v[172:175], v[56:59]
	v_mfma_f32_16x16x32_bf16 v[44:47], v[140:143], v[182:185], v[44:47]
	v_mfma_f32_16x16x32_bf16 v[40:43], v[148:151], v[182:185], v[40:43]
	v_mfma_f32_16x16x32_bf16 v[28:31], v[140:143], v[190:193], v[28:31]
	v_mfma_f32_16x16x32_bf16 v[24:27], v[148:151], v[190:193], v[24:27]
	v_mfma_f32_16x16x32_bf16 v[12:15], v[140:143], v[198:201], v[12:15]
	v_mfma_f32_16x16x32_bf16 v[8:11], v[148:151], v[198:201], v[8:11]
	v_mfma_f32_16x16x32_bf16 v[60:63], v[144:147], v[176:179], v[60:63]
	v_mfma_f32_16x16x32_bf16 v[56:59], v[152:155], v[176:179], v[56:59]
	v_mfma_f32_16x16x32_bf16 v[44:47], v[144:147], v[186:189], v[44:47]
	v_mfma_f32_16x16x32_bf16 v[40:43], v[152:155], v[186:189], v[40:43]
	v_mfma_f32_16x16x32_bf16 v[28:31], v[144:147], v[194:197], v[28:31]
	v_mfma_f32_16x16x32_bf16 v[24:27], v[152:155], v[194:197], v[24:27]
	v_mfma_f32_16x16x32_bf16 v[12:15], v[144:147], v[202:205], v[12:15]
	v_mfma_f32_16x16x32_bf16 v[8:11], v[152:155], v[202:205], v[8:11]
	v_mfma_f32_16x16x32_bf16 v[52:55], v[156:159], v[172:175], v[52:55]
	v_mfma_f32_16x16x32_bf16 v[48:51], v[164:167], v[172:175], v[48:51]
	v_mfma_f32_16x16x32_bf16 v[36:39], v[156:159], v[182:185], v[36:39]
	v_mfma_f32_16x16x32_bf16 v[32:35], v[164:167], v[182:185], v[32:35]
	v_mfma_f32_16x16x32_bf16 v[20:23], v[156:159], v[190:193], v[20:23]
	v_mfma_f32_16x16x32_bf16 v[16:19], v[164:167], v[190:193], v[16:19]
	v_mfma_f32_16x16x32_bf16 v[4:7], v[156:159], v[198:201], v[4:7]
	v_mfma_f32_16x16x32_bf16 v[0:3], v[164:167], v[198:201], v[0:3]
	v_mfma_f32_16x16x32_bf16 v[52:55], v[160:163], v[176:179], v[52:55]
	v_mfma_f32_16x16x32_bf16 v[48:51], v[168:171], v[176:179], v[48:51]
	v_mfma_f32_16x16x32_bf16 v[36:39], v[160:163], v[186:189], v[36:39]
	v_mfma_f32_16x16x32_bf16 v[32:35], v[168:171], v[186:189], v[32:35]
	v_mfma_f32_16x16x32_bf16 v[20:23], v[160:163], v[194:197], v[20:23]
	v_mfma_f32_16x16x32_bf16 v[16:19], v[168:171], v[194:197], v[16:19]
	v_mfma_f32_16x16x32_bf16 v[4:7], v[160:163], v[202:205], v[4:7]
	v_mfma_f32_16x16x32_bf16 v[0:3], v[168:171], v[202:205], v[0:3]
	s_setprio 0
	s_barrier
	ds_read_b128 v[140:143], v137
	ds_read_b128 v[144:147], v137 offset:1024
	ds_read_b128 v[148:151], v137 offset:2048
	ds_read_b128 v[152:155], v137 offset:3072
	ds_read_b128 v[156:159], v138
	ds_read_b128 v[160:163], v138 offset:1024
	ds_read_b128 v[164:167], v138 offset:2048
	ds_read_b128 v[168:171], v138 offset:3072
	s_add_u32 s36, s36, 0x100000
	s_addc_u32 s37, s37, 0
	s_mov_b32 m0, s23
	v_lshl_add_u64 v[214:215], s[36:37], 0, v[128:129]
	ds_read_b128 v[172:175], v136 offset:32768
	ds_read_b128 v[176:179], v136 offset:33792
	ds_read_b128 v[182:185], v136 offset:34816
	ds_read_b128 v[186:189], v136 offset:35840
	ds_read_b128 v[190:193], v136 offset:36864
	ds_read_b128 v[194:197], v136 offset:37888
	ds_read_b128 v[198:201], v136 offset:38912
	ds_read_b128 v[202:205], v136 offset:39936
	global_load_lds_dwordx4 v[214:215], off
	v_lshl_add_u64 v[214:215], s[36:37], 0, v[130:131]
	s_mov_b32 m0, s28
	s_nop 0
	global_load_lds_dwordx4 v[214:215], off
	s_waitcnt vmcnt(8)
	s_waitcnt lgkmcnt(0)
	s_barrier
	s_setprio 1
	v_mfma_f32_16x16x32_bf16 v[124:127], v[140:143], v[172:175], v[124:127]
	v_mfma_f32_16x16x32_bf16 v[120:123], v[148:151], v[172:175], v[120:123]
	v_mfma_f32_16x16x32_bf16 v[108:111], v[140:143], v[182:185], v[108:111]
	v_mfma_f32_16x16x32_bf16 v[104:107], v[148:151], v[182:185], v[104:107]
	v_mfma_f32_16x16x32_bf16 v[92:95], v[140:143], v[190:193], v[92:95]
	v_mfma_f32_16x16x32_bf16 v[88:91], v[148:151], v[190:193], v[88:91]
	v_mfma_f32_16x16x32_bf16 v[76:79], v[140:143], v[198:201], v[76:79]
	v_mfma_f32_16x16x32_bf16 v[72:75], v[148:151], v[198:201], v[72:75]
	v_mfma_f32_16x16x32_bf16 v[124:127], v[144:147], v[176:179], v[124:127]
	v_mfma_f32_16x16x32_bf16 v[120:123], v[152:155], v[176:179], v[120:123]
	v_mfma_f32_16x16x32_bf16 v[108:111], v[144:147], v[186:189], v[108:111]
	v_mfma_f32_16x16x32_bf16 v[104:107], v[152:155], v[186:189], v[104:107]
	v_mfma_f32_16x16x32_bf16 v[92:95], v[144:147], v[194:197], v[92:95]
	v_mfma_f32_16x16x32_bf16 v[88:91], v[152:155], v[194:197], v[88:91]
	v_mfma_f32_16x16x32_bf16 v[76:79], v[144:147], v[202:205], v[76:79]
	v_mfma_f32_16x16x32_bf16 v[72:75], v[152:155], v[202:205], v[72:75]
	v_mfma_f32_16x16x32_bf16 v[116:119], v[156:159], v[172:175], v[116:119]
	v_mfma_f32_16x16x32_bf16 v[112:115], v[164:167], v[172:175], v[112:115]
	v_mfma_f32_16x16x32_bf16 v[100:103], v[156:159], v[182:185], v[100:103]
	v_mfma_f32_16x16x32_bf16 v[96:99], v[164:167], v[182:185], v[96:99]
	v_mfma_f32_16x16x32_bf16 v[84:87], v[156:159], v[190:193], v[84:87]
	v_mfma_f32_16x16x32_bf16 v[80:83], v[164:167], v[190:193], v[80:83]
	v_mfma_f32_16x16x32_bf16 v[68:71], v[156:159], v[198:201], v[68:71]
	v_mfma_f32_16x16x32_bf16 v[64:67], v[164:167], v[198:201], v[64:67]
	v_mfma_f32_16x16x32_bf16 v[116:119], v[160:163], v[176:179], v[116:119]
	v_mfma_f32_16x16x32_bf16 v[112:115], v[168:171], v[176:179], v[112:115]
	v_mfma_f32_16x16x32_bf16 v[100:103], v[160:163], v[186:189], v[100:103]
	v_mfma_f32_16x16x32_bf16 v[96:99], v[168:171], v[186:189], v[96:99]
	v_mfma_f32_16x16x32_bf16 v[84:87], v[160:163], v[194:197], v[84:87]
	v_mfma_f32_16x16x32_bf16 v[80:83], v[168:171], v[194:197], v[80:83]
	v_mfma_f32_16x16x32_bf16 v[68:71], v[160:163], v[202:205], v[68:71]
	v_mfma_f32_16x16x32_bf16 v[64:67], v[168:171], v[202:205], v[64:67]
	s_setprio 0
	s_barrier
	s_mov_b32 m0, s46
	v_lshl_add_u64 v[206:207], v[206:207], 0, s[10:11]
	s_add_u32 s34, s34, 0x100080
	ds_read_b128 v[172:175], v136 offset:49152
	ds_read_b128 v[176:179], v136 offset:50176
	ds_read_b128 v[182:185], v136 offset:51200
	ds_read_b128 v[186:189], v136 offset:52224
	ds_read_b128 v[190:193], v136 offset:53248
	ds_read_b128 v[194:197], v136 offset:54272
	ds_read_b128 v[198:201], v136 offset:55296
	ds_read_b128 v[202:205], v136 offset:56320
	global_load_lds_dwordx4 v[206:207], off
	v_lshl_add_u64 v[206:207], v[208:209], 0, s[10:11]
	s_mov_b32 m0, s47
	s_addc_u32 s35, s35, 0
	global_load_lds_dwordx4 v[206:207], off
	v_lshl_add_u64 v[206:207], s[34:35], 0, v[128:129]
	s_mov_b32 m0, s52
	s_nop 0
	global_load_lds_dwordx4 v[206:207], off
	v_lshl_add_u64 v[206:207], s[34:35], 0, v[130:131]
	s_mov_b32 m0, s53
	s_nop 0
	global_load_lds_dwordx4 v[206:207], off
	v_lshl_add_u64 v[206:207], v[210:211], 0, s[10:11]
	s_mov_b32 m0, s29
	s_nop 0
	global_load_lds_dwordx4 v[206:207], off
	v_lshl_add_u64 v[206:207], v[212:213], 0, s[10:11]
	s_mov_b32 m0, s30
	s_nop 0
	global_load_lds_dwordx4 v[206:207], off
	s_waitcnt vmcnt(8)
	s_waitcnt lgkmcnt(0)
	s_barrier
	s_setprio 1
	v_mfma_f32_16x16x32_bf16 v[60:63], v[140:143], v[172:175], v[60:63]
	v_mfma_f32_16x16x32_bf16 v[56:59], v[148:151], v[172:175], v[56:59]
	v_mfma_f32_16x16x32_bf16 v[44:47], v[140:143], v[182:185], v[44:47]
	v_mfma_f32_16x16x32_bf16 v[40:43], v[148:151], v[182:185], v[40:43]
	v_mfma_f32_16x16x32_bf16 v[28:31], v[140:143], v[190:193], v[28:31]
	v_mfma_f32_16x16x32_bf16 v[24:27], v[148:151], v[190:193], v[24:27]
	v_mfma_f32_16x16x32_bf16 v[12:15], v[140:143], v[198:201], v[12:15]
	v_mfma_f32_16x16x32_bf16 v[8:11], v[148:151], v[198:201], v[8:11]
	v_mfma_f32_16x16x32_bf16 v[60:63], v[144:147], v[176:179], v[60:63]
	v_mfma_f32_16x16x32_bf16 v[56:59], v[152:155], v[176:179], v[56:59]
	v_mfma_f32_16x16x32_bf16 v[44:47], v[144:147], v[186:189], v[44:47]
	v_mfma_f32_16x16x32_bf16 v[40:43], v[152:155], v[186:189], v[40:43]
	v_mfma_f32_16x16x32_bf16 v[28:31], v[144:147], v[194:197], v[28:31]
	v_mfma_f32_16x16x32_bf16 v[24:27], v[152:155], v[194:197], v[24:27]
	v_mfma_f32_16x16x32_bf16 v[12:15], v[144:147], v[202:205], v[12:15]
	v_mfma_f32_16x16x32_bf16 v[8:11], v[152:155], v[202:205], v[8:11]
	v_mfma_f32_16x16x32_bf16 v[52:55], v[156:159], v[172:175], v[52:55]
	v_mfma_f32_16x16x32_bf16 v[48:51], v[164:167], v[172:175], v[48:51]
	v_mfma_f32_16x16x32_bf16 v[36:39], v[156:159], v[182:185], v[36:39]
	v_mfma_f32_16x16x32_bf16 v[32:35], v[164:167], v[182:185], v[32:35]
	v_mfma_f32_16x16x32_bf16 v[20:23], v[156:159], v[190:193], v[20:23]
	v_mfma_f32_16x16x32_bf16 v[16:19], v[164:167], v[190:193], v[16:19]
	v_mfma_f32_16x16x32_bf16 v[4:7], v[156:159], v[198:201], v[4:7]
	v_mfma_f32_16x16x32_bf16 v[0:3], v[164:167], v[198:201], v[0:3]
	v_mfma_f32_16x16x32_bf16 v[52:55], v[160:163], v[176:179], v[52:55]
	v_mfma_f32_16x16x32_bf16 v[48:51], v[168:171], v[176:179], v[48:51]
	v_mfma_f32_16x16x32_bf16 v[36:39], v[160:163], v[186:189], v[36:39]
	v_mfma_f32_16x16x32_bf16 v[32:35], v[168:171], v[186:189], v[32:35]
	v_mfma_f32_16x16x32_bf16 v[20:23], v[160:163], v[194:197], v[20:23]
	v_mfma_f32_16x16x32_bf16 v[16:19], v[168:171], v[194:197], v[16:19]
	v_mfma_f32_16x16x32_bf16 v[4:7], v[160:163], v[202:205], v[4:7]
	v_mfma_f32_16x16x32_bf16 v[0:3], v[168:171], v[202:205], v[0:3]
	s_setprio 0
	s_barrier
	s_add_i32 s39, s39, 2
	s_add_u32 s16, s16, 0x100
	s_addc_u32 s17, s17, 0
	s_cmp_ge_i32 s39, s31
	s_cbranch_scc0 .LBB0_1511
	v_mov_b32_e32 v129, v127

.LBB0_1684:
	s_mov_b64 s[6:7], s[58:59]
	ds_read_b128 v[140:143], v147
	ds_read_b128 v[150:153], v147 offset:1024
	ds_read_b128 v[154:157], v147 offset:2048
	ds_read_b128 v[158:161], v147 offset:3072
	ds_read_b128 v[162:165], v148
	ds_read_b128 v[166:169], v148 offset:1024
	ds_read_b128 v[170:173], v148 offset:2048
	ds_read_b128 v[174:177], v148 offset:3072
	s_add_u32 s8, s54, s6
	s_addc_u32 s9, s55, s7
	s_add_u32 s28, s8, 0x100
	s_addc_u32 s29, s9, 0
	s_add_u32 s6, s56, s6
	s_addc_u32 s7, s57, s7
	s_add_u32 s6, s6, 0x100
	s_addc_u32 s7, s7, 0
	s_cmp_eq_u32 s71, s5
	s_cselect_b32 s63, s17, s29
	s_cselect_b32 s62, s16, s28
	s_cselect_b32 s61, s37, s7
	s_cselect_b32 s60, s36, s6
	s_add_u32 s6, s8, 0x80080
	s_addc_u32 s7, s9, 0
	v_lshl_add_u64 v[178:179], s[6:7], 0, v[134:135]
	s_add_i32 m0, s23, 0xc000
	ds_read_b128 v[182:185], v149
	ds_read_b128 v[186:189], v149 offset:1024
	ds_read_b128 v[190:193], v149 offset:2048
	ds_read_b128 v[194:197], v149 offset:3072
	ds_read_b128 v[198:201], v149 offset:4096
	ds_read_b128 v[202:205], v149 offset:5120
	ds_read_b128 v[206:209], v149 offset:6144
	ds_read_b128 v[210:213], v149 offset:7168
	global_load_lds_dwordx4 v[178:179], off
	v_lshl_add_u64 v[178:179], s[6:7], 0, v[130:131]
	s_add_i32 m0, s23, 0xe000
	s_nop 0
	global_load_lds_dwordx4 v[178:179], off
	s_waitcnt vmcnt(8)
	s_waitcnt lgkmcnt(0)
	s_barrier
	s_setprio 1
	v_mfma_f32_16x16x32_bf16 v[124:127], v[140:143], v[182:185], v[124:127]
	v_mfma_f32_16x16x32_bf16 v[116:119], v[154:157], v[182:185], v[116:119]
	v_mfma_f32_16x16x32_bf16 v[108:111], v[140:143], v[190:193], v[108:111]
	v_mfma_f32_16x16x32_bf16 v[100:103], v[154:157], v[190:193], v[100:103]
	v_mfma_f32_16x16x32_bf16 v[92:95], v[140:143], v[198:201], v[92:95]
	v_mfma_f32_16x16x32_bf16 v[84:87], v[154:157], v[198:201], v[84:87]
	v_mfma_f32_16x16x32_bf16 v[76:79], v[140:143], v[206:209], v[76:79]
	v_mfma_f32_16x16x32_bf16 v[68:71], v[154:157], v[206:209], v[68:71]
	v_mfma_f32_16x16x32_bf16 v[124:127], v[150:153], v[186:189], v[124:127]
	v_mfma_f32_16x16x32_bf16 v[116:119], v[158:161], v[186:189], v[116:119]
	v_mfma_f32_16x16x32_bf16 v[108:111], v[150:153], v[194:197], v[108:111]
	v_mfma_f32_16x16x32_bf16 v[100:103], v[158:161], v[194:197], v[100:103]
	v_mfma_f32_16x16x32_bf16 v[92:95], v[150:153], v[202:205], v[92:95]
	v_mfma_f32_16x16x32_bf16 v[84:87], v[158:161], v[202:205], v[84:87]
	v_mfma_f32_16x16x32_bf16 v[76:79], v[150:153], v[210:213], v[76:79]
	v_mfma_f32_16x16x32_bf16 v[68:71], v[158:161], v[210:213], v[68:71]
	v_mfma_f32_16x16x32_bf16 v[120:123], v[162:165], v[182:185], v[120:123]
	v_mfma_f32_16x16x32_bf16 v[112:115], v[170:173], v[182:185], v[112:115]
	v_mfma_f32_16x16x32_bf16 v[104:107], v[162:165], v[190:193], v[104:107]
	v_mfma_f32_16x16x32_bf16 v[96:99], v[170:173], v[190:193], v[96:99]
	v_mfma_f32_16x16x32_bf16 v[88:91], v[162:165], v[198:201], v[88:91]
	v_mfma_f32_16x16x32_bf16 v[80:83], v[170:173], v[198:201], v[80:83]
	v_mfma_f32_16x16x32_bf16 v[72:75], v[162:165], v[206:209], v[72:75]
	v_mfma_f32_16x16x32_bf16 v[64:67], v[170:173], v[206:209], v[64:67]
	v_mfma_f32_16x16x32_bf16 v[120:123], v[166:169], v[186:189], v[120:123]
	v_mfma_f32_16x16x32_bf16 v[112:115], v[174:177], v[186:189], v[112:115]
	v_mfma_f32_16x16x32_bf16 v[104:107], v[166:169], v[194:197], v[104:107]
	v_mfma_f32_16x16x32_bf16 v[96:99], v[174:177], v[194:197], v[96:99]
	v_mfma_f32_16x16x32_bf16 v[88:91], v[166:169], v[202:205], v[88:91]
	v_mfma_f32_16x16x32_bf16 v[80:83], v[174:177], v[202:205], v[80:83]
	v_mfma_f32_16x16x32_bf16 v[72:75], v[166:169], v[210:213], v[72:75]
	v_mfma_f32_16x16x32_bf16 v[64:67], v[174:177], v[210:213], v[64:67]
	s_setprio 0
	s_barrier
	s_add_i32 s6, s72, s18
	v_lshl_add_u64 v[178:179], s[60:61], 0, v[132:133]
	s_mov_b32 m0, s6
	ds_read_b128 v[182:185], v149 offset:16384
	ds_read_b128 v[186:189], v149 offset:17408
	ds_read_b128 v[190:193], v149 offset:18432
	ds_read_b128 v[194:197], v149 offset:19456
	ds_read_b128 v[198:201], v149 offset:20480
	ds_read_b128 v[202:205], v149 offset:21504
	ds_read_b128 v[206:209], v149 offset:22528
	ds_read_b128 v[210:213], v149 offset:23552
	global_load_lds_dwordx4 v[178:179], off
	s_add_i32 m0, s6, 0x2000
	s_add_u32 s6, s60, 0x80000
	v_lshl_add_u64 v[214:215], s[60:61], 0, v[128:129]
	s_addc_u32 s7, s61, 0
	s_add_i32 s8, s73, s18
	global_load_lds_dwordx4 v[214:215], off
	v_lshl_add_u64 v[216:217], s[6:7], 0, v[132:133]
	s_mov_b32 m0, s8
	v_lshl_add_u64 v[218:219], s[62:63], 0, v[130:131]
	global_load_lds_dwordx4 v[216:217], off
	v_lshl_add_u64 v[216:217], s[6:7], 0, v[128:129]
	s_add_i32 m0, s8, 0x2000
	s_nop 0
	global_load_lds_dwordx4 v[216:217], off
	v_lshl_add_u64 v[216:217], s[62:63], 0, v[134:135]
	s_mov_b32 m0, s23
	s_nop 0
	global_load_lds_dwordx4 v[216:217], off
	s_mov_b32 m0, s64
	s_nop 0
	global_load_lds_dwordx4 v[218:219], off
	s_waitcnt vmcnt(8)
	s_waitcnt lgkmcnt(0)
	s_barrier
	s_setprio 1
	v_mfma_f32_16x16x32_bf16 v[60:63], v[140:143], v[182:185], v[60:63]
	v_mfma_f32_16x16x32_bf16 v[52:55], v[154:157], v[182:185], v[52:55]
	v_mfma_f32_16x16x32_bf16 v[44:47], v[140:143], v[190:193], v[44:47]
	v_mfma_f32_16x16x32_bf16 v[36:39], v[154:157], v[190:193], v[36:39]
	v_mfma_f32_16x16x32_bf16 v[28:31], v[140:143], v[198:201], v[28:31]
	v_mfma_f32_16x16x32_bf16 v[20:23], v[154:157], v[198:201], v[20:23]
	v_mfma_f32_16x16x32_bf16 v[12:15], v[140:143], v[206:209], v[12:15]
	v_mfma_f32_16x16x32_bf16 v[4:7], v[154:157], v[206:209], v[4:7]
	v_mfma_f32_16x16x32_bf16 v[60:63], v[150:153], v[186:189], v[60:63]
	v_mfma_f32_16x16x32_bf16 v[52:55], v[158:161], v[186:189], v[52:55]
	v_mfma_f32_16x16x32_bf16 v[44:47], v[150:153], v[194:197], v[44:47]
	v_mfma_f32_16x16x32_bf16 v[36:39], v[158:161], v[194:197], v[36:39]
	v_mfma_f32_16x16x32_bf16 v[28:31], v[150:153], v[202:205], v[28:31]
	v_mfma_f32_16x16x32_bf16 v[20:23], v[158:161], v[202:205], v[20:23]
	v_mfma_f32_16x16x32_bf16 v[12:15], v[150:153], v[210:213], v[12:15]
	v_mfma_f32_16x16x32_bf16 v[4:7], v[158:161], v[210:213], v[4:7]
	v_mfma_f32_16x16x32_bf16 v[56:59], v[162:165], v[182:185], v[56:59]
	v_mfma_f32_16x16x32_bf16 v[48:51], v[170:173], v[182:185], v[48:51]
	v_mfma_f32_16x16x32_bf16 v[40:43], v[162:165], v[190:193], v[40:43]
	v_mfma_f32_16x16x32_bf16 v[32:35], v[170:173], v[190:193], v[32:35]
	v_mfma_f32_16x16x32_bf16 v[24:27], v[162:165], v[198:201], v[24:27]
	v_mfma_f32_16x16x32_bf16 v[16:19], v[170:173], v[198:201], v[16:19]
	v_mfma_f32_16x16x32_bf16 v[8:11], v[162:165], v[206:209], v[8:11]
	v_mfma_f32_16x16x32_bf16 v[0:3], v[170:173], v[206:209], v[0:3]
	v_mfma_f32_16x16x32_bf16 v[56:59], v[166:169], v[186:189], v[56:59]
	v_mfma_f32_16x16x32_bf16 v[48:51], v[174:177], v[186:189], v[48:51]
	v_mfma_f32_16x16x32_bf16 v[40:43], v[166:169], v[194:197], v[40:43]
	v_mfma_f32_16x16x32_bf16 v[32:35], v[174:177], v[194:197], v[32:35]
	v_mfma_f32_16x16x32_bf16 v[24:27], v[166:169], v[202:205], v[24:27]
	v_mfma_f32_16x16x32_bf16 v[16:19], v[174:177], v[202:205], v[16:19]
	v_mfma_f32_16x16x32_bf16 v[8:11], v[166:169], v[210:213], v[8:11]
	v_mfma_f32_16x16x32_bf16 v[0:3], v[174:177], v[210:213], v[0:3]
	s_setprio 0
	s_barrier
	s_add_i32 s8, 0, 0x18000
	s_add_i32 s9, 0, 0x1c000
	v_add_u32_e32 v158, s8, v146
	v_add_u32_e32 v174, s9, v146
	ds_read_b128 v[140:143], v158
	ds_read_b128 v[150:153], v158 offset:1024
	ds_read_b128 v[154:157], v158 offset:2048
	ds_read_b128 v[158:161], v158 offset:3072
	ds_read_b128 v[162:165], v174
	ds_read_b128 v[166:169], v174 offset:1024
	ds_read_b128 v[170:173], v174 offset:2048
	ds_read_b128 v[174:177], v174 offset:3072
	s_add_u32 s6, s62, 0x80000
	s_addc_u32 s7, s63, 0
	s_mov_b32 m0, s65
	v_lshl_add_u64 v[220:221], s[6:7], 0, v[134:135]
	ds_read_b128 v[182:185], v149 offset:32768
	ds_read_b128 v[186:189], v149 offset:33792
	ds_read_b128 v[190:193], v149 offset:34816
	ds_read_b128 v[194:197], v149 offset:35840
	ds_read_b128 v[198:201], v149 offset:36864
	ds_read_b128 v[202:205], v149 offset:37888
	ds_read_b128 v[206:209], v149 offset:38912
	ds_read_b128 v[210:213], v149 offset:39936
	global_load_lds_dwordx4 v[220:221], off
	v_lshl_add_u64 v[220:221], s[6:7], 0, v[130:131]
	s_mov_b32 m0, s66
	s_nop 0
	global_load_lds_dwordx4 v[220:221], off
	s_waitcnt vmcnt(8)
	s_waitcnt lgkmcnt(0)
	s_barrier
	s_setprio 1
	v_mfma_f32_16x16x32_bf16 v[124:127], v[140:143], v[182:185], v[124:127]
	v_mfma_f32_16x16x32_bf16 v[116:119], v[154:157], v[182:185], v[116:119]
	v_mfma_f32_16x16x32_bf16 v[108:111], v[140:143], v[190:193], v[108:111]
	v_mfma_f32_16x16x32_bf16 v[100:103], v[154:157], v[190:193], v[100:103]
	v_mfma_f32_16x16x32_bf16 v[92:95], v[140:143], v[198:201], v[92:95]
	v_mfma_f32_16x16x32_bf16 v[84:87], v[154:157], v[198:201], v[84:87]
	v_mfma_f32_16x16x32_bf16 v[76:79], v[140:143], v[206:209], v[76:79]
	v_mfma_f32_16x16x32_bf16 v[68:71], v[154:157], v[206:209], v[68:71]
	v_mfma_f32_16x16x32_bf16 v[124:127], v[150:153], v[186:189], v[124:127]
	v_mfma_f32_16x16x32_bf16 v[116:119], v[158:161], v[186:189], v[116:119]
	v_mfma_f32_16x16x32_bf16 v[108:111], v[150:153], v[194:197], v[108:111]
	v_mfma_f32_16x16x32_bf16 v[100:103], v[158:161], v[194:197], v[100:103]
	v_mfma_f32_16x16x32_bf16 v[92:95], v[150:153], v[202:205], v[92:95]
	v_mfma_f32_16x16x32_bf16 v[84:87], v[158:161], v[202:205], v[84:87]
	v_mfma_f32_16x16x32_bf16 v[76:79], v[150:153], v[210:213], v[76:79]
	v_mfma_f32_16x16x32_bf16 v[68:71], v[158:161], v[210:213], v[68:71]
	v_mfma_f32_16x16x32_bf16 v[120:123], v[162:165], v[182:185], v[120:123]
	v_mfma_f32_16x16x32_bf16 v[112:115], v[170:173], v[182:185], v[112:115]
	v_mfma_f32_16x16x32_bf16 v[104:107], v[162:165], v[190:193], v[104:107]
	v_mfma_f32_16x16x32_bf16 v[96:99], v[170:173], v[190:193], v[96:99]
	v_mfma_f32_16x16x32_bf16 v[88:91], v[162:165], v[198:201], v[88:91]
	v_mfma_f32_16x16x32_bf16 v[80:83], v[170:173], v[198:201], v[80:83]
	v_mfma_f32_16x16x32_bf16 v[72:75], v[162:165], v[206:209], v[72:75]
	v_mfma_f32_16x16x32_bf16 v[64:67], v[170:173], v[206:209], v[64:67]
	v_mfma_f32_16x16x32_bf16 v[120:123], v[166:169], v[186:189], v[120:123]
	v_mfma_f32_16x16x32_bf16 v[112:115], v[174:177], v[186:189], v[112:115]
	v_mfma_f32_16x16x32_bf16 v[104:107], v[166:169], v[194:197], v[104:107]
	v_mfma_f32_16x16x32_bf16 v[96:99], v[174:177], v[194:197], v[96:99]
	v_mfma_f32_16x16x32_bf16 v[88:91], v[166:169], v[202:205], v[88:91]
	v_mfma_f32_16x16x32_bf16 v[80:83], v[174:177], v[202:205], v[80:83]
	v_mfma_f32_16x16x32_bf16 v[72:75], v[166:169], v[210:213], v[72:75]
	v_mfma_f32_16x16x32_bf16 v[64:67], v[174:177], v[210:213], v[64:67]
	s_setprio 0
	s_barrier
	s_add_i32 s6, s8, s18
	v_lshl_add_u64 v[178:179], v[178:179], 0, s[34:35]
	s_mov_b32 m0, s6
	ds_read_b128 v[182:185], v149 offset:49152
	ds_read_b128 v[186:189], v149 offset:50176
	ds_read_b128 v[190:193], v149 offset:51200
	ds_read_b128 v[194:197], v149 offset:52224
	ds_read_b128 v[198:201], v149 offset:53248
	ds_read_b128 v[202:205], v149 offset:54272
	ds_read_b128 v[206:209], v149 offset:55296
	ds_read_b128 v[210:213], v149 offset:56320
	global_load_lds_dwordx4 v[178:179], off
	s_add_i32 m0, s6, 0x2000
	s_add_u32 s6, s60, 0x80080
	v_lshl_add_u64 v[178:179], v[214:215], 0, s[34:35]
	s_addc_u32 s7, s61, 0
	s_add_i32 s8, s9, s18
	global_load_lds_dwordx4 v[178:179], off
	v_lshl_add_u64 v[178:179], s[6:7], 0, v[132:133]
	s_mov_b32 m0, s8
	s_nop 0
	global_load_lds_dwordx4 v[178:179], off
	v_lshl_add_u64 v[178:179], s[6:7], 0, v[128:129]
	s_add_i32 m0, s8, 0x2000
	s_nop 0
	global_load_lds_dwordx4 v[178:179], off
	v_lshl_add_u64 v[178:179], v[216:217], 0, s[34:35]
	s_mov_b32 m0, s69
	s_nop 0
	global_load_lds_dwordx4 v[178:179], off
	v_lshl_add_u64 v[178:179], v[218:219], 0, s[34:35]
	s_mov_b32 m0, s70
	s_nop 0
	global_load_lds_dwordx4 v[178:179], off
	s_waitcnt vmcnt(8)
	s_waitcnt lgkmcnt(0)
	s_barrier
	s_setprio 1
	v_mfma_f32_16x16x32_bf16 v[60:63], v[140:143], v[182:185], v[60:63]
	v_mfma_f32_16x16x32_bf16 v[52:55], v[154:157], v[182:185], v[52:55]
	v_mfma_f32_16x16x32_bf16 v[44:47], v[140:143], v[190:193], v[44:47]
	v_mfma_f32_16x16x32_bf16 v[36:39], v[154:157], v[190:193], v[36:39]
	v_mfma_f32_16x16x32_bf16 v[28:31], v[140:143], v[198:201], v[28:31]
	v_mfma_f32_16x16x32_bf16 v[20:23], v[154:157], v[198:201], v[20:23]
	v_mfma_f32_16x16x32_bf16 v[12:15], v[140:143], v[206:209], v[12:15]
	v_mfma_f32_16x16x32_bf16 v[4:7], v[154:157], v[206:209], v[4:7]
	v_mfma_f32_16x16x32_bf16 v[60:63], v[150:153], v[186:189], v[60:63]
	v_mfma_f32_16x16x32_bf16 v[52:55], v[158:161], v[186:189], v[52:55]
	v_mfma_f32_16x16x32_bf16 v[44:47], v[150:153], v[194:197], v[44:47]
	v_mfma_f32_16x16x32_bf16 v[36:39], v[158:161], v[194:197], v[36:39]
	v_mfma_f32_16x16x32_bf16 v[28:31], v[150:153], v[202:205], v[28:31]
	v_mfma_f32_16x16x32_bf16 v[20:23], v[158:161], v[202:205], v[20:23]
	v_mfma_f32_16x16x32_bf16 v[12:15], v[150:153], v[210:213], v[12:15]
	v_mfma_f32_16x16x32_bf16 v[4:7], v[158:161], v[210:213], v[4:7]
	v_mfma_f32_16x16x32_bf16 v[56:59], v[162:165], v[182:185], v[56:59]
	v_mfma_f32_16x16x32_bf16 v[48:51], v[170:173], v[182:185], v[48:51]
	v_mfma_f32_16x16x32_bf16 v[40:43], v[162:165], v[190:193], v[40:43]
	v_mfma_f32_16x16x32_bf16 v[32:35], v[170:173], v[190:193], v[32:35]
	v_mfma_f32_16x16x32_bf16 v[24:27], v[162:165], v[198:201], v[24:27]
	v_mfma_f32_16x16x32_bf16 v[16:19], v[170:173], v[198:201], v[16:19]
	v_mfma_f32_16x16x32_bf16 v[8:11], v[162:165], v[206:209], v[8:11]
	v_mfma_f32_16x16x32_bf16 v[0:3], v[170:173], v[206:209], v[0:3]
	v_mfma_f32_16x16x32_bf16 v[56:59], v[166:169], v[186:189], v[56:59]
	v_mfma_f32_16x16x32_bf16 v[48:51], v[174:177], v[186:189], v[48:51]
	v_mfma_f32_16x16x32_bf16 v[40:43], v[166:169], v[194:197], v[40:43]
	v_mfma_f32_16x16x32_bf16 v[32:35], v[174:177], v[194:197], v[32:35]
	v_mfma_f32_16x16x32_bf16 v[24:27], v[166:169], v[202:205], v[24:27]
	v_mfma_f32_16x16x32_bf16 v[16:19], v[174:177], v[202:205], v[16:19]
	v_mfma_f32_16x16x32_bf16 v[8:11], v[166:169], v[210:213], v[8:11]
	v_mfma_f32_16x16x32_bf16 v[0:3], v[174:177], v[210:213], v[0:3]
	s_setprio 0
	s_barrier
	s_add_i32 s5, s5, 2
	s_add_u32 s58, s58, 0x100
	s_addc_u32 s59, s59, 0
	s_cmp_ge_i32 s5, s67
	s_cbranch_scc0 .LBB0_1684

.LBB0_1757:
	s_mov_b64 s[8:9], s[38:39]
	ds_read_b128 v[136:139], v183
	ds_read_b128 v[140:143], v183 offset:1024
	ds_read_b128 v[144:147], v183 offset:2048
	ds_read_b128 v[148:151], v183 offset:3072
	ds_read_b128 v[152:155], v184
	ds_read_b128 v[156:159], v184 offset:1024
	ds_read_b128 v[160:163], v184 offset:2048
	ds_read_b128 v[164:167], v184 offset:3072
	s_add_u32 s5, s16, s8
	s_addc_u32 s48, s17, s9
	s_add_u32 s40, s5, 0x100
	s_addc_u32 s41, s48, 0
	s_add_u32 s8, s36, s8
	s_addc_u32 s9, s37, s9
	s_add_u32 s8, s8, 0x100
	s_addc_u32 s9, s9, 0
	s_cmp_eq_u32 s60, s4
	s_cselect_b32 s43, s31, s41
	s_cselect_b32 s42, s30, s40
	s_cselect_b32 s41, s35, s9
	s_cselect_b32 s40, s34, s8
	s_add_u32 s8, s5, 0x160080
	s_addc_u32 s9, s48, 0
	v_lshl_add_u64 v[176:177], s[8:9], 0, v[128:129]
	s_add_i32 m0, s45, 0xc000
	ds_read_b128 v[168:171], v185
	ds_read_b128 v[172:175], v185 offset:1024
	ds_read_b128 v[186:189], v185 offset:2048
	ds_read_b128 v[190:193], v185 offset:3072
	ds_read_b128 v[194:197], v185 offset:4096
	ds_read_b128 v[198:201], v185 offset:5120
	ds_read_b128 v[202:205], v185 offset:6144
	ds_read_b128 v[206:209], v185 offset:7168
	global_load_lds_dwordx4 v[176:177], off
	v_lshl_add_u64 v[176:177], s[8:9], 0, v[130:131]
	s_add_i32 m0, s45, 0xe000
	s_nop 0
	global_load_lds_dwordx4 v[176:177], off
	s_waitcnt vmcnt(8)
	s_waitcnt lgkmcnt(0)
	s_barrier
	s_setprio 1
	v_mfma_f32_16x16x32_bf16 v[124:127], v[136:139], v[168:171], v[124:127]
	v_mfma_f32_16x16x32_bf16 v[120:123], v[144:147], v[168:171], v[120:123]
	v_mfma_f32_16x16x32_bf16 v[116:119], v[136:139], v[186:189], v[116:119]
	v_mfma_f32_16x16x32_bf16 v[112:115], v[144:147], v[186:189], v[112:115]
	v_mfma_f32_16x16x32_bf16 v[104:107], v[136:139], v[194:197], v[104:107]
	v_mfma_f32_16x16x32_bf16 v[96:99], v[144:147], v[194:197], v[96:99]
	v_mfma_f32_16x16x32_bf16 v[88:91], v[136:139], v[202:205], v[88:91]
	v_mfma_f32_16x16x32_bf16 v[80:83], v[144:147], v[202:205], v[80:83]
	v_mfma_f32_16x16x32_bf16 v[124:127], v[140:143], v[172:175], v[124:127]
	v_mfma_f32_16x16x32_bf16 v[120:123], v[148:151], v[172:175], v[120:123]
	v_mfma_f32_16x16x32_bf16 v[116:119], v[140:143], v[190:193], v[116:119]
	v_mfma_f32_16x16x32_bf16 v[112:115], v[148:151], v[190:193], v[112:115]
	v_mfma_f32_16x16x32_bf16 v[104:107], v[140:143], v[198:201], v[104:107]
	v_mfma_f32_16x16x32_bf16 v[96:99], v[148:151], v[198:201], v[96:99]
	v_mfma_f32_16x16x32_bf16 v[88:91], v[140:143], v[206:209], v[88:91]
	v_mfma_f32_16x16x32_bf16 v[80:83], v[148:151], v[206:209], v[80:83]
	v_mfma_f32_16x16x32_bf16 v[108:111], v[152:155], v[168:171], v[108:111]
	v_mfma_f32_16x16x32_bf16 v[100:103], v[160:163], v[168:171], v[100:103]
	v_mfma_f32_16x16x32_bf16 v[92:95], v[152:155], v[186:189], v[92:95]
	v_mfma_f32_16x16x32_bf16 v[84:87], v[160:163], v[186:189], v[84:87]
	v_mfma_f32_16x16x32_bf16 v[76:79], v[152:155], v[194:197], v[76:79]
	v_mfma_f32_16x16x32_bf16 v[72:75], v[160:163], v[194:197], v[72:75]
	v_mfma_f32_16x16x32_bf16 v[68:71], v[152:155], v[202:205], v[68:71]
	v_mfma_f32_16x16x32_bf16 v[64:67], v[160:163], v[202:205], v[64:67]
	v_mfma_f32_16x16x32_bf16 v[108:111], v[156:159], v[172:175], v[108:111]
	v_mfma_f32_16x16x32_bf16 v[100:103], v[164:167], v[172:175], v[100:103]
	v_mfma_f32_16x16x32_bf16 v[92:95], v[156:159], v[190:193], v[92:95]
	v_mfma_f32_16x16x32_bf16 v[84:87], v[164:167], v[190:193], v[84:87]
	v_mfma_f32_16x16x32_bf16 v[76:79], v[156:159], v[198:201], v[76:79]
	v_mfma_f32_16x16x32_bf16 v[72:75], v[164:167], v[198:201], v[72:75]
	v_mfma_f32_16x16x32_bf16 v[68:71], v[156:159], v[206:209], v[68:71]
	v_mfma_f32_16x16x32_bf16 v[64:67], v[164:167], v[206:209], v[64:67]
	s_setprio 0
	s_barrier
	s_add_i32 s5, s61, s44
	v_lshl_add_u64 v[176:177], s[40:41], 0, v[128:129]
	s_mov_b32 m0, s5
	ds_read_b128 v[168:171], v185 offset:16384
	ds_read_b128 v[172:175], v185 offset:17408
	ds_read_b128 v[186:189], v185 offset:18432
	ds_read_b128 v[190:193], v185 offset:19456
	ds_read_b128 v[194:197], v185 offset:20480
	ds_read_b128 v[198:201], v185 offset:21504
	ds_read_b128 v[202:205], v185 offset:22528
	ds_read_b128 v[206:209], v185 offset:23552
	global_load_lds_dwordx4 v[176:177], off
	s_add_i32 m0, s5, 0x2000
	s_add_u32 s8, s40, 0x160000
	v_lshl_add_u64 v[210:211], s[40:41], 0, v[130:131]
	s_addc_u32 s9, s41, 0
	s_add_i32 s5, s62, s44
	global_load_lds_dwordx4 v[210:211], off
	v_lshl_add_u64 v[212:213], s[8:9], 0, v[128:129]
	s_mov_b32 m0, s5
	v_lshl_add_u64 v[214:215], s[42:43], 0, v[130:131]
	global_load_lds_dwordx4 v[212:213], off
	v_lshl_add_u64 v[212:213], s[8:9], 0, v[130:131]
	s_add_i32 m0, s5, 0x2000
	s_nop 0
	global_load_lds_dwordx4 v[212:213], off
	v_lshl_add_u64 v[212:213], s[42:43], 0, v[128:129]
	s_mov_b32 m0, s45
	s_nop 0
	global_load_lds_dwordx4 v[212:213], off
	s_mov_b32 m0, s46
	s_nop 0
	global_load_lds_dwordx4 v[214:215], off
	s_waitcnt vmcnt(8)
	s_waitcnt lgkmcnt(0)
	s_barrier
	s_setprio 1
	v_mfma_f32_16x16x32_bf16 v[60:63], v[136:139], v[168:171], v[60:63]
	v_mfma_f32_16x16x32_bf16 v[56:59], v[144:147], v[168:171], v[56:59]
	v_mfma_f32_16x16x32_bf16 v[52:55], v[136:139], v[186:189], v[52:55]
	v_mfma_f32_16x16x32_bf16 v[48:51], v[144:147], v[186:189], v[48:51]
	v_mfma_f32_16x16x32_bf16 v[40:43], v[136:139], v[194:197], v[40:43]
	v_mfma_f32_16x16x32_bf16 v[32:35], v[144:147], v[194:197], v[32:35]
	v_mfma_f32_16x16x32_bf16 v[24:27], v[136:139], v[202:205], v[24:27]
	v_mfma_f32_16x16x32_bf16 v[16:19], v[144:147], v[202:205], v[16:19]
	v_mfma_f32_16x16x32_bf16 v[60:63], v[140:143], v[172:175], v[60:63]
	v_mfma_f32_16x16x32_bf16 v[56:59], v[148:151], v[172:175], v[56:59]
	v_mfma_f32_16x16x32_bf16 v[52:55], v[140:143], v[190:193], v[52:55]
	v_mfma_f32_16x16x32_bf16 v[48:51], v[148:151], v[190:193], v[48:51]
	v_mfma_f32_16x16x32_bf16 v[40:43], v[140:143], v[198:201], v[40:43]
	v_mfma_f32_16x16x32_bf16 v[32:35], v[148:151], v[198:201], v[32:35]
	v_mfma_f32_16x16x32_bf16 v[24:27], v[140:143], v[206:209], v[24:27]
	v_mfma_f32_16x16x32_bf16 v[16:19], v[148:151], v[206:209], v[16:19]
	v_mfma_f32_16x16x32_bf16 v[44:47], v[152:155], v[168:171], v[44:47]
	v_mfma_f32_16x16x32_bf16 v[36:39], v[160:163], v[168:171], v[36:39]
	v_mfma_f32_16x16x32_bf16 v[28:31], v[152:155], v[186:189], v[28:31]
	v_mfma_f32_16x16x32_bf16 v[20:23], v[160:163], v[186:189], v[20:23]
	v_mfma_f32_16x16x32_bf16 v[12:15], v[152:155], v[194:197], v[12:15]
	v_mfma_f32_16x16x32_bf16 v[8:11], v[160:163], v[194:197], v[8:11]
	v_mfma_f32_16x16x32_bf16 v[4:7], v[152:155], v[202:205], v[4:7]
	v_mfma_f32_16x16x32_bf16 v[0:3], v[160:163], v[202:205], v[0:3]
	v_mfma_f32_16x16x32_bf16 v[44:47], v[156:159], v[172:175], v[44:47]
	v_mfma_f32_16x16x32_bf16 v[36:39], v[164:167], v[172:175], v[36:39]
	v_mfma_f32_16x16x32_bf16 v[28:31], v[156:159], v[190:193], v[28:31]
	v_mfma_f32_16x16x32_bf16 v[20:23], v[164:167], v[190:193], v[20:23]
	v_mfma_f32_16x16x32_bf16 v[12:15], v[156:159], v[198:201], v[12:15]
	v_mfma_f32_16x16x32_bf16 v[8:11], v[164:167], v[198:201], v[8:11]
	v_mfma_f32_16x16x32_bf16 v[4:7], v[156:159], v[206:209], v[4:7]
	v_mfma_f32_16x16x32_bf16 v[0:3], v[164:167], v[206:209], v[0:3]
	s_setprio 0
	s_barrier
	s_add_i32 s5, 0, 0x18000
	v_add_u32_e32 v132, s5, v182
	s_add_i32 s48, 0, 0x1c000
	ds_read_b128 v[136:139], v132
	ds_read_b128 v[140:143], v132 offset:1024
	ds_read_b128 v[144:147], v132 offset:2048
	ds_read_b128 v[148:151], v132 offset:3072
	v_add_u32_e32 v132, s48, v182
	ds_read_b128 v[152:155], v132
	ds_read_b128 v[156:159], v132 offset:1024
	ds_read_b128 v[160:163], v132 offset:2048
	ds_read_b128 v[164:167], v132 offset:3072
	s_add_u32 s8, s42, 0x160000
	s_addc_u32 s9, s43, 0
	s_mov_b32 m0, s47
	v_lshl_add_u64 v[216:217], s[8:9], 0, v[128:129]
	ds_read_b128 v[168:171], v185 offset:32768
	ds_read_b128 v[172:175], v185 offset:33792
	ds_read_b128 v[186:189], v185 offset:34816
	ds_read_b128 v[190:193], v185 offset:35840
	ds_read_b128 v[194:197], v185 offset:36864
	ds_read_b128 v[198:201], v185 offset:37888
	ds_read_b128 v[202:205], v185 offset:38912
	ds_read_b128 v[206:209], v185 offset:39936
	global_load_lds_dwordx4 v[216:217], off
	v_lshl_add_u64 v[216:217], s[8:9], 0, v[130:131]
	s_mov_b32 m0, s52
	s_nop 0
	global_load_lds_dwordx4 v[216:217], off
	s_waitcnt vmcnt(8)
	s_waitcnt lgkmcnt(0)
	s_barrier
	s_setprio 1
	v_mfma_f32_16x16x32_bf16 v[124:127], v[136:139], v[168:171], v[124:127]
	v_mfma_f32_16x16x32_bf16 v[120:123], v[144:147], v[168:171], v[120:123]
	v_mfma_f32_16x16x32_bf16 v[116:119], v[136:139], v[186:189], v[116:119]
	v_mfma_f32_16x16x32_bf16 v[112:115], v[144:147], v[186:189], v[112:115]
	v_mfma_f32_16x16x32_bf16 v[104:107], v[136:139], v[194:197], v[104:107]
	v_mfma_f32_16x16x32_bf16 v[96:99], v[144:147], v[194:197], v[96:99]
	v_mfma_f32_16x16x32_bf16 v[88:91], v[136:139], v[202:205], v[88:91]
	v_mfma_f32_16x16x32_bf16 v[80:83], v[144:147], v[202:205], v[80:83]
	v_mfma_f32_16x16x32_bf16 v[124:127], v[140:143], v[172:175], v[124:127]
	v_mfma_f32_16x16x32_bf16 v[120:123], v[148:151], v[172:175], v[120:123]
	v_mfma_f32_16x16x32_bf16 v[116:119], v[140:143], v[190:193], v[116:119]
	v_mfma_f32_16x16x32_bf16 v[112:115], v[148:151], v[190:193], v[112:115]
	v_mfma_f32_16x16x32_bf16 v[104:107], v[140:143], v[198:201], v[104:107]
	v_mfma_f32_16x16x32_bf16 v[96:99], v[148:151], v[198:201], v[96:99]
	v_mfma_f32_16x16x32_bf16 v[88:91], v[140:143], v[206:209], v[88:91]
	v_mfma_f32_16x16x32_bf16 v[80:83], v[148:151], v[206:209], v[80:83]
	v_mfma_f32_16x16x32_bf16 v[108:111], v[152:155], v[168:171], v[108:111]
	v_mfma_f32_16x16x32_bf16 v[100:103], v[160:163], v[168:171], v[100:103]
	v_mfma_f32_16x16x32_bf16 v[92:95], v[152:155], v[186:189], v[92:95]
	v_mfma_f32_16x16x32_bf16 v[84:87], v[160:163], v[186:189], v[84:87]
	v_mfma_f32_16x16x32_bf16 v[76:79], v[152:155], v[194:197], v[76:79]
	v_mfma_f32_16x16x32_bf16 v[72:75], v[160:163], v[194:197], v[72:75]
	v_mfma_f32_16x16x32_bf16 v[68:71], v[152:155], v[202:205], v[68:71]
	v_mfma_f32_16x16x32_bf16 v[64:67], v[160:163], v[202:205], v[64:67]
	v_mfma_f32_16x16x32_bf16 v[108:111], v[156:159], v[172:175], v[108:111]
	v_mfma_f32_16x16x32_bf16 v[100:103], v[164:167], v[172:175], v[100:103]
	v_mfma_f32_16x16x32_bf16 v[92:95], v[156:159], v[190:193], v[92:95]
	v_mfma_f32_16x16x32_bf16 v[84:87], v[164:167], v[190:193], v[84:87]
	v_mfma_f32_16x16x32_bf16 v[76:79], v[156:159], v[198:201], v[76:79]
	v_mfma_f32_16x16x32_bf16 v[72:75], v[164:167], v[198:201], v[72:75]
	v_mfma_f32_16x16x32_bf16 v[68:71], v[156:159], v[206:209], v[68:71]
	v_mfma_f32_16x16x32_bf16 v[64:67], v[164:167], v[206:209], v[64:67]
	s_setprio 0
	s_barrier
	s_add_i32 s5, s5, s44
	v_lshl_add_u64 v[176:177], v[176:177], 0, s[14:15]
	s_mov_b32 m0, s5
	ds_read_b128 v[168:171], v185 offset:49152
	ds_read_b128 v[172:175], v185 offset:50176
	ds_read_b128 v[186:189], v185 offset:51200
	ds_read_b128 v[190:193], v185 offset:52224
	ds_read_b128 v[194:197], v185 offset:53248
	ds_read_b128 v[198:201], v185 offset:54272
	ds_read_b128 v[202:205], v185 offset:55296
	ds_read_b128 v[206:209], v185 offset:56320
	global_load_lds_dwordx4 v[176:177], off
	s_add_i32 m0, s5, 0x2000
	s_add_u32 s8, s40, 0x160080
	v_lshl_add_u64 v[176:177], v[210:211], 0, s[14:15]
	s_addc_u32 s9, s41, 0
	s_add_i32 s5, s48, s44
	global_load_lds_dwordx4 v[176:177], off
	v_lshl_add_u64 v[176:177], s[8:9], 0, v[128:129]
	s_mov_b32 m0, s5
	s_nop 0
	global_load_lds_dwordx4 v[176:177], off
	v_lshl_add_u64 v[176:177], s[8:9], 0, v[130:131]
	s_add_i32 m0, s5, 0x2000
	s_nop 0
	global_load_lds_dwordx4 v[176:177], off
	v_lshl_add_u64 v[176:177], v[212:213], 0, s[14:15]
	s_mov_b32 m0, s58
	s_nop 0
	global_load_lds_dwordx4 v[176:177], off
	v_lshl_add_u64 v[176:177], v[214:215], 0, s[14:15]
	s_mov_b32 m0, s59
	s_nop 0
	global_load_lds_dwordx4 v[176:177], off
	s_waitcnt vmcnt(8)
	s_waitcnt lgkmcnt(0)
	s_barrier
	s_setprio 1
	v_mfma_f32_16x16x32_bf16 v[60:63], v[136:139], v[168:171], v[60:63]
	v_mfma_f32_16x16x32_bf16 v[56:59], v[144:147], v[168:171], v[56:59]
	v_mfma_f32_16x16x32_bf16 v[52:55], v[136:139], v[186:189], v[52:55]
	v_mfma_f32_16x16x32_bf16 v[48:51], v[144:147], v[186:189], v[48:51]
	v_mfma_f32_16x16x32_bf16 v[40:43], v[136:139], v[194:197], v[40:43]
	v_mfma_f32_16x16x32_bf16 v[32:35], v[144:147], v[194:197], v[32:35]
	v_mfma_f32_16x16x32_bf16 v[24:27], v[136:139], v[202:205], v[24:27]
	v_mfma_f32_16x16x32_bf16 v[16:19], v[144:147], v[202:205], v[16:19]
	v_mfma_f32_16x16x32_bf16 v[60:63], v[140:143], v[172:175], v[60:63]
	v_mfma_f32_16x16x32_bf16 v[56:59], v[148:151], v[172:175], v[56:59]
	v_mfma_f32_16x16x32_bf16 v[52:55], v[140:143], v[190:193], v[52:55]
	v_mfma_f32_16x16x32_bf16 v[48:51], v[148:151], v[190:193], v[48:51]
	v_mfma_f32_16x16x32_bf16 v[40:43], v[140:143], v[198:201], v[40:43]
	v_mfma_f32_16x16x32_bf16 v[32:35], v[148:151], v[198:201], v[32:35]
	v_mfma_f32_16x16x32_bf16 v[24:27], v[140:143], v[206:209], v[24:27]
	v_mfma_f32_16x16x32_bf16 v[16:19], v[148:151], v[206:209], v[16:19]
	v_mfma_f32_16x16x32_bf16 v[44:47], v[152:155], v[168:171], v[44:47]
	v_mfma_f32_16x16x32_bf16 v[36:39], v[160:163], v[168:171], v[36:39]
	v_mfma_f32_16x16x32_bf16 v[28:31], v[152:155], v[186:189], v[28:31]
	v_mfma_f32_16x16x32_bf16 v[20:23], v[160:163], v[186:189], v[20:23]
	v_mfma_f32_16x16x32_bf16 v[12:15], v[152:155], v[194:197], v[12:15]
	v_mfma_f32_16x16x32_bf16 v[8:11], v[160:163], v[194:197], v[8:11]
	v_mfma_f32_16x16x32_bf16 v[4:7], v[152:155], v[202:205], v[4:7]
	v_mfma_f32_16x16x32_bf16 v[0:3], v[160:163], v[202:205], v[0:3]
	v_mfma_f32_16x16x32_bf16 v[44:47], v[156:159], v[172:175], v[44:47]
	v_mfma_f32_16x16x32_bf16 v[36:39], v[164:167], v[172:175], v[36:39]
	v_mfma_f32_16x16x32_bf16 v[28:31], v[156:159], v[190:193], v[28:31]
	v_mfma_f32_16x16x32_bf16 v[20:23], v[164:167], v[190:193], v[20:23]
	v_mfma_f32_16x16x32_bf16 v[12:15], v[156:159], v[198:201], v[12:15]
	v_mfma_f32_16x16x32_bf16 v[8:11], v[164:167], v[198:201], v[8:11]
	v_mfma_f32_16x16x32_bf16 v[4:7], v[156:159], v[206:209], v[4:7]
	v_mfma_f32_16x16x32_bf16 v[0:3], v[164:167], v[206:209], v[0:3]
	s_setprio 0
	s_barrier
	s_add_i32 s4, s4, 2
	s_add_u32 s38, s38, 0x100
	s_addc_u32 s39, s39, 0
	s_cmp_ge_i32 s4, s53
	s_cbranch_scc0 .LBB0_1757
	v_pk_add_f32 v[160:161], v[126:127], 0 op_sel_hi:[1,0]
	v_pk_add_f32 v[162:163], v[124:125], 0 op_sel_hi:[1,0]
	v_pk_add_f32 v[158:159], v[122:123], 0 op_sel_hi:[1,0]
	v_pk_add_f32 v[156:157], v[120:121], 0 op_sel_hi:[1,0]
	v_pk_add_f32 v[170:171], v[110:111], 0 op_sel_hi:[1,0]
	v_pk_add_f32 v[168:169], v[108:109], 0 op_sel_hi:[1,0]
	v_pk_add_f32 v[166:167], v[102:103], 0 op_sel_hi:[1,0]
	v_pk_add_f32 v[164:165], v[100:101], 0 op_sel_hi:[1,0]
	v_pk_add_f32 v[138:139], v[118:119], 0 op_sel_hi:[1,0]
	v_pk_add_f32 v[140:141], v[116:117], 0 op_sel_hi:[1,0]
	v_pk_add_f32 v[142:143], v[114:115], 0 op_sel_hi:[1,0]
	v_pk_add_f32 v[144:145], v[112:113], 0 op_sel_hi:[1,0]
	v_pk_add_f32 v[146:147], v[94:95], 0 op_sel_hi:[1,0]
	v_pk_add_f32 v[148:149], v[92:93], 0 op_sel_hi:[1,0]
	v_pk_add_f32 v[150:151], v[86:87], 0 op_sel_hi:[1,0]
	v_pk_add_f32 v[152:153], v[84:85], 0 op_sel_hi:[1,0]
	v_pk_add_f32 v[120:121], v[106:107], 0 op_sel_hi:[1,0]
	v_pk_add_f32 v[118:119], v[104:105], 0 op_sel_hi:[1,0]
	v_pk_add_f32 v[114:115], v[98:99], 0 op_sel_hi:[1,0]
	v_pk_add_f32 v[112:113], v[96:97], 0 op_sel_hi:[1,0]
	v_pk_add_f32 v[136:137], v[78:79], 0 op_sel_hi:[1,0]
	v_pk_add_f32 v[126:127], v[76:77], 0 op_sel_hi:[1,0]
	v_pk_add_f32 v[124:125], v[74:75], 0 op_sel_hi:[1,0]
	v_pk_add_f32 v[122:123], v[72:73], 0 op_sel_hi:[1,0]
	v_pk_add_f32 v[96:97], v[90:91], 0 op_sel_hi:[1,0]
	v_pk_add_f32 v[98:99], v[88:89], 0 op_sel_hi:[1,0]
	v_pk_add_f32 v[100:101], v[82:83], 0 op_sel_hi:[1,0]
	v_pk_add_f32 v[102:103], v[80:81], 0 op_sel_hi:[1,0]
	v_pk_add_f32 v[104:105], v[70:71], 0 op_sel_hi:[1,0]
	v_pk_add_f32 v[106:107], v[68:69], 0 op_sel_hi:[1,0]
	v_pk_add_f32 v[108:109], v[66:67], 0 op_sel_hi:[1,0]
	v_pk_add_f32 v[110:111], v[64:65], 0 op_sel_hi:[1,0]
	v_pk_add_f32 v[86:87], v[62:63], 0 op_sel_hi:[1,0]
	v_pk_add_f32 v[84:85], v[60:61], 0 op_sel_hi:[1,0]
	v_pk_add_f32 v[82:83], v[58:59], 0 op_sel_hi:[1,0]
	v_pk_add_f32 v[80:81], v[56:57], 0 op_sel_hi:[1,0]
	v_pk_add_f32 v[94:95], v[46:47], 0 op_sel_hi:[1,0]
	v_pk_add_f32 v[92:93], v[44:45], 0 op_sel_hi:[1,0]
	v_pk_add_f32 v[90:91], v[38:39], 0 op_sel_hi:[1,0]
	v_pk_add_f32 v[88:89], v[36:37], 0 op_sel_hi:[1,0]
	v_pk_add_f32 v[64:65], v[54:55], 0 op_sel_hi:[1,0]
	v_pk_add_f32 v[66:67], v[52:53], 0 op_sel_hi:[1,0]
	v_pk_add_f32 v[68:69], v[50:51], 0 op_sel_hi:[1,0]
	v_pk_add_f32 v[70:71], v[48:49], 0 op_sel_hi:[1,0]
	v_pk_add_f32 v[72:73], v[30:31], 0 op_sel_hi:[1,0]
	v_pk_add_f32 v[74:75], v[28:29], 0 op_sel_hi:[1,0]
	v_pk_add_f32 v[76:77], v[22:23], 0 op_sel_hi:[1,0]
	v_pk_add_f32 v[78:79], v[20:21], 0 op_sel_hi:[1,0]
	v_pk_add_f32 v[54:55], v[42:43], 0 op_sel_hi:[1,0]
	v_pk_add_f32 v[52:53], v[40:41], 0 op_sel_hi:[1,0]
	v_pk_add_f32 v[50:51], v[34:35], 0 op_sel_hi:[1,0]
	v_pk_add_f32 v[48:49], v[32:33], 0 op_sel_hi:[1,0]
	v_pk_add_f32 v[62:63], v[14:15], 0 op_sel_hi:[1,0]
	v_pk_add_f32 v[60:61], v[12:13], 0 op_sel_hi:[1,0]
	v_pk_add_f32 v[58:59], v[10:11], 0 op_sel_hi:[1,0]
	v_pk_add_f32 v[56:57], v[8:9], 0 op_sel_hi:[1,0]
	v_pk_add_f32 v[32:33], v[26:27], 0 op_sel_hi:[1,0]
	v_pk_add_f32 v[34:35], v[24:25], 0 op_sel_hi:[1,0]
	v_pk_add_f32 v[36:37], v[18:19], 0 op_sel_hi:[1,0]
	v_pk_add_f32 v[38:39], v[16:17], 0 op_sel_hi:[1,0]
	v_pk_add_f32 v[40:41], v[6:7], 0 op_sel_hi:[1,0]
	v_pk_add_f32 v[42:43], v[4:5], 0 op_sel_hi:[1,0]
	v_pk_add_f32 v[44:45], v[2:3], 0 op_sel_hi:[1,0]
	v_pk_add_f32 v[46:47], v[0:1], 0 op_sel_hi:[1,0]

.LBB0_1789:
	s_mov_b64 s[14:15], s[12:13]
	ds_read_b128 v[140:143], v134
	ds_read_b128 v[144:147], v134 offset:1024
	ds_read_b128 v[148:151], v134 offset:2048
	ds_read_b128 v[152:155], v134 offset:3072
	ds_read_b128 v[156:159], v135
	ds_read_b128 v[160:163], v135 offset:1024
	ds_read_b128 v[164:167], v135 offset:2048
	ds_read_b128 v[168:171], v135 offset:3072
	s_add_u32 s44, s2, s14
	s_addc_u32 s45, s3, s15
	s_add_u32 s16, s44, 0x100
	s_addc_u32 s17, s45, 0
	s_add_u32 s14, s0, s14
	s_addc_u32 s15, s1, s15
	s_add_u32 s14, s14, 0x100
	s_addc_u32 s15, s15, 0
	s_cmp_eq_u32 s31, s33
	s_cselect_b32 s17, s9, s17
	s_cselect_b32 s16, s8, s16
	s_cselect_b32 s15, s11, s15
	s_cselect_b32 s14, s10, s14
	s_add_u32 s44, s44, 0x160080
	s_addc_u32 s45, s45, 0
	s_mov_b32 m0, s34
	v_lshl_add_u64 v[206:207], s[44:45], 0, v[128:129]
	ds_read_b128 v[172:175], v136
	ds_read_b128 v[176:179], v136 offset:1024
	ds_read_b128 v[182:185], v136 offset:2048
	ds_read_b128 v[186:189], v136 offset:3072
	ds_read_b128 v[190:193], v136 offset:4096
	ds_read_b128 v[194:197], v136 offset:5120
	ds_read_b128 v[198:201], v136 offset:6144
	ds_read_b128 v[202:205], v136 offset:7168
	global_load_lds_dwordx4 v[206:207], off
	v_lshl_add_u64 v[206:207], s[44:45], 0, v[130:131]
	s_mov_b32 m0, s35
	s_nop 0
	global_load_lds_dwordx4 v[206:207], off
	s_waitcnt vmcnt(8)
	s_waitcnt lgkmcnt(0)
	s_barrier
	s_setprio 1
	v_mfma_f32_16x16x32_bf16 v[124:127], v[140:143], v[172:175], v[124:127]
	v_mfma_f32_16x16x32_bf16 v[120:123], v[148:151], v[172:175], v[120:123]
	v_mfma_f32_16x16x32_bf16 v[108:111], v[140:143], v[182:185], v[108:111]
	v_mfma_f32_16x16x32_bf16 v[104:107], v[148:151], v[182:185], v[104:107]
	v_mfma_f32_16x16x32_bf16 v[92:95], v[140:143], v[190:193], v[92:95]
	v_mfma_f32_16x16x32_bf16 v[88:91], v[148:151], v[190:193], v[88:91]
	v_mfma_f32_16x16x32_bf16 v[76:79], v[140:143], v[198:201], v[76:79]
	v_mfma_f32_16x16x32_bf16 v[72:75], v[148:151], v[198:201], v[72:75]
	v_mfma_f32_16x16x32_bf16 v[124:127], v[144:147], v[176:179], v[124:127]
	v_mfma_f32_16x16x32_bf16 v[120:123], v[152:155], v[176:179], v[120:123]
	v_mfma_f32_16x16x32_bf16 v[108:111], v[144:147], v[186:189], v[108:111]
	v_mfma_f32_16x16x32_bf16 v[104:107], v[152:155], v[186:189], v[104:107]
	v_mfma_f32_16x16x32_bf16 v[92:95], v[144:147], v[194:197], v[92:95]
	v_mfma_f32_16x16x32_bf16 v[88:91], v[152:155], v[194:197], v[88:91]
	v_mfma_f32_16x16x32_bf16 v[76:79], v[144:147], v[202:205], v[76:79]
	v_mfma_f32_16x16x32_bf16 v[72:75], v[152:155], v[202:205], v[72:75]
	v_mfma_f32_16x16x32_bf16 v[116:119], v[156:159], v[172:175], v[116:119]
	v_mfma_f32_16x16x32_bf16 v[112:115], v[164:167], v[172:175], v[112:115]
	v_mfma_f32_16x16x32_bf16 v[100:103], v[156:159], v[182:185], v[100:103]
	v_mfma_f32_16x16x32_bf16 v[96:99], v[164:167], v[182:185], v[96:99]
	v_mfma_f32_16x16x32_bf16 v[84:87], v[156:159], v[190:193], v[84:87]
	v_mfma_f32_16x16x32_bf16 v[80:83], v[164:167], v[190:193], v[80:83]
	v_mfma_f32_16x16x32_bf16 v[68:71], v[156:159], v[198:201], v[68:71]
	v_mfma_f32_16x16x32_bf16 v[64:67], v[164:167], v[198:201], v[64:67]
	v_mfma_f32_16x16x32_bf16 v[116:119], v[160:163], v[176:179], v[116:119]
	v_mfma_f32_16x16x32_bf16 v[112:115], v[168:171], v[176:179], v[112:115]
	v_mfma_f32_16x16x32_bf16 v[100:103], v[160:163], v[186:189], v[100:103]
	v_mfma_f32_16x16x32_bf16 v[96:99], v[168:171], v[186:189], v[96:99]
	v_mfma_f32_16x16x32_bf16 v[84:87], v[160:163], v[194:197], v[84:87]
	v_mfma_f32_16x16x32_bf16 v[80:83], v[168:171], v[194:197], v[80:83]
	v_mfma_f32_16x16x32_bf16 v[68:71], v[160:163], v[202:205], v[68:71]
	v_mfma_f32_16x16x32_bf16 v[64:67], v[168:171], v[202:205], v[64:67]
	s_setprio 0
	s_barrier
	s_mov_b32 m0, s36
	v_lshl_add_u64 v[206:207], s[14:15], 0, v[128:129]
	s_add_u32 s44, s14, 0x160000
	ds_read_b128 v[172:175], v136 offset:16384
	ds_read_b128 v[176:179], v136 offset:17408
	ds_read_b128 v[182:185], v136 offset:18432
	ds_read_b128 v[186:189], v136 offset:19456
	ds_read_b128 v[190:193], v136 offset:20480
	ds_read_b128 v[194:197], v136 offset:21504
	ds_read_b128 v[198:201], v136 offset:22528
	ds_read_b128 v[202:205], v136 offset:23552
	global_load_lds_dwordx4 v[206:207], off
	v_lshl_add_u64 v[208:209], s[14:15], 0, v[130:131]
	s_mov_b32 m0, s37
	s_addc_u32 s45, s15, 0
	global_load_lds_dwordx4 v[208:209], off
	v_lshl_add_u64 v[210:211], s[44:45], 0, v[128:129]
	s_mov_b32 m0, s38
	v_lshl_add_u64 v[212:213], s[16:17], 0, v[130:131]
	global_load_lds_dwordx4 v[210:211], off
	v_lshl_add_u64 v[210:211], s[44:45], 0, v[130:131]
	s_mov_b32 m0, s39
	s_nop 0
	global_load_lds_dwordx4 v[210:211], off
	v_lshl_add_u64 v[210:211], s[16:17], 0, v[128:129]
	s_mov_b32 m0, s20
	s_nop 0
	global_load_lds_dwordx4 v[210:211], off
	s_mov_b32 m0, s21
	s_nop 0
	global_load_lds_dwordx4 v[212:213], off
	s_waitcnt vmcnt(8)
	s_waitcnt lgkmcnt(0)
	s_barrier
	s_setprio 1
	v_mfma_f32_16x16x32_bf16 v[60:63], v[140:143], v[172:175], v[60:63]
	v_mfma_f32_16x16x32_bf16 v[56:59], v[148:151], v[172:175], v[56:59]
	v_mfma_f32_16x16x32_bf16 v[44:47], v[140:143], v[182:185], v[44:47]
	v_mfma_f32_16x16x32_bf16 v[40:43], v[148:151], v[182:185], v[40:43]
	v_mfma_f32_16x16x32_bf16 v[28:31], v[140:143], v[190:193], v[28:31]
	v_mfma_f32_16x16x32_bf16 v[24:27], v[148:151], v[190:193], v[24:27]
	v_mfma_f32_16x16x32_bf16 v[12:15], v[140:143], v[198:201], v[12:15]
	v_mfma_f32_16x16x32_bf16 v[8:11], v[148:151], v[198:201], v[8:11]
	v_mfma_f32_16x16x32_bf16 v[60:63], v[144:147], v[176:179], v[60:63]
	v_mfma_f32_16x16x32_bf16 v[56:59], v[152:155], v[176:179], v[56:59]
	v_mfma_f32_16x16x32_bf16 v[44:47], v[144:147], v[186:189], v[44:47]
	v_mfma_f32_16x16x32_bf16 v[40:43], v[152:155], v[186:189], v[40:43]
	v_mfma_f32_16x16x32_bf16 v[28:31], v[144:147], v[194:197], v[28:31]
	v_mfma_f32_16x16x32_bf16 v[24:27], v[152:155], v[194:197], v[24:27]
	v_mfma_f32_16x16x32_bf16 v[12:15], v[144:147], v[202:205], v[12:15]
	v_mfma_f32_16x16x32_bf16 v[8:11], v[152:155], v[202:205], v[8:11]
	v_mfma_f32_16x16x32_bf16 v[52:55], v[156:159], v[172:175], v[52:55]
	v_mfma_f32_16x16x32_bf16 v[48:51], v[164:167], v[172:175], v[48:51]
	v_mfma_f32_16x16x32_bf16 v[36:39], v[156:159], v[182:185], v[36:39]
	v_mfma_f32_16x16x32_bf16 v[32:35], v[164:167], v[182:185], v[32:35]
	v_mfma_f32_16x16x32_bf16 v[20:23], v[156:159], v[190:193], v[20:23]
	v_mfma_f32_16x16x32_bf16 v[16:19], v[164:167], v[190:193], v[16:19]
	v_mfma_f32_16x16x32_bf16 v[4:7], v[156:159], v[198:201], v[4:7]
	v_mfma_f32_16x16x32_bf16 v[0:3], v[164:167], v[198:201], v[0:3]
	v_mfma_f32_16x16x32_bf16 v[52:55], v[160:163], v[176:179], v[52:55]
	v_mfma_f32_16x16x32_bf16 v[48:51], v[168:171], v[176:179], v[48:51]
	v_mfma_f32_16x16x32_bf16 v[36:39], v[160:163], v[186:189], v[36:39]
	v_mfma_f32_16x16x32_bf16 v[32:35], v[168:171], v[186:189], v[32:35]
	v_mfma_f32_16x16x32_bf16 v[20:23], v[160:163], v[194:197], v[20:23]
	v_mfma_f32_16x16x32_bf16 v[16:19], v[168:171], v[194:197], v[16:19]
	v_mfma_f32_16x16x32_bf16 v[4:7], v[160:163], v[202:205], v[4:7]
	v_mfma_f32_16x16x32_bf16 v[0:3], v[168:171], v[202:205], v[0:3]
	s_setprio 0
	s_barrier
	ds_read_b128 v[140:143], v137
	ds_read_b128 v[144:147], v137 offset:1024
	ds_read_b128 v[148:151], v137 offset:2048
	ds_read_b128 v[152:155], v137 offset:3072
	ds_read_b128 v[156:159], v138
	ds_read_b128 v[160:163], v138 offset:1024
	ds_read_b128 v[164:167], v138 offset:2048
	ds_read_b128 v[168:171], v138 offset:3072
	s_add_u32 s16, s16, 0x160000
	s_addc_u32 s17, s17, 0
	s_mov_b32 m0, s22
	v_lshl_add_u64 v[214:215], s[16:17], 0, v[128:129]
	ds_read_b128 v[172:175], v136 offset:32768
	ds_read_b128 v[176:179], v136 offset:33792
	ds_read_b128 v[182:185], v136 offset:34816
	ds_read_b128 v[186:189], v136 offset:35840
	ds_read_b128 v[190:193], v136 offset:36864
	ds_read_b128 v[194:197], v136 offset:37888
	ds_read_b128 v[198:201], v136 offset:38912
	ds_read_b128 v[202:205], v136 offset:39936
	global_load_lds_dwordx4 v[214:215], off
	v_lshl_add_u64 v[214:215], s[16:17], 0, v[130:131]
	s_mov_b32 m0, s23
	s_nop 0
	global_load_lds_dwordx4 v[214:215], off
	s_waitcnt vmcnt(8)
	s_waitcnt lgkmcnt(0)
	s_barrier
	s_setprio 1
	v_mfma_f32_16x16x32_bf16 v[124:127], v[140:143], v[172:175], v[124:127]
	v_mfma_f32_16x16x32_bf16 v[120:123], v[148:151], v[172:175], v[120:123]
	v_mfma_f32_16x16x32_bf16 v[108:111], v[140:143], v[182:185], v[108:111]
	v_mfma_f32_16x16x32_bf16 v[104:107], v[148:151], v[182:185], v[104:107]
	v_mfma_f32_16x16x32_bf16 v[92:95], v[140:143], v[190:193], v[92:95]
	v_mfma_f32_16x16x32_bf16 v[88:91], v[148:151], v[190:193], v[88:91]
	v_mfma_f32_16x16x32_bf16 v[76:79], v[140:143], v[198:201], v[76:79]
	v_mfma_f32_16x16x32_bf16 v[72:75], v[148:151], v[198:201], v[72:75]
	v_mfma_f32_16x16x32_bf16 v[124:127], v[144:147], v[176:179], v[124:127]
	v_mfma_f32_16x16x32_bf16 v[120:123], v[152:155], v[176:179], v[120:123]
	v_mfma_f32_16x16x32_bf16 v[108:111], v[144:147], v[186:189], v[108:111]
	v_mfma_f32_16x16x32_bf16 v[104:107], v[152:155], v[186:189], v[104:107]
	v_mfma_f32_16x16x32_bf16 v[92:95], v[144:147], v[194:197], v[92:95]
	v_mfma_f32_16x16x32_bf16 v[88:91], v[152:155], v[194:197], v[88:91]
	v_mfma_f32_16x16x32_bf16 v[76:79], v[144:147], v[202:205], v[76:79]
	v_mfma_f32_16x16x32_bf16 v[72:75], v[152:155], v[202:205], v[72:75]
	v_mfma_f32_16x16x32_bf16 v[116:119], v[156:159], v[172:175], v[116:119]
	v_mfma_f32_16x16x32_bf16 v[112:115], v[164:167], v[172:175], v[112:115]
	v_mfma_f32_16x16x32_bf16 v[100:103], v[156:159], v[182:185], v[100:103]
	v_mfma_f32_16x16x32_bf16 v[96:99], v[164:167], v[182:185], v[96:99]
	v_mfma_f32_16x16x32_bf16 v[84:87], v[156:159], v[190:193], v[84:87]
	v_mfma_f32_16x16x32_bf16 v[80:83], v[164:167], v[190:193], v[80:83]
	v_mfma_f32_16x16x32_bf16 v[68:71], v[156:159], v[198:201], v[68:71]
	v_mfma_f32_16x16x32_bf16 v[64:67], v[164:167], v[198:201], v[64:67]
	v_mfma_f32_16x16x32_bf16 v[116:119], v[160:163], v[176:179], v[116:119]
	v_mfma_f32_16x16x32_bf16 v[112:115], v[168:171], v[176:179], v[112:115]
	v_mfma_f32_16x16x32_bf16 v[100:103], v[160:163], v[186:189], v[100:103]
	v_mfma_f32_16x16x32_bf16 v[96:99], v[168:171], v[186:189], v[96:99]
	v_mfma_f32_16x16x32_bf16 v[84:87], v[160:163], v[194:197], v[84:87]
	v_mfma_f32_16x16x32_bf16 v[80:83], v[168:171], v[194:197], v[80:83]
	v_mfma_f32_16x16x32_bf16 v[68:71], v[160:163], v[202:205], v[68:71]
	v_mfma_f32_16x16x32_bf16 v[64:67], v[168:171], v[202:205], v[64:67]
	s_setprio 0
	s_barrier
	s_mov_b32 m0, s40
	v_lshl_add_u64 v[206:207], v[206:207], 0, s[6:7]
	s_add_u32 s14, s14, 0x160080
	ds_read_b128 v[172:175], v136 offset:49152
	ds_read_b128 v[176:179], v136 offset:50176
	ds_read_b128 v[182:185], v136 offset:51200
	ds_read_b128 v[186:189], v136 offset:52224
	ds_read_b128 v[190:193], v136 offset:53248
	ds_read_b128 v[194:197], v136 offset:54272
	ds_read_b128 v[198:201], v136 offset:55296
	ds_read_b128 v[202:205], v136 offset:56320
	global_load_lds_dwordx4 v[206:207], off
	v_lshl_add_u64 v[206:207], v[208:209], 0, s[6:7]
	s_mov_b32 m0, s41
	s_addc_u32 s15, s15, 0
	global_load_lds_dwordx4 v[206:207], off
	v_lshl_add_u64 v[206:207], s[14:15], 0, v[128:129]
	s_mov_b32 m0, s42
	s_nop 0
	global_load_lds_dwordx4 v[206:207], off
	v_lshl_add_u64 v[206:207], s[14:15], 0, v[130:131]
	s_mov_b32 m0, s43
	s_nop 0
	global_load_lds_dwordx4 v[206:207], off
	v_lshl_add_u64 v[206:207], v[210:211], 0, s[6:7]
	s_mov_b32 m0, s28
	s_nop 0
	global_load_lds_dwordx4 v[206:207], off
	v_lshl_add_u64 v[206:207], v[212:213], 0, s[6:7]
	s_mov_b32 m0, s29
	s_nop 0
	global_load_lds_dwordx4 v[206:207], off
	s_waitcnt vmcnt(8)
	s_waitcnt lgkmcnt(0)
	s_barrier
	s_setprio 1
	v_mfma_f32_16x16x32_bf16 v[60:63], v[140:143], v[172:175], v[60:63]
	v_mfma_f32_16x16x32_bf16 v[56:59], v[148:151], v[172:175], v[56:59]
	v_mfma_f32_16x16x32_bf16 v[44:47], v[140:143], v[182:185], v[44:47]
	v_mfma_f32_16x16x32_bf16 v[40:43], v[148:151], v[182:185], v[40:43]
	v_mfma_f32_16x16x32_bf16 v[28:31], v[140:143], v[190:193], v[28:31]
	v_mfma_f32_16x16x32_bf16 v[24:27], v[148:151], v[190:193], v[24:27]
	v_mfma_f32_16x16x32_bf16 v[12:15], v[140:143], v[198:201], v[12:15]
	v_mfma_f32_16x16x32_bf16 v[8:11], v[148:151], v[198:201], v[8:11]
	v_mfma_f32_16x16x32_bf16 v[60:63], v[144:147], v[176:179], v[60:63]
	v_mfma_f32_16x16x32_bf16 v[56:59], v[152:155], v[176:179], v[56:59]
	v_mfma_f32_16x16x32_bf16 v[44:47], v[144:147], v[186:189], v[44:47]
	v_mfma_f32_16x16x32_bf16 v[40:43], v[152:155], v[186:189], v[40:43]
	v_mfma_f32_16x16x32_bf16 v[28:31], v[144:147], v[194:197], v[28:31]
	v_mfma_f32_16x16x32_bf16 v[24:27], v[152:155], v[194:197], v[24:27]
	v_mfma_f32_16x16x32_bf16 v[12:15], v[144:147], v[202:205], v[12:15]
	v_mfma_f32_16x16x32_bf16 v[8:11], v[152:155], v[202:205], v[8:11]
	v_mfma_f32_16x16x32_bf16 v[52:55], v[156:159], v[172:175], v[52:55]
	v_mfma_f32_16x16x32_bf16 v[48:51], v[164:167], v[172:175], v[48:51]
	v_mfma_f32_16x16x32_bf16 v[36:39], v[156:159], v[182:185], v[36:39]
	v_mfma_f32_16x16x32_bf16 v[32:35], v[164:167], v[182:185], v[32:35]
	v_mfma_f32_16x16x32_bf16 v[20:23], v[156:159], v[190:193], v[20:23]
	v_mfma_f32_16x16x32_bf16 v[16:19], v[164:167], v[190:193], v[16:19]
	v_mfma_f32_16x16x32_bf16 v[4:7], v[156:159], v[198:201], v[4:7]
	v_mfma_f32_16x16x32_bf16 v[0:3], v[164:167], v[198:201], v[0:3]
	v_mfma_f32_16x16x32_bf16 v[52:55], v[160:163], v[176:179], v[52:55]
	v_mfma_f32_16x16x32_bf16 v[48:51], v[168:171], v[176:179], v[48:51]
	v_mfma_f32_16x16x32_bf16 v[36:39], v[160:163], v[186:189], v[36:39]
	v_mfma_f32_16x16x32_bf16 v[32:35], v[168:171], v[186:189], v[32:35]
	v_mfma_f32_16x16x32_bf16 v[20:23], v[160:163], v[194:197], v[20:23]
	v_mfma_f32_16x16x32_bf16 v[16:19], v[168:171], v[194:197], v[16:19]
	v_mfma_f32_16x16x32_bf16 v[4:7], v[160:163], v[202:205], v[4:7]
	v_mfma_f32_16x16x32_bf16 v[0:3], v[168:171], v[202:205], v[0:3]
	s_setprio 0
	s_barrier
	s_add_i32 s33, s33, 2
	s_add_u32 s12, s12, 0x100
	s_addc_u32 s13, s13, 0
	s_cmp_ge_i32 s33, s30
	s_cbranch_scc0 .LBB0_1789
	v_mov_b32_e32 v129, v127
